# speedup vs baseline: 1.0079x; 1.0012x over previous
; #define SBAR() __builtin_amdgcn_sched_barrier(0)
; #define LDA8(dst, b, h) _Pragma("unroll") for (int m = 0; m < 4; ++m) _Pragma("unroll") for (int k = 0; k < 2; ++k) \
;     dst[m][k] = *reinterpret_cast<const bf16x8*>((const char*)SA8(b, h) + la + m * 2048 + k * 1024)
; #define LDB8(dst, b, h) _Pragma("unroll") for (int n = 0; n < 2; ++n) _Pragma("unroll") for (int k = 0; k < 2; ++k) \
;     dst[n][k] = *reinterpret_cast<const bf16x8*>((const char*)SB8(b, h) + lb + n * 2048 + k * 1024)
; #define MMA8(ai, bj, At_, Bx_) do { __builtin_amdgcn_s_setprio(1); \
;     _Pragma("unroll") for (int m = 0; m < 4; ++m) _Pragma("unroll") for (int n = 0; n < 2; ++n) _Pragma("unroll") for (int k = 0; k < 2; ++k) \
;       acc[ai][bj][m][n] = __builtin_amdgcn_mfma_f32_16x16x32_bf16(Bx_[n][k], At_[m][k], acc[ai][bj][m][n], 0, 0, 0); \
;     __builtin_amdgcn_s_setprio(0); } while (0)
; #define WAITV8(n) asm volatile("s_waitcnt vmcnt(" #n ")" ::: "memory")
; #define WAITL8(n) asm volatile("s_waitcnt lgkmcnt(" #n ")" ::: "memory")
; #define BAR8 __builtin_amdgcn_s_barrier()
; template <class Epi>
; DEV void gemm8_phase(const u16* __restrict__ A, int lda, const u16* __restrict__ Bt, int K, int nM, int nN, char* shmc, const Epi& epi) {
;     ...
;       LDB8(B0, 0, 0); SBAR(); LDA8(At, 0, 0); STAGE8(SA8(1, 1), A, lda, brow + HALF, kt + 1);
;       WAITL8(8); BAR8; WAITL8(0); MMA8(0, 0, At, B0); BAR8; SBAR();
;       LDB8(B1, 0, 1); STAGE8(SB8(0, 0), Bt, K, bcol, kt + 2);
;       BAR8; WAITL8(0); MMA8(0, 1, At, B1); BAR8;
;       LDA8(At, 0, 1); STAGE8(SA8(0, 0), A, lda, brow, kt + 2);
;       BAR8; WAITL8(0); MMA8(1, 0, At, B0); BAR8; SBAR();
;       STAGE8(SB8(0, 1), Bt, K, bcol + HALF, kt + 2);
;       WAITV8(6); BAR8; MMA8(1, 1, At, B1); BAR8;
.LBB0_338:
	ds_read_b128 v[142:145], v153
	ds_read_b128 v[146:149], v154
	ds_read_b128 v[172:175], v155
	ds_read_b128 v[176:179], v156
	v_add_u32_e32 v132, s1, v152
	s_mov_b32 m0, s73
	v_add_u32_e32 v212, 0x80, v132
	v_add_u32_e32 v228, s1, v151
	ds_read_b128 v[180:183], v150
	ds_read_b128 v[184:187], v150 offset:1024
	ds_read_b128 v[188:191], v150 offset:2048
	ds_read_b128 v[192:195], v150 offset:3072
	ds_read_b128 v[196:199], v150 offset:4096
	ds_read_b128 v[200:203], v150 offset:5120
	ds_read_b128 v[204:207], v150 offset:6144
	ds_read_b128 v[208:211], v150 offset:7168
	global_load_lds_dwordx4 v212, s[18:19]
	v_add_u32_e32 v212, 0x80, v228
	s_mov_b32 m0, s74
	s_nop 0
	global_load_lds_dwordx4 v212, s[18:19]
	s_waitcnt lgkmcnt(8)
	s_barrier
	s_waitcnt lgkmcnt(7)
	s_setprio 1
	v_mfma_f32_16x16x32_bf16 v[124:127], v[142:145], v[180:183], v[124:127]
	v_mfma_f32_16x16x32_bf16 v[120:123], v[172:175], v[180:183], v[120:123]
	s_waitcnt lgkmcnt(5)
	v_mfma_f32_16x16x32_bf16 v[116:119], v[142:145], v[188:191], v[116:119]
	v_mfma_f32_16x16x32_bf16 v[112:115], v[172:175], v[188:191], v[112:115]
	s_waitcnt lgkmcnt(3)
	v_mfma_f32_16x16x32_bf16 v[108:111], v[142:145], v[196:199], v[108:111]
	v_mfma_f32_16x16x32_bf16 v[104:107], v[172:175], v[196:199], v[104:107]
	s_waitcnt lgkmcnt(1)
	v_mfma_f32_16x16x32_bf16 v[100:103], v[142:145], v[204:207], v[100:103]
	v_mfma_f32_16x16x32_bf16 v[96:99], v[172:175], v[204:207], v[96:99]
	v_mfma_f32_16x16x32_bf16 v[124:127], v[146:149], v[184:187], v[124:127]
	v_mfma_f32_16x16x32_bf16 v[120:123], v[176:179], v[184:187], v[120:123]
	v_mfma_f32_16x16x32_bf16 v[116:119], v[146:149], v[192:195], v[116:119]
	v_mfma_f32_16x16x32_bf16 v[112:115], v[176:179], v[192:195], v[112:115]
	v_mfma_f32_16x16x32_bf16 v[108:111], v[146:149], v[200:203], v[108:111]
	v_mfma_f32_16x16x32_bf16 v[104:107], v[176:179], v[200:203], v[104:107]
	s_waitcnt lgkmcnt(0)
	v_mfma_f32_16x16x32_bf16 v[100:103], v[146:149], v[208:211], v[100:103]
	v_mfma_f32_16x16x32_bf16 v[96:99], v[176:179], v[208:211], v[96:99]
	s_setprio 0
	s_barrier
	s_mov_b32 m0, s28
	v_add_u32_e32 v229, 0x100, v132
	ds_read_b128 v[212:215], v157
	ds_read_b128 v[216:219], v158
	ds_read_b128 v[220:223], v159
	ds_read_b128 v[224:227], v160
	global_load_lds_dwordx4 v229, s[14:15]
	v_add_u32_e32 v230, 0x100, v228
	s_mov_b32 m0, s29
	s_nop 0
	global_load_lds_dwordx4 v230, s[14:15]
	s_barrier
	s_waitcnt lgkmcnt(3)
	s_setprio 1
	v_mfma_f32_16x16x32_bf16 v[92:95], v[212:215], v[180:183], v[92:95]
	s_waitcnt lgkmcnt(1)
	v_mfma_f32_16x16x32_bf16 v[88:91], v[220:223], v[180:183], v[88:91]
	v_mfma_f32_16x16x32_bf16 v[84:87], v[212:215], v[188:191], v[84:87]
	v_mfma_f32_16x16x32_bf16 v[80:83], v[220:223], v[188:191], v[80:83]
	v_mfma_f32_16x16x32_bf16 v[76:79], v[212:215], v[196:199], v[76:79]
	v_mfma_f32_16x16x32_bf16 v[72:75], v[220:223], v[196:199], v[72:75]
	v_mfma_f32_16x16x32_bf16 v[68:71], v[212:215], v[204:207], v[68:71]
	v_mfma_f32_16x16x32_bf16 v[64:67], v[220:223], v[204:207], v[64:67]
	v_mfma_f32_16x16x32_bf16 v[92:95], v[216:219], v[184:187], v[92:95]
	s_waitcnt lgkmcnt(0)
	v_mfma_f32_16x16x32_bf16 v[88:91], v[224:227], v[184:187], v[88:91]
	v_mfma_f32_16x16x32_bf16 v[84:87], v[216:219], v[192:195], v[84:87]
	v_mfma_f32_16x16x32_bf16 v[80:83], v[224:227], v[192:195], v[80:83]
	v_mfma_f32_16x16x32_bf16 v[76:79], v[216:219], v[200:203], v[76:79]
	v_mfma_f32_16x16x32_bf16 v[72:75], v[224:227], v[200:203], v[72:75]
	v_mfma_f32_16x16x32_bf16 v[68:71], v[216:219], v[208:211], v[68:71]
	v_mfma_f32_16x16x32_bf16 v[64:67], v[224:227], v[208:211], v[64:67]
	s_setprio 0
	s_mov_b32 m0, s26
	s_barrier
	ds_read_b128 v[180:183], v150 offset:16384
	ds_read_b128 v[184:187], v150 offset:17408
	ds_read_b128 v[188:191], v150 offset:18432
	ds_read_b128 v[192:195], v150 offset:19456
	ds_read_b128 v[196:199], v150 offset:20480
	ds_read_b128 v[200:203], v150 offset:21504
	ds_read_b128 v[204:207], v150 offset:22528
	ds_read_b128 v[208:211], v150 offset:23552
	global_load_lds_dwordx4 v229, s[16:17]
	s_mov_b32 m0, s30
	s_nop 0
	global_load_lds_dwordx4 v230, s[16:17]
	s_barrier
	s_waitcnt lgkmcnt(7)
	s_setprio 1
	v_mfma_f32_16x16x32_bf16 v[60:63], v[142:145], v[180:183], v[60:63]
	v_mfma_f32_16x16x32_bf16 v[56:59], v[172:175], v[180:183], v[56:59]
	s_waitcnt lgkmcnt(5)
	v_mfma_f32_16x16x32_bf16 v[52:55], v[142:145], v[188:191], v[52:55]
	v_mfma_f32_16x16x32_bf16 v[48:51], v[172:175], v[188:191], v[48:51]
	s_waitcnt lgkmcnt(3)
	v_mfma_f32_16x16x32_bf16 v[44:47], v[142:145], v[196:199], v[44:47]
	v_mfma_f32_16x16x32_bf16 v[40:43], v[172:175], v[196:199], v[40:43]
	s_waitcnt lgkmcnt(1)
	v_mfma_f32_16x16x32_bf16 v[36:39], v[142:145], v[204:207], v[36:39]
	v_mfma_f32_16x16x32_bf16 v[32:35], v[172:175], v[204:207], v[32:35]
	v_mfma_f32_16x16x32_bf16 v[60:63], v[146:149], v[184:187], v[60:63]
	v_mfma_f32_16x16x32_bf16 v[56:59], v[176:179], v[184:187], v[56:59]
	v_mfma_f32_16x16x32_bf16 v[52:55], v[146:149], v[192:195], v[52:55]
	v_mfma_f32_16x16x32_bf16 v[48:51], v[176:179], v[192:195], v[48:51]
	v_mfma_f32_16x16x32_bf16 v[44:47], v[146:149], v[200:203], v[44:47]
	v_mfma_f32_16x16x32_bf16 v[40:43], v[176:179], v[200:203], v[40:43]
	s_waitcnt lgkmcnt(0)
	v_mfma_f32_16x16x32_bf16 v[36:39], v[146:149], v[208:211], v[36:39]
	v_mfma_f32_16x16x32_bf16 v[32:35], v[176:179], v[208:211], v[32:35]
	s_setprio 0
	s_barrier
	s_mov_b32 m0, s31
	s_nop 0
	global_load_lds_dwordx4 v229, s[22:23]
	s_mov_b32 m0, s34
	s_nop 0
	global_load_lds_dwordx4 v230, s[22:23]
	s_waitcnt vmcnt(6)
	s_barrier
; #define SBAR() __builtin_amdgcn_sched_barrier(0)
; #define LDA8(dst, b, h) _Pragma("unroll") for (int m = 0; m < 4; ++m) _Pragma("unroll") for (int k = 0; k < 2; ++k) \
;     dst[m][k] = *reinterpret_cast<const bf16x8*>((const char*)SA8(b, h) + la + m * 2048 + k * 1024)
; #define LDB8(dst, b, h) _Pragma("unroll") for (int n = 0; n < 2; ++n) _Pragma("unroll") for (int k = 0; k < 2; ++k) \
;     dst[n][k] = *reinterpret_cast<const bf16x8*>((const char*)SB8(b, h) + lb + n * 2048 + k * 1024)
; #define MMA8(ai, bj, At_, Bx_) do { __builtin_amdgcn_s_setprio(1); \
;     _Pragma("unroll") for (int m = 0; m < 4; ++m) _Pragma("unroll") for (int n = 0; n < 2; ++n) _Pragma("unroll") for (int k = 0; k < 2; ++k) \
;       acc[ai][bj][m][n] = __builtin_amdgcn_mfma_f32_16x16x32_bf16(Bx_[n][k], At_[m][k], acc[ai][bj][m][n], 0, 0, 0); \
;     __builtin_amdgcn_s_setprio(0); } while (0)
; #define WAITV8(n) asm volatile("s_waitcnt vmcnt(" #n ")" ::: "memory")
; #define WAITL8(n) asm volatile("s_waitcnt lgkmcnt(" #n ")" ::: "memory")
; #define BAR8 __builtin_amdgcn_s_barrier()
; template <class Epi>
; DEV void gemm8_phase(const u16* __restrict__ A, int lda, const u16* __restrict__ Bt, int K, int nM, int nN, char* shmc, const Epi& epi) {
;     ...
;       WAITV8(6); BAR8; MMA8(1, 1, At, B1); BAR8;
;       LDB8(B0, 1, 0); SBAR(); LDA8(At, 1, 0); STAGE8(SA8(0, 1), A, lda, brow + HALF, kt + 2);
;       WAITL8(8); BAR8; WAITL8(0); MMA8(0, 0, At, B0); BAR8; SBAR();
;       LDB8(B1, 1, 1); STAGE8(SB8(1, 0), Bt, K, bcol, kt + 3);
;       BAR8; WAITL8(0); MMA8(0, 1, At, B1); BAR8;
;       LDA8(At, 1, 1); STAGE8(SA8(1, 0), A, lda, brow, kt + 3);
	s_setprio 1
	v_mfma_f32_16x16x32_bf16 v[28:31], v[212:215], v[180:183], v[28:31]
	v_mfma_f32_16x16x32_bf16 v[24:27], v[220:223], v[180:183], v[24:27]
	v_mfma_f32_16x16x32_bf16 v[20:23], v[212:215], v[188:191], v[20:23]
	v_mfma_f32_16x16x32_bf16 v[16:19], v[220:223], v[188:191], v[16:19]
	v_mfma_f32_16x16x32_bf16 v[12:15], v[212:215], v[196:199], v[12:15]
	v_mfma_f32_16x16x32_bf16 v[8:11], v[220:223], v[196:199], v[8:11]
	v_mfma_f32_16x16x32_bf16 v[4:7], v[212:215], v[204:207], v[4:7]
	v_mfma_f32_16x16x32_bf16 v[0:3], v[220:223], v[204:207], v[0:3]
	v_mfma_f32_16x16x32_bf16 v[28:31], v[216:219], v[184:187], v[28:31]
	v_mfma_f32_16x16x32_bf16 v[24:27], v[224:227], v[184:187], v[24:27]
	v_mfma_f32_16x16x32_bf16 v[20:23], v[216:219], v[192:195], v[20:23]
	v_mfma_f32_16x16x32_bf16 v[16:19], v[224:227], v[192:195], v[16:19]
	v_mfma_f32_16x16x32_bf16 v[12:15], v[216:219], v[200:203], v[12:15]
	v_mfma_f32_16x16x32_bf16 v[8:11], v[224:227], v[200:203], v[8:11]
	v_mfma_f32_16x16x32_bf16 v[4:7], v[216:219], v[208:211], v[4:7]
	v_mfma_f32_16x16x32_bf16 v[0:3], v[224:227], v[208:211], v[0:3]
	s_setprio 0
	s_barrier
	ds_read_b128 v[142:145], v161
	ds_read_b128 v[146:149], v162
	ds_read_b128 v[172:175], v163
	ds_read_b128 v[176:179], v166
	s_mov_b32 m0, s35
	ds_read_b128 v[180:183], v150 offset:32768
	ds_read_b128 v[184:187], v150 offset:33792
	ds_read_b128 v[188:191], v150 offset:34816
	ds_read_b128 v[192:195], v150 offset:35840
	ds_read_b128 v[196:199], v150 offset:36864
	ds_read_b128 v[200:203], v150 offset:37888
	ds_read_b128 v[204:207], v150 offset:38912
	ds_read_b128 v[208:211], v150 offset:39936
	global_load_lds_dwordx4 v229, s[18:19]
	s_mov_b32 m0, s54
	s_nop 0
	global_load_lds_dwordx4 v230, s[18:19]
	s_waitcnt lgkmcnt(8)
	s_barrier
	s_waitcnt lgkmcnt(7)
	s_setprio 1
	v_mfma_f32_16x16x32_bf16 v[124:127], v[142:145], v[180:183], v[124:127]
	v_mfma_f32_16x16x32_bf16 v[120:123], v[172:175], v[180:183], v[120:123]
	s_waitcnt lgkmcnt(5)
	v_mfma_f32_16x16x32_bf16 v[116:119], v[142:145], v[188:191], v[116:119]
	v_mfma_f32_16x16x32_bf16 v[112:115], v[172:175], v[188:191], v[112:115]
	s_waitcnt lgkmcnt(3)
	v_mfma_f32_16x16x32_bf16 v[108:111], v[142:145], v[196:199], v[108:111]
	v_mfma_f32_16x16x32_bf16 v[104:107], v[172:175], v[196:199], v[104:107]
	s_waitcnt lgkmcnt(1)
	v_mfma_f32_16x16x32_bf16 v[100:103], v[142:145], v[204:207], v[100:103]
	v_mfma_f32_16x16x32_bf16 v[96:99], v[172:175], v[204:207], v[96:99]
	v_mfma_f32_16x16x32_bf16 v[124:127], v[146:149], v[184:187], v[124:127]
	v_mfma_f32_16x16x32_bf16 v[120:123], v[176:179], v[184:187], v[120:123]
	v_mfma_f32_16x16x32_bf16 v[116:119], v[146:149], v[192:195], v[116:119]
	v_mfma_f32_16x16x32_bf16 v[112:115], v[176:179], v[192:195], v[112:115]
	v_mfma_f32_16x16x32_bf16 v[108:111], v[146:149], v[200:203], v[108:111]
	v_mfma_f32_16x16x32_bf16 v[104:107], v[176:179], v[200:203], v[104:107]
	s_waitcnt lgkmcnt(0)
	v_mfma_f32_16x16x32_bf16 v[100:103], v[146:149], v[208:211], v[100:103]
	v_mfma_f32_16x16x32_bf16 v[96:99], v[176:179], v[208:211], v[96:99]
	s_setprio 0
	s_barrier
	s_mov_b32 m0, s55
	v_add_u32_e32 v132, 0x180, v132
	ds_read_b128 v[212:215], v167
	ds_read_b128 v[216:219], v168
	ds_read_b128 v[220:223], v169
	ds_read_b128 v[224:227], v170
	global_load_lds_dwordx4 v132, s[14:15]
	v_add_u32_e32 v228, 0x180, v228
	s_mov_b32 m0, s62
	s_nop 0
	global_load_lds_dwordx4 v228, s[14:15]
	s_barrier
	s_waitcnt lgkmcnt(3)
	s_setprio 1
	v_mfma_f32_16x16x32_bf16 v[92:95], v[212:215], v[180:183], v[92:95]
	s_waitcnt lgkmcnt(1)
	v_mfma_f32_16x16x32_bf16 v[88:91], v[220:223], v[180:183], v[88:91]
	v_mfma_f32_16x16x32_bf16 v[84:87], v[212:215], v[188:191], v[84:87]
	v_mfma_f32_16x16x32_bf16 v[80:83], v[220:223], v[188:191], v[80:83]
	v_mfma_f32_16x16x32_bf16 v[76:79], v[212:215], v[196:199], v[76:79]
	v_mfma_f32_16x16x32_bf16 v[72:75], v[220:223], v[196:199], v[72:75]
	v_mfma_f32_16x16x32_bf16 v[68:71], v[212:215], v[204:207], v[68:71]
	v_mfma_f32_16x16x32_bf16 v[64:67], v[220:223], v[204:207], v[64:67]
	v_mfma_f32_16x16x32_bf16 v[92:95], v[216:219], v[184:187], v[92:95]
	s_waitcnt lgkmcnt(0)
	v_mfma_f32_16x16x32_bf16 v[88:91], v[224:227], v[184:187], v[88:91]
	v_mfma_f32_16x16x32_bf16 v[84:87], v[216:219], v[192:195], v[84:87]
	v_mfma_f32_16x16x32_bf16 v[80:83], v[224:227], v[192:195], v[80:83]
	v_mfma_f32_16x16x32_bf16 v[76:79], v[216:219], v[200:203], v[76:79]
	v_mfma_f32_16x16x32_bf16 v[72:75], v[224:227], v[200:203], v[72:75]
	v_mfma_f32_16x16x32_bf16 v[68:71], v[216:219], v[208:211], v[68:71]
	v_mfma_f32_16x16x32_bf16 v[64:67], v[224:227], v[208:211], v[64:67]
	s_setprio 0
	s_mov_b32 m0, s63
	s_barrier
	ds_read_b128 v[180:183], v150 offset:49152
	ds_read_b128 v[184:187], v150 offset:50176
	ds_read_b128 v[188:191], v150 offset:51200
	ds_read_b128 v[192:195], v150 offset:52224
	ds_read_b128 v[196:199], v150 offset:53248
	ds_read_b128 v[200:203], v150 offset:54272
	ds_read_b128 v[204:207], v150 offset:55296
	ds_read_b128 v[208:211], v150 offset:56320
	global_load_lds_dwordx4 v132, s[16:17]
	s_mov_b32 m0, s70
	s_nop 0
	global_load_lds_dwordx4 v228, s[16:17]
	s_barrier
; #define SBAR() __builtin_amdgcn_sched_barrier(0)
; #define LDA8(dst, b, h) _Pragma("unroll") for (int m = 0; m < 4; ++m) _Pragma("unroll") for (int k = 0; k < 2; ++k) \
;     dst[m][k] = *reinterpret_cast<const bf16x8*>((const char*)SA8(b, h) + la + m * 2048 + k * 1024)
; #define LDB8(dst, b, h) _Pragma("unroll") for (int n = 0; n < 2; ++n) _Pragma("unroll") for (int k = 0; k < 2; ++k) \
;     dst[n][k] = *reinterpret_cast<const bf16x8*>((const char*)SB8(b, h) + lb + n * 2048 + k * 1024)
; #define MMA8(ai, bj, At_, Bx_) do { __builtin_amdgcn_s_setprio(1); \
;     _Pragma("unroll") for (int m = 0; m < 4; ++m) _Pragma("unroll") for (int n = 0; n < 2; ++n) _Pragma("unroll") for (int k = 0; k < 2; ++k) \
;       acc[ai][bj][m][n] = __builtin_amdgcn_mfma_f32_16x16x32_bf16(Bx_[n][k], At_[m][k], acc[ai][bj][m][n], 0, 0, 0); \
;     __builtin_amdgcn_s_setprio(0); } while (0)
; #define WAITV8(n) asm volatile("s_waitcnt vmcnt(" #n ")" ::: "memory")
; #define WAITL8(n) asm volatile("s_waitcnt lgkmcnt(" #n ")" ::: "memory")
; #define BAR8 __builtin_amdgcn_s_barrier()
; template <class Epi>
; DEV void gemm8_phase(const u16* __restrict__ A, int lda, const u16* __restrict__ Bt, int K, int nM, int nN, char* shmc, const Epi& epi) {
;     ...
;       BAR8; WAITL8(0); MMA8(1, 0, At, B0); BAR8; SBAR();
;       STAGE8(SB8(1, 1), Bt, K, bcol + HALF, kt + 3);
;       WAITV8(6); BAR8; MMA8(1, 1, At, B1); BAR8;
;     }
;     { LDB8(B0, 0, 0); LDA8(At, 0, 0); STAGE8(SA8(1, 1), A, lda, brow + HALF, nt - 1);
;       BAR8; WAITL8(0); MMA8(0, 0, At, B0); BAR8;
;       LDB8(B1, 0, 1); BAR8; WAITL8(0); MMA8(0, 1, At, B1); BAR8;
	s_waitcnt lgkmcnt(7)
	s_setprio 1
	v_mfma_f32_16x16x32_bf16 v[60:63], v[142:145], v[180:183], v[60:63]
	v_mfma_f32_16x16x32_bf16 v[56:59], v[172:175], v[180:183], v[56:59]
	s_waitcnt lgkmcnt(5)
	v_mfma_f32_16x16x32_bf16 v[52:55], v[142:145], v[188:191], v[52:55]
	v_mfma_f32_16x16x32_bf16 v[48:51], v[172:175], v[188:191], v[48:51]
	s_waitcnt lgkmcnt(3)
	v_mfma_f32_16x16x32_bf16 v[44:47], v[142:145], v[196:199], v[44:47]
	v_mfma_f32_16x16x32_bf16 v[40:43], v[172:175], v[196:199], v[40:43]
	s_waitcnt lgkmcnt(1)
	v_mfma_f32_16x16x32_bf16 v[36:39], v[142:145], v[204:207], v[36:39]
	v_mfma_f32_16x16x32_bf16 v[32:35], v[172:175], v[204:207], v[32:35]
	v_mfma_f32_16x16x32_bf16 v[60:63], v[146:149], v[184:187], v[60:63]
	v_mfma_f32_16x16x32_bf16 v[56:59], v[176:179], v[184:187], v[56:59]
	v_mfma_f32_16x16x32_bf16 v[52:55], v[146:149], v[192:195], v[52:55]
	v_mfma_f32_16x16x32_bf16 v[48:51], v[176:179], v[192:195], v[48:51]
	v_mfma_f32_16x16x32_bf16 v[44:47], v[146:149], v[200:203], v[44:47]
	v_mfma_f32_16x16x32_bf16 v[40:43], v[176:179], v[200:203], v[40:43]
	s_waitcnt lgkmcnt(0)
	v_mfma_f32_16x16x32_bf16 v[36:39], v[146:149], v[208:211], v[36:39]
	v_mfma_f32_16x16x32_bf16 v[32:35], v[176:179], v[208:211], v[32:35]
	s_setprio 0
	s_barrier
	s_mov_b32 m0, s71
	s_nop 0
	global_load_lds_dwordx4 v132, s[22:23]
	s_mov_b32 m0, s72
	s_nop 0
	global_load_lds_dwordx4 v228, s[22:23]
	s_waitcnt vmcnt(6)
	s_barrier
	s_setprio 1
	v_mfma_f32_16x16x32_bf16 v[28:31], v[212:215], v[180:183], v[28:31]
	v_mfma_f32_16x16x32_bf16 v[24:27], v[220:223], v[180:183], v[24:27]
	v_mfma_f32_16x16x32_bf16 v[20:23], v[212:215], v[188:191], v[20:23]
	v_mfma_f32_16x16x32_bf16 v[16:19], v[220:223], v[188:191], v[16:19]
	v_mfma_f32_16x16x32_bf16 v[12:15], v[212:215], v[196:199], v[12:15]
	v_mfma_f32_16x16x32_bf16 v[8:11], v[220:223], v[196:199], v[8:11]
	v_mfma_f32_16x16x32_bf16 v[4:7], v[212:215], v[204:207], v[4:7]
	v_mfma_f32_16x16x32_bf16 v[0:3], v[220:223], v[204:207], v[0:3]
	v_mfma_f32_16x16x32_bf16 v[28:31], v[216:219], v[184:187], v[28:31]
	v_mfma_f32_16x16x32_bf16 v[24:27], v[224:227], v[184:187], v[24:27]
	v_mfma_f32_16x16x32_bf16 v[20:23], v[216:219], v[192:195], v[20:23]
	v_mfma_f32_16x16x32_bf16 v[16:19], v[224:227], v[192:195], v[16:19]
	v_mfma_f32_16x16x32_bf16 v[12:15], v[216:219], v[200:203], v[12:15]
	v_mfma_f32_16x16x32_bf16 v[8:11], v[224:227], v[200:203], v[8:11]
	v_mfma_f32_16x16x32_bf16 v[4:7], v[216:219], v[208:211], v[4:7]
	v_mfma_f32_16x16x32_bf16 v[0:3], v[224:227], v[208:211], v[0:3]
	s_setprio 0
	s_add_i32 s0, s0, 2
	s_addk_i32 s1, 0x100
	s_cmp_gt_u32 s0, 27
	s_barrier
	s_cbranch_scc0 .LBB0_338
	s_mov_b32 m0, s73
	v_lshl_add_u64 v[212:213], s[18:19], 0, v[138:139]
	ds_read_b128 v[142:145], v153
	ds_read_b128 v[146:149], v154
	ds_read_b128 v[172:175], v155
	ds_read_b128 v[176:179], v156
	ds_read_b128 v[180:183], v150
	ds_read_b128 v[184:187], v150 offset:1024
	ds_read_b128 v[188:191], v150 offset:2048
	ds_read_b128 v[192:195], v150 offset:3072
	ds_read_b128 v[196:199], v150 offset:4096
	ds_read_b128 v[200:203], v150 offset:5120
	ds_read_b128 v[204:207], v150 offset:6144
	ds_read_b128 v[208:211], v150 offset:7168
	global_load_lds_dwordx4 v[212:213], off
	v_lshl_add_u64 v[212:213], s[18:19], 0, v[140:141]
	s_mov_b32 m0, s74
	s_nop 0
	global_load_lds_dwordx4 v[212:213], off
	s_barrier
	s_waitcnt lgkmcnt(0)
	s_setprio 1
	s_waitcnt lgkmcnt(0)
	v_mfma_f32_16x16x32_bf16 v[124:127], v[142:145], v[180:183], v[124:127]
	v_mfma_f32_16x16x32_bf16 v[120:123], v[172:175], v[180:183], v[120:123]
	v_mfma_f32_16x16x32_bf16 v[116:119], v[142:145], v[188:191], v[116:119]
	v_mfma_f32_16x16x32_bf16 v[112:115], v[172:175], v[188:191], v[112:115]
	v_mfma_f32_16x16x32_bf16 v[108:111], v[142:145], v[196:199], v[108:111]
	v_mfma_f32_16x16x32_bf16 v[104:107], v[172:175], v[196:199], v[104:107]
	v_mfma_f32_16x16x32_bf16 v[100:103], v[142:145], v[204:207], v[100:103]
	v_mfma_f32_16x16x32_bf16 v[96:99], v[172:175], v[204:207], v[96:99]
	v_mfma_f32_16x16x32_bf16 v[124:127], v[146:149], v[184:187], v[124:127]
	v_mfma_f32_16x16x32_bf16 v[120:123], v[176:179], v[184:187], v[120:123]
	v_mfma_f32_16x16x32_bf16 v[116:119], v[146:149], v[192:195], v[116:119]
	v_mfma_f32_16x16x32_bf16 v[112:115], v[176:179], v[192:195], v[112:115]
	v_mfma_f32_16x16x32_bf16 v[108:111], v[146:149], v[200:203], v[108:111]
	v_mfma_f32_16x16x32_bf16 v[104:107], v[176:179], v[200:203], v[104:107]
	v_mfma_f32_16x16x32_bf16 v[100:103], v[146:149], v[208:211], v[100:103]
	v_mfma_f32_16x16x32_bf16 v[96:99], v[176:179], v[208:211], v[96:99]
	s_setprio 0
	s_barrier
	ds_read_b128 v[212:215], v157
	ds_read_b128 v[216:219], v158
	ds_read_b128 v[220:223], v159
	ds_read_b128 v[224:227], v160
	s_barrier
	s_waitcnt lgkmcnt(0)
	s_setprio 1
	s_waitcnt lgkmcnt(0)
	v_mfma_f32_16x16x32_bf16 v[92:95], v[212:215], v[180:183], v[92:95]
	v_mfma_f32_16x16x32_bf16 v[88:91], v[220:223], v[180:183], v[88:91]
	v_mfma_f32_16x16x32_bf16 v[84:87], v[212:215], v[188:191], v[84:87]
	v_mfma_f32_16x16x32_bf16 v[80:83], v[220:223], v[188:191], v[80:83]
	v_mfma_f32_16x16x32_bf16 v[76:79], v[212:215], v[196:199], v[76:79]
	v_mfma_f32_16x16x32_bf16 v[72:75], v[220:223], v[196:199], v[72:75]
	v_mfma_f32_16x16x32_bf16 v[68:71], v[212:215], v[204:207], v[68:71]
	v_mfma_f32_16x16x32_bf16 v[64:67], v[220:223], v[204:207], v[64:67]
	v_mfma_f32_16x16x32_bf16 v[92:95], v[216:219], v[184:187], v[92:95]
	v_mfma_f32_16x16x32_bf16 v[88:91], v[224:227], v[184:187], v[88:91]
	v_mfma_f32_16x16x32_bf16 v[84:87], v[216:219], v[192:195], v[84:87]
	v_mfma_f32_16x16x32_bf16 v[80:83], v[224:227], v[192:195], v[80:83]
	v_mfma_f32_16x16x32_bf16 v[76:79], v[216:219], v[200:203], v[76:79]
	v_mfma_f32_16x16x32_bf16 v[72:75], v[224:227], v[200:203], v[72:75]
	v_mfma_f32_16x16x32_bf16 v[68:71], v[216:219], v[208:211], v[68:71]
	v_mfma_f32_16x16x32_bf16 v[64:67], v[224:227], v[208:211], v[64:67]
	s_setprio 0
	s_barrier
; #define LDA8(dst, b, h) _Pragma("unroll") for (int m = 0; m < 4; ++m) _Pragma("unroll") for (int k = 0; k < 2; ++k) \
;     dst[m][k] = *reinterpret_cast<const bf16x8*>((const char*)SA8(b, h) + la + m * 2048 + k * 1024)
; #define LDB8(dst, b, h) _Pragma("unroll") for (int n = 0; n < 2; ++n) _Pragma("unroll") for (int k = 0; k < 2; ++k) \
;     dst[n][k] = *reinterpret_cast<const bf16x8*>((const char*)SB8(b, h) + lb + n * 2048 + k * 1024)
; #define MMA8(ai, bj, At_, Bx_) do { __builtin_amdgcn_s_setprio(1); \
;     _Pragma("unroll") for (int m = 0; m < 4; ++m) _Pragma("unroll") for (int n = 0; n < 2; ++n) _Pragma("unroll") for (int k = 0; k < 2; ++k) \
;       acc[ai][bj][m][n] = __builtin_amdgcn_mfma_f32_16x16x32_bf16(Bx_[n][k], At_[m][k], acc[ai][bj][m][n], 0, 0, 0); \
;     __builtin_amdgcn_s_setprio(0); } while (0)
; #define WAITV8(n) asm volatile("s_waitcnt vmcnt(" #n ")" ::: "memory")
; #define WAITL8(n) asm volatile("s_waitcnt lgkmcnt(" #n ")" ::: "memory")
; #define BAR8 __builtin_amdgcn_s_barrier()
; template <class Epi>
; DEV void gemm8_phase(const u16* __restrict__ A, int lda, const u16* __restrict__ Bt, int K, int nM, int nN, char* shmc, const Epi& epi) {
;     ...
;       LDA8(At, 0, 1); WAITV8(4); BAR8; WAITL8(0); MMA8(1, 0, At, B0); MMA8(1, 1, At, B1); BAR8; }
;     { LDB8(B0, 1, 0); LDA8(At, 1, 0); WAITV8(2); BAR8; WAITL8(0); MMA8(0, 0, At, B0); BAR8;
	ds_read_b128 v[180:183], v150 offset:16384
	ds_read_b128 v[184:187], v150 offset:17408
	ds_read_b128 v[188:191], v150 offset:18432
	ds_read_b128 v[192:195], v150 offset:19456
	ds_read_b128 v[196:199], v150 offset:20480
	ds_read_b128 v[200:203], v150 offset:21504
	ds_read_b128 v[204:207], v150 offset:22528
	ds_read_b128 v[208:211], v150 offset:23552
	s_waitcnt vmcnt(4)
	s_barrier
	s_waitcnt lgkmcnt(0)
	s_setprio 1
	s_waitcnt lgkmcnt(0)
	v_mfma_f32_16x16x32_bf16 v[60:63], v[142:145], v[180:183], v[60:63]
	v_mfma_f32_16x16x32_bf16 v[56:59], v[172:175], v[180:183], v[56:59]
	v_mfma_f32_16x16x32_bf16 v[52:55], v[142:145], v[188:191], v[52:55]
	v_mfma_f32_16x16x32_bf16 v[48:51], v[172:175], v[188:191], v[48:51]
	v_mfma_f32_16x16x32_bf16 v[44:47], v[142:145], v[196:199], v[44:47]
	v_mfma_f32_16x16x32_bf16 v[40:43], v[172:175], v[196:199], v[40:43]
	v_mfma_f32_16x16x32_bf16 v[36:39], v[142:145], v[204:207], v[36:39]
	v_mfma_f32_16x16x32_bf16 v[32:35], v[172:175], v[204:207], v[32:35]
	v_mfma_f32_16x16x32_bf16 v[60:63], v[146:149], v[184:187], v[60:63]
	v_mfma_f32_16x16x32_bf16 v[56:59], v[176:179], v[184:187], v[56:59]
	v_mfma_f32_16x16x32_bf16 v[52:55], v[146:149], v[192:195], v[52:55]
	v_mfma_f32_16x16x32_bf16 v[48:51], v[176:179], v[192:195], v[48:51]
	v_mfma_f32_16x16x32_bf16 v[44:47], v[146:149], v[200:203], v[44:47]
	v_mfma_f32_16x16x32_bf16 v[40:43], v[176:179], v[200:203], v[40:43]
	v_mfma_f32_16x16x32_bf16 v[36:39], v[146:149], v[208:211], v[36:39]
	v_mfma_f32_16x16x32_bf16 v[32:35], v[176:179], v[208:211], v[32:35]
	s_setprio 0
	s_setprio 1
	v_mfma_f32_16x16x32_bf16 v[28:31], v[212:215], v[180:183], v[28:31]
	v_mfma_f32_16x16x32_bf16 v[24:27], v[220:223], v[180:183], v[24:27]
	v_mfma_f32_16x16x32_bf16 v[20:23], v[212:215], v[188:191], v[20:23]
	v_mfma_f32_16x16x32_bf16 v[16:19], v[220:223], v[188:191], v[16:19]
	v_mfma_f32_16x16x32_bf16 v[12:15], v[212:215], v[196:199], v[12:15]
	v_mfma_f32_16x16x32_bf16 v[8:11], v[220:223], v[196:199], v[8:11]
	v_mfma_f32_16x16x32_bf16 v[4:7], v[212:215], v[204:207], v[4:7]
	v_mfma_f32_16x16x32_bf16 v[0:3], v[220:223], v[204:207], v[0:3]
	v_mfma_f32_16x16x32_bf16 v[28:31], v[216:219], v[184:187], v[28:31]
	v_mfma_f32_16x16x32_bf16 v[24:27], v[224:227], v[184:187], v[24:27]
	v_mfma_f32_16x16x32_bf16 v[20:23], v[216:219], v[192:195], v[20:23]
	v_mfma_f32_16x16x32_bf16 v[16:19], v[224:227], v[192:195], v[16:19]
	v_mfma_f32_16x16x32_bf16 v[12:15], v[216:219], v[200:203], v[12:15]
	v_mfma_f32_16x16x32_bf16 v[8:11], v[224:227], v[200:203], v[8:11]
	v_mfma_f32_16x16x32_bf16 v[4:7], v[216:219], v[208:211], v[4:7]
	v_mfma_f32_16x16x32_bf16 v[0:3], v[224:227], v[208:211], v[0:3]
	s_setprio 0
	s_barrier
	ds_read_b128 v[142:145], v161
	ds_read_b128 v[146:149], v162
	ds_read_b128 v[172:175], v163
	ds_read_b128 v[176:179], v166
	ds_read_b128 v[180:183], v150 offset:32768
	ds_read_b128 v[184:187], v150 offset:33792
	ds_read_b128 v[188:191], v150 offset:34816
	ds_read_b128 v[192:195], v150 offset:35840
	ds_read_b128 v[196:199], v150 offset:36864
	ds_read_b128 v[200:203], v150 offset:37888
	ds_read_b128 v[204:207], v150 offset:38912
	ds_read_b128 v[208:211], v150 offset:39936
	s_waitcnt vmcnt(2)
	s_barrier
	s_waitcnt lgkmcnt(0)
	s_setprio 1
	s_waitcnt lgkmcnt(0)
	v_mfma_f32_16x16x32_bf16 v[124:127], v[142:145], v[180:183], v[124:127]
	v_mfma_f32_16x16x32_bf16 v[120:123], v[172:175], v[180:183], v[120:123]
	v_mfma_f32_16x16x32_bf16 v[116:119], v[142:145], v[188:191], v[116:119]
	v_mfma_f32_16x16x32_bf16 v[112:115], v[172:175], v[188:191], v[112:115]
	v_mfma_f32_16x16x32_bf16 v[108:111], v[142:145], v[196:199], v[108:111]
	v_mfma_f32_16x16x32_bf16 v[104:107], v[172:175], v[196:199], v[104:107]
	v_mfma_f32_16x16x32_bf16 v[100:103], v[142:145], v[204:207], v[100:103]
	v_mfma_f32_16x16x32_bf16 v[96:99], v[172:175], v[204:207], v[96:99]
	v_mfma_f32_16x16x32_bf16 v[124:127], v[146:149], v[184:187], v[124:127]
	v_mfma_f32_16x16x32_bf16 v[120:123], v[176:179], v[184:187], v[120:123]
	v_mfma_f32_16x16x32_bf16 v[116:119], v[146:149], v[192:195], v[116:119]
	v_mfma_f32_16x16x32_bf16 v[112:115], v[176:179], v[192:195], v[112:115]
	v_mfma_f32_16x16x32_bf16 v[108:111], v[146:149], v[200:203], v[108:111]
	v_mfma_f32_16x16x32_bf16 v[104:107], v[176:179], v[200:203], v[104:107]
	v_mfma_f32_16x16x32_bf16 v[100:103], v[146:149], v[208:211], v[100:103]
	v_mfma_f32_16x16x32_bf16 v[96:99], v[176:179], v[208:211], v[96:99]
	s_setprio 0
	s_barrier
; #define LDA8(dst, b, h) _Pragma("unroll") for (int m = 0; m < 4; ++m) _Pragma("unroll") for (int k = 0; k < 2; ++k) \
;     dst[m][k] = *reinterpret_cast<const bf16x8*>((const char*)SA8(b, h) + la + m * 2048 + k * 1024)
; #define LDB8(dst, b, h) _Pragma("unroll") for (int n = 0; n < 2; ++n) _Pragma("unroll") for (int k = 0; k < 2; ++k) \
;     dst[n][k] = *reinterpret_cast<const bf16x8*>((const char*)SB8(b, h) + lb + n * 2048 + k * 1024)
; #define MMA8(ai, bj, At_, Bx_) do { __builtin_amdgcn_s_setprio(1); \
;     _Pragma("unroll") for (int m = 0; m < 4; ++m) _Pragma("unroll") for (int n = 0; n < 2; ++n) _Pragma("unroll") for (int k = 0; k < 2; ++k) \
;       acc[ai][bj][m][n] = __builtin_amdgcn_mfma_f32_16x16x32_bf16(Bx_[n][k], At_[m][k], acc[ai][bj][m][n], 0, 0, 0); \
;     __builtin_amdgcn_s_setprio(0); } while (0)
; #define WAITV8(n) asm volatile("s_waitcnt vmcnt(" #n ")" ::: "memory")
; #define WAITL8(n) asm volatile("s_waitcnt lgkmcnt(" #n ")" ::: "memory")
; #define BAR8 __builtin_amdgcn_s_barrier()
; template <class Epi>
; DEV void gemm8_phase(const u16* __restrict__ A, int lda, const u16* __restrict__ Bt, int K, int nM, int nN, char* shmc, const Epi& epi) {
;     ...
;       LDB8(B1, 1, 1); WAITV8(0); BAR8; WAITL8(0); MMA8(0, 1, At, B1); BAR8;
;       LDA8(At, 1, 1); BAR8; WAITL8(0); MMA8(1, 0, At, B0); MMA8(1, 1, At, B1); BAR8; }
;     if (wr == 0) BAR8;
	ds_read_b128 v[212:215], v167
	ds_read_b128 v[216:219], v168
	ds_read_b128 v[220:223], v169
	ds_read_b128 v[224:227], v170
	s_waitcnt vmcnt(0)
	s_barrier
	s_waitcnt lgkmcnt(0)
	s_setprio 1
	s_waitcnt lgkmcnt(0)
	v_mfma_f32_16x16x32_bf16 v[92:95], v[212:215], v[180:183], v[92:95]
	v_mfma_f32_16x16x32_bf16 v[88:91], v[220:223], v[180:183], v[88:91]
	v_mfma_f32_16x16x32_bf16 v[84:87], v[212:215], v[188:191], v[84:87]
	v_mfma_f32_16x16x32_bf16 v[80:83], v[220:223], v[188:191], v[80:83]
	v_mfma_f32_16x16x32_bf16 v[76:79], v[212:215], v[196:199], v[76:79]
	v_mfma_f32_16x16x32_bf16 v[72:75], v[220:223], v[196:199], v[72:75]
	v_mfma_f32_16x16x32_bf16 v[68:71], v[212:215], v[204:207], v[68:71]
	v_mfma_f32_16x16x32_bf16 v[64:67], v[220:223], v[204:207], v[64:67]
	v_mfma_f32_16x16x32_bf16 v[92:95], v[216:219], v[184:187], v[92:95]
	v_mfma_f32_16x16x32_bf16 v[88:91], v[224:227], v[184:187], v[88:91]
	v_mfma_f32_16x16x32_bf16 v[84:87], v[216:219], v[192:195], v[84:87]
	v_mfma_f32_16x16x32_bf16 v[80:83], v[224:227], v[192:195], v[80:83]
	v_mfma_f32_16x16x32_bf16 v[76:79], v[216:219], v[200:203], v[76:79]
	v_mfma_f32_16x16x32_bf16 v[72:75], v[224:227], v[200:203], v[72:75]
	v_mfma_f32_16x16x32_bf16 v[68:71], v[216:219], v[208:211], v[68:71]
	v_mfma_f32_16x16x32_bf16 v[64:67], v[224:227], v[208:211], v[64:67]
	s_setprio 0
	s_barrier
	ds_read_b128 v[180:183], v150 offset:49152
	ds_read_b128 v[184:187], v150 offset:50176
	ds_read_b128 v[188:191], v150 offset:51200
	ds_read_b128 v[192:195], v150 offset:52224
	ds_read_b128 v[196:199], v150 offset:53248
	ds_read_b128 v[200:203], v150 offset:54272
	ds_read_b128 v[204:207], v150 offset:55296
	ds_read_b128 v[208:211], v150 offset:56320
	s_barrier
	s_waitcnt lgkmcnt(0)
	s_setprio 1
	s_waitcnt lgkmcnt(0)
	v_mfma_f32_16x16x32_bf16 v[60:63], v[142:145], v[180:183], v[60:63]
	v_mfma_f32_16x16x32_bf16 v[56:59], v[172:175], v[180:183], v[56:59]
	v_mfma_f32_16x16x32_bf16 v[52:55], v[142:145], v[188:191], v[52:55]
	v_mfma_f32_16x16x32_bf16 v[48:51], v[172:175], v[188:191], v[48:51]
	v_mfma_f32_16x16x32_bf16 v[44:47], v[142:145], v[196:199], v[44:47]
	v_mfma_f32_16x16x32_bf16 v[40:43], v[172:175], v[196:199], v[40:43]
	v_mfma_f32_16x16x32_bf16 v[36:39], v[142:145], v[204:207], v[36:39]
	v_mfma_f32_16x16x32_bf16 v[32:35], v[172:175], v[204:207], v[32:35]
	v_mfma_f32_16x16x32_bf16 v[60:63], v[146:149], v[184:187], v[60:63]
	v_mfma_f32_16x16x32_bf16 v[56:59], v[176:179], v[184:187], v[56:59]
	v_mfma_f32_16x16x32_bf16 v[52:55], v[146:149], v[192:195], v[52:55]
	v_mfma_f32_16x16x32_bf16 v[48:51], v[176:179], v[192:195], v[48:51]
	v_mfma_f32_16x16x32_bf16 v[44:47], v[146:149], v[200:203], v[44:47]
	v_mfma_f32_16x16x32_bf16 v[40:43], v[176:179], v[200:203], v[40:43]
	v_mfma_f32_16x16x32_bf16 v[36:39], v[146:149], v[208:211], v[36:39]
	v_mfma_f32_16x16x32_bf16 v[32:35], v[176:179], v[208:211], v[32:35]
	s_setprio 0
	s_setprio 1
	v_mfma_f32_16x16x32_bf16 v[28:31], v[212:215], v[180:183], v[28:31]
	v_mfma_f32_16x16x32_bf16 v[24:27], v[220:223], v[180:183], v[24:27]
	v_mfma_f32_16x16x32_bf16 v[20:23], v[212:215], v[188:191], v[20:23]
	v_mfma_f32_16x16x32_bf16 v[16:19], v[220:223], v[188:191], v[16:19]
	v_mfma_f32_16x16x32_bf16 v[12:15], v[212:215], v[196:199], v[12:15]
	v_mfma_f32_16x16x32_bf16 v[8:11], v[220:223], v[196:199], v[8:11]
	v_mfma_f32_16x16x32_bf16 v[4:7], v[212:215], v[204:207], v[4:7]
	v_mfma_f32_16x16x32_bf16 v[0:3], v[220:223], v[204:207], v[0:3]
	v_mfma_f32_16x16x32_bf16 v[28:31], v[216:219], v[184:187], v[28:31]
	v_mfma_f32_16x16x32_bf16 v[24:27], v[224:227], v[184:187], v[24:27]
	v_mfma_f32_16x16x32_bf16 v[20:23], v[216:219], v[192:195], v[20:23]
	v_mfma_f32_16x16x32_bf16 v[16:19], v[224:227], v[192:195], v[16:19]
	v_mfma_f32_16x16x32_bf16 v[12:15], v[216:219], v[200:203], v[12:15]
	v_mfma_f32_16x16x32_bf16 v[8:11], v[224:227], v[200:203], v[8:11]
	v_mfma_f32_16x16x32_bf16 v[4:7], v[216:219], v[208:211], v[4:7]
	v_mfma_f32_16x16x32_bf16 v[0:3], v[224:227], v[208:211], v[0:3]
	s_setprio 0
	s_and_b64 vcc, exec, s[10:11]
	s_barrier
	s_cbranch_vccz .LBB0_341
	s_barrier

; #define SBAR() __builtin_amdgcn_sched_barrier(0)
; #define LDA8(dst, b, h) _Pragma("unroll") for (int m = 0; m < 4; ++m) _Pragma("unroll") for (int k = 0; k < 2; ++k) \
;     dst[m][k] = *reinterpret_cast<const bf16x8*>((const char*)SA8(b, h) + la + m * 2048 + k * 1024)
; #define LDB8(dst, b, h) _Pragma("unroll") for (int n = 0; n < 2; ++n) _Pragma("unroll") for (int k = 0; k < 2; ++k) \
;     dst[n][k] = *reinterpret_cast<const bf16x8*>((const char*)SB8(b, h) + lb + n * 2048 + k * 1024)
; #define MMA8(ai, bj, At_, Bx_) do { __builtin_amdgcn_s_setprio(1); \
;     _Pragma("unroll") for (int m = 0; m < 4; ++m) _Pragma("unroll") for (int n = 0; n < 2; ++n) _Pragma("unroll") for (int k = 0; k < 2; ++k) \
;       acc[ai][bj][m][n] = __builtin_amdgcn_mfma_f32_16x16x32_bf16(Bx_[n][k], At_[m][k], acc[ai][bj][m][n], 0, 0, 0); \
;     __builtin_amdgcn_s_setprio(0); } while (0)
; #define WAITV8(n) asm volatile("s_waitcnt vmcnt(" #n ")" ::: "memory")
; #define WAITL8(n) asm volatile("s_waitcnt lgkmcnt(" #n ")" ::: "memory")
; #define BAR8 __builtin_amdgcn_s_barrier()
; template <class Epi>
; DEV void gemm8_phase(const u16* __restrict__ A, int lda, const u16* __restrict__ Bt, int K, int nM, int nN, char* shmc, const Epi& epi) {
;     ...
;       LDB8(B0, 0, 0); SBAR(); LDA8(At, 0, 0); STAGE8(SA8(1, 1), A, lda, brow + HALF, kt + 1);
;       WAITL8(8); BAR8; WAITL8(0); MMA8(0, 0, At, B0); BAR8; SBAR();
;       LDB8(B1, 0, 1); STAGE8(SB8(0, 0), Bt, K, bcol, kt + 2);
;       BAR8; WAITL8(0); MMA8(0, 1, At, B1); BAR8;
;       LDA8(At, 0, 1); STAGE8(SA8(0, 0), A, lda, brow, kt + 2);
;       BAR8; WAITL8(0); MMA8(1, 0, At, B0); BAR8; SBAR();
;       STAGE8(SB8(0, 1), Bt, K, bcol + HALF, kt + 2);
;       WAITV8(6); BAR8; MMA8(1, 1, At, B1); BAR8;
.LBB0_408:
	ds_read_b128 v[144:147], v166
	ds_read_b128 v[148:151], v167
	ds_read_b128 v[152:155], v168
	ds_read_b128 v[156:159], v169
	v_add_u32_e32 v143, v160, v132
	s_mov_b32 m0, s71
	v_add_u32_e32 v214, 0x80, v143
	v_add_u32_e32 v230, v160, v142
	ds_read_b128 v[182:185], v161
	ds_read_b128 v[186:189], v161 offset:1024
	ds_read_b128 v[190:193], v161 offset:2048
	ds_read_b128 v[194:197], v161 offset:3072
	ds_read_b128 v[198:201], v161 offset:4096
	ds_read_b128 v[202:205], v161 offset:5120
	ds_read_b128 v[206:209], v161 offset:6144
	ds_read_b128 v[210:213], v161 offset:7168
	global_load_lds_dwordx4 v214, s[24:25]
	v_add_u32_e32 v214, 0x80, v230
	s_mov_b32 m0, s72
	s_nop 0
	global_load_lds_dwordx4 v214, s[24:25]
	s_waitcnt lgkmcnt(8)
	s_barrier
	s_waitcnt lgkmcnt(7)
	s_setprio 1
	v_mfma_f32_16x16x32_bf16 v[124:127], v[144:147], v[182:185], v[124:127]
	v_mfma_f32_16x16x32_bf16 v[120:123], v[152:155], v[182:185], v[120:123]
	s_waitcnt lgkmcnt(5)
	v_mfma_f32_16x16x32_bf16 v[116:119], v[144:147], v[190:193], v[116:119]
	v_mfma_f32_16x16x32_bf16 v[112:115], v[152:155], v[190:193], v[112:115]
	s_waitcnt lgkmcnt(3)
	v_mfma_f32_16x16x32_bf16 v[108:111], v[144:147], v[198:201], v[108:111]
	v_mfma_f32_16x16x32_bf16 v[104:107], v[152:155], v[198:201], v[104:107]
	s_waitcnt lgkmcnt(1)
	v_mfma_f32_16x16x32_bf16 v[100:103], v[144:147], v[206:209], v[100:103]
	v_mfma_f32_16x16x32_bf16 v[96:99], v[152:155], v[206:209], v[96:99]
	v_mfma_f32_16x16x32_bf16 v[124:127], v[148:151], v[186:189], v[124:127]
	v_mfma_f32_16x16x32_bf16 v[120:123], v[156:159], v[186:189], v[120:123]
	v_mfma_f32_16x16x32_bf16 v[116:119], v[148:151], v[194:197], v[116:119]
	v_mfma_f32_16x16x32_bf16 v[112:115], v[156:159], v[194:197], v[112:115]
	v_mfma_f32_16x16x32_bf16 v[108:111], v[148:151], v[202:205], v[108:111]
	v_mfma_f32_16x16x32_bf16 v[104:107], v[156:159], v[202:205], v[104:107]
	s_waitcnt lgkmcnt(0)
	v_mfma_f32_16x16x32_bf16 v[100:103], v[148:151], v[210:213], v[100:103]
	v_mfma_f32_16x16x32_bf16 v[96:99], v[156:159], v[210:213], v[96:99]
	s_setprio 0
	s_barrier
	s_mov_b32 m0, s30
	v_add_u32_e32 v231, 0x100, v143
	ds_read_b128 v[214:217], v170
	ds_read_b128 v[218:221], v171
	ds_read_b128 v[222:225], v172
	ds_read_b128 v[226:229], v173
	global_load_lds_dwordx4 v231, s[14:15]
	v_add_u32_e32 v232, 0x100, v230
	s_mov_b32 m0, s31
	s_nop 0
	global_load_lds_dwordx4 v232, s[14:15]
	s_barrier
	s_waitcnt lgkmcnt(3)
	s_setprio 1
	v_mfma_f32_16x16x32_bf16 v[92:95], v[214:217], v[182:185], v[92:95]
	s_waitcnt lgkmcnt(1)
	v_mfma_f32_16x16x32_bf16 v[88:91], v[222:225], v[182:185], v[88:91]
	v_mfma_f32_16x16x32_bf16 v[84:87], v[214:217], v[190:193], v[84:87]
	v_mfma_f32_16x16x32_bf16 v[80:83], v[222:225], v[190:193], v[80:83]
	v_mfma_f32_16x16x32_bf16 v[76:79], v[214:217], v[198:201], v[76:79]
	v_mfma_f32_16x16x32_bf16 v[72:75], v[222:225], v[198:201], v[72:75]
	v_mfma_f32_16x16x32_bf16 v[68:71], v[214:217], v[206:209], v[68:71]
	v_mfma_f32_16x16x32_bf16 v[64:67], v[222:225], v[206:209], v[64:67]
	v_mfma_f32_16x16x32_bf16 v[92:95], v[218:221], v[186:189], v[92:95]
	s_waitcnt lgkmcnt(0)
	v_mfma_f32_16x16x32_bf16 v[88:91], v[226:229], v[186:189], v[88:91]
	v_mfma_f32_16x16x32_bf16 v[84:87], v[218:221], v[194:197], v[84:87]
	v_mfma_f32_16x16x32_bf16 v[80:83], v[226:229], v[194:197], v[80:83]
	v_mfma_f32_16x16x32_bf16 v[76:79], v[218:221], v[202:205], v[76:79]
	v_mfma_f32_16x16x32_bf16 v[72:75], v[226:229], v[202:205], v[72:75]
	v_mfma_f32_16x16x32_bf16 v[68:71], v[218:221], v[210:213], v[68:71]
	v_mfma_f32_16x16x32_bf16 v[64:67], v[226:229], v[210:213], v[64:67]
	s_setprio 0
	s_mov_b32 m0, s28
	s_barrier
	ds_read_b128 v[182:185], v161 offset:16384
	ds_read_b128 v[186:189], v161 offset:17408
	ds_read_b128 v[190:193], v161 offset:18432
	ds_read_b128 v[194:197], v161 offset:19456
	ds_read_b128 v[198:201], v161 offset:20480
	ds_read_b128 v[202:205], v161 offset:21504
	ds_read_b128 v[206:209], v161 offset:22528
	ds_read_b128 v[210:213], v161 offset:23552
	global_load_lds_dwordx4 v231, s[22:23]
	s_mov_b32 m0, s34
	s_nop 0
	global_load_lds_dwordx4 v232, s[22:23]
	s_barrier
	s_waitcnt lgkmcnt(7)
	s_setprio 1
	v_mfma_f32_16x16x32_bf16 v[60:63], v[144:147], v[182:185], v[60:63]
	v_mfma_f32_16x16x32_bf16 v[56:59], v[152:155], v[182:185], v[56:59]
	s_waitcnt lgkmcnt(5)
	v_mfma_f32_16x16x32_bf16 v[52:55], v[144:147], v[190:193], v[52:55]
	v_mfma_f32_16x16x32_bf16 v[48:51], v[152:155], v[190:193], v[48:51]
	s_waitcnt lgkmcnt(3)
	v_mfma_f32_16x16x32_bf16 v[44:47], v[144:147], v[198:201], v[44:47]
	v_mfma_f32_16x16x32_bf16 v[40:43], v[152:155], v[198:201], v[40:43]
	s_waitcnt lgkmcnt(1)
	v_mfma_f32_16x16x32_bf16 v[36:39], v[144:147], v[206:209], v[36:39]
	v_mfma_f32_16x16x32_bf16 v[32:35], v[152:155], v[206:209], v[32:35]
	v_mfma_f32_16x16x32_bf16 v[60:63], v[148:151], v[186:189], v[60:63]
	v_mfma_f32_16x16x32_bf16 v[56:59], v[156:159], v[186:189], v[56:59]
	v_mfma_f32_16x16x32_bf16 v[52:55], v[148:151], v[194:197], v[52:55]
	v_mfma_f32_16x16x32_bf16 v[48:51], v[156:159], v[194:197], v[48:51]
	v_mfma_f32_16x16x32_bf16 v[44:47], v[148:151], v[202:205], v[44:47]
	v_mfma_f32_16x16x32_bf16 v[40:43], v[156:159], v[202:205], v[40:43]
	s_waitcnt lgkmcnt(0)
	v_mfma_f32_16x16x32_bf16 v[36:39], v[148:151], v[210:213], v[36:39]
	v_mfma_f32_16x16x32_bf16 v[32:35], v[156:159], v[210:213], v[32:35]
	s_setprio 0
	s_barrier
	s_mov_b32 m0, s35
	s_nop 0
	global_load_lds_dwordx4 v231, s[26:27]
	s_mov_b32 m0, s36
	s_nop 0
	global_load_lds_dwordx4 v232, s[26:27]
	s_waitcnt vmcnt(6)
	s_barrier
; #define SBAR() __builtin_amdgcn_sched_barrier(0)
; #define LDA8(dst, b, h) _Pragma("unroll") for (int m = 0; m < 4; ++m) _Pragma("unroll") for (int k = 0; k < 2; ++k) \
;     dst[m][k] = *reinterpret_cast<const bf16x8*>((const char*)SA8(b, h) + la + m * 2048 + k * 1024)
; #define LDB8(dst, b, h) _Pragma("unroll") for (int n = 0; n < 2; ++n) _Pragma("unroll") for (int k = 0; k < 2; ++k) \
;     dst[n][k] = *reinterpret_cast<const bf16x8*>((const char*)SB8(b, h) + lb + n * 2048 + k * 1024)
; #define MMA8(ai, bj, At_, Bx_) do { __builtin_amdgcn_s_setprio(1); \
;     _Pragma("unroll") for (int m = 0; m < 4; ++m) _Pragma("unroll") for (int n = 0; n < 2; ++n) _Pragma("unroll") for (int k = 0; k < 2; ++k) \
;       acc[ai][bj][m][n] = __builtin_amdgcn_mfma_f32_16x16x32_bf16(Bx_[n][k], At_[m][k], acc[ai][bj][m][n], 0, 0, 0); \
;     __builtin_amdgcn_s_setprio(0); } while (0)
; #define WAITV8(n) asm volatile("s_waitcnt vmcnt(" #n ")" ::: "memory")
; #define WAITL8(n) asm volatile("s_waitcnt lgkmcnt(" #n ")" ::: "memory")
; #define BAR8 __builtin_amdgcn_s_barrier()
; template <class Epi>
; DEV void gemm8_phase(const u16* __restrict__ A, int lda, const u16* __restrict__ Bt, int K, int nM, int nN, char* shmc, const Epi& epi) {
;     ...
;       WAITV8(6); BAR8; MMA8(1, 1, At, B1); BAR8;
;       LDB8(B0, 1, 0); SBAR(); LDA8(At, 1, 0); STAGE8(SA8(0, 1), A, lda, brow + HALF, kt + 2);
;       WAITL8(8); BAR8; WAITL8(0); MMA8(0, 0, At, B0); BAR8; SBAR();
;       LDB8(B1, 1, 1); STAGE8(SB8(1, 0), Bt, K, bcol, kt + 3);
;       BAR8; WAITL8(0); MMA8(0, 1, At, B1); BAR8;
;       LDA8(At, 1, 1); STAGE8(SA8(1, 0), A, lda, brow, kt + 3);
	s_setprio 1
	v_mfma_f32_16x16x32_bf16 v[28:31], v[214:217], v[182:185], v[28:31]
	v_mfma_f32_16x16x32_bf16 v[24:27], v[222:225], v[182:185], v[24:27]
	v_mfma_f32_16x16x32_bf16 v[20:23], v[214:217], v[190:193], v[20:23]
	v_mfma_f32_16x16x32_bf16 v[16:19], v[222:225], v[190:193], v[16:19]
	v_mfma_f32_16x16x32_bf16 v[12:15], v[214:217], v[198:201], v[12:15]
	v_mfma_f32_16x16x32_bf16 v[8:11], v[222:225], v[198:201], v[8:11]
	v_mfma_f32_16x16x32_bf16 v[4:7], v[214:217], v[206:209], v[4:7]
	v_mfma_f32_16x16x32_bf16 v[0:3], v[222:225], v[206:209], v[0:3]
	v_mfma_f32_16x16x32_bf16 v[28:31], v[218:221], v[186:189], v[28:31]
	v_mfma_f32_16x16x32_bf16 v[24:27], v[226:229], v[186:189], v[24:27]
	v_mfma_f32_16x16x32_bf16 v[20:23], v[218:221], v[194:197], v[20:23]
	v_mfma_f32_16x16x32_bf16 v[16:19], v[226:229], v[194:197], v[16:19]
	v_mfma_f32_16x16x32_bf16 v[12:15], v[218:221], v[202:205], v[12:15]
	v_mfma_f32_16x16x32_bf16 v[8:11], v[226:229], v[202:205], v[8:11]
	v_mfma_f32_16x16x32_bf16 v[4:7], v[218:221], v[210:213], v[4:7]
	v_mfma_f32_16x16x32_bf16 v[0:3], v[226:229], v[210:213], v[0:3]
	s_setprio 0
	s_barrier
	ds_read_b128 v[144:147], v174
	ds_read_b128 v[148:151], v175
	ds_read_b128 v[152:155], v176
	ds_read_b128 v[156:159], v177
	s_mov_b32 m0, s37
	ds_read_b128 v[182:185], v161 offset:32768
	ds_read_b128 v[186:189], v161 offset:33792
	ds_read_b128 v[190:193], v161 offset:34816
	ds_read_b128 v[194:197], v161 offset:35840
	ds_read_b128 v[198:201], v161 offset:36864
	ds_read_b128 v[202:205], v161 offset:37888
	ds_read_b128 v[206:209], v161 offset:38912
	ds_read_b128 v[210:213], v161 offset:39936
	global_load_lds_dwordx4 v231, s[24:25]
	s_mov_b32 m0, s38
	s_nop 0
	global_load_lds_dwordx4 v232, s[24:25]
	s_waitcnt lgkmcnt(8)
	s_barrier
	s_waitcnt lgkmcnt(7)
	s_setprio 1
	v_mfma_f32_16x16x32_bf16 v[124:127], v[144:147], v[182:185], v[124:127]
	v_mfma_f32_16x16x32_bf16 v[120:123], v[152:155], v[182:185], v[120:123]
	s_waitcnt lgkmcnt(5)
	v_mfma_f32_16x16x32_bf16 v[116:119], v[144:147], v[190:193], v[116:119]
	v_mfma_f32_16x16x32_bf16 v[112:115], v[152:155], v[190:193], v[112:115]
	s_waitcnt lgkmcnt(3)
	v_mfma_f32_16x16x32_bf16 v[108:111], v[144:147], v[198:201], v[108:111]
	v_mfma_f32_16x16x32_bf16 v[104:107], v[152:155], v[198:201], v[104:107]
	s_waitcnt lgkmcnt(1)
	v_mfma_f32_16x16x32_bf16 v[100:103], v[144:147], v[206:209], v[100:103]
	v_mfma_f32_16x16x32_bf16 v[96:99], v[152:155], v[206:209], v[96:99]
	v_mfma_f32_16x16x32_bf16 v[124:127], v[148:151], v[186:189], v[124:127]
	v_mfma_f32_16x16x32_bf16 v[120:123], v[156:159], v[186:189], v[120:123]
	v_mfma_f32_16x16x32_bf16 v[116:119], v[148:151], v[194:197], v[116:119]
	v_mfma_f32_16x16x32_bf16 v[112:115], v[156:159], v[194:197], v[112:115]
	v_mfma_f32_16x16x32_bf16 v[108:111], v[148:151], v[202:205], v[108:111]
	v_mfma_f32_16x16x32_bf16 v[104:107], v[156:159], v[202:205], v[104:107]
	s_waitcnt lgkmcnt(0)
	v_mfma_f32_16x16x32_bf16 v[100:103], v[148:151], v[210:213], v[100:103]
	v_mfma_f32_16x16x32_bf16 v[96:99], v[156:159], v[210:213], v[96:99]
	s_setprio 0
	s_barrier
	s_mov_b32 m0, s39
	v_add_u32_e32 v143, 0x180, v143
	ds_read_b128 v[214:217], v178
	ds_read_b128 v[218:221], v179
	ds_read_b128 v[222:225], v180
	ds_read_b128 v[226:229], v181
	global_load_lds_dwordx4 v143, s[14:15]
	v_add_u32_e32 v230, 0x180, v230
	s_mov_b32 m0, s54
	s_nop 0
	global_load_lds_dwordx4 v230, s[14:15]
	s_barrier
	s_waitcnt lgkmcnt(3)
	s_setprio 1
	v_mfma_f32_16x16x32_bf16 v[92:95], v[214:217], v[182:185], v[92:95]
	s_waitcnt lgkmcnt(1)
	v_mfma_f32_16x16x32_bf16 v[88:91], v[222:225], v[182:185], v[88:91]
	v_mfma_f32_16x16x32_bf16 v[84:87], v[214:217], v[190:193], v[84:87]
	v_mfma_f32_16x16x32_bf16 v[80:83], v[222:225], v[190:193], v[80:83]
	v_mfma_f32_16x16x32_bf16 v[76:79], v[214:217], v[198:201], v[76:79]
	v_mfma_f32_16x16x32_bf16 v[72:75], v[222:225], v[198:201], v[72:75]
	v_mfma_f32_16x16x32_bf16 v[68:71], v[214:217], v[206:209], v[68:71]
	v_mfma_f32_16x16x32_bf16 v[64:67], v[222:225], v[206:209], v[64:67]
	v_mfma_f32_16x16x32_bf16 v[92:95], v[218:221], v[186:189], v[92:95]
	s_waitcnt lgkmcnt(0)
	v_mfma_f32_16x16x32_bf16 v[88:91], v[226:229], v[186:189], v[88:91]
	v_mfma_f32_16x16x32_bf16 v[84:87], v[218:221], v[194:197], v[84:87]
	v_mfma_f32_16x16x32_bf16 v[80:83], v[226:229], v[194:197], v[80:83]
	v_mfma_f32_16x16x32_bf16 v[76:79], v[218:221], v[202:205], v[76:79]
	v_mfma_f32_16x16x32_bf16 v[72:75], v[226:229], v[202:205], v[72:75]
	v_mfma_f32_16x16x32_bf16 v[68:71], v[218:221], v[210:213], v[68:71]
	v_mfma_f32_16x16x32_bf16 v[64:67], v[226:229], v[210:213], v[64:67]
	s_setprio 0
	s_mov_b32 m0, s55
	s_barrier
	ds_read_b128 v[182:185], v161 offset:49152
	ds_read_b128 v[186:189], v161 offset:50176
	ds_read_b128 v[190:193], v161 offset:51200
	ds_read_b128 v[194:197], v161 offset:52224
	ds_read_b128 v[198:201], v161 offset:53248
	ds_read_b128 v[202:205], v161 offset:54272
	ds_read_b128 v[206:209], v161 offset:55296
	ds_read_b128 v[210:213], v161 offset:56320
	global_load_lds_dwordx4 v143, s[22:23]
	s_mov_b32 m0, s62
	s_nop 0
	global_load_lds_dwordx4 v230, s[22:23]
	s_barrier
; #define SBAR() __builtin_amdgcn_sched_barrier(0)
; #define LDA8(dst, b, h) _Pragma("unroll") for (int m = 0; m < 4; ++m) _Pragma("unroll") for (int k = 0; k < 2; ++k) \
;     dst[m][k] = *reinterpret_cast<const bf16x8*>((const char*)SA8(b, h) + la + m * 2048 + k * 1024)
; #define LDB8(dst, b, h) _Pragma("unroll") for (int n = 0; n < 2; ++n) _Pragma("unroll") for (int k = 0; k < 2; ++k) \
;     dst[n][k] = *reinterpret_cast<const bf16x8*>((const char*)SB8(b, h) + lb + n * 2048 + k * 1024)
; #define MMA8(ai, bj, At_, Bx_) do { __builtin_amdgcn_s_setprio(1); \
;     _Pragma("unroll") for (int m = 0; m < 4; ++m) _Pragma("unroll") for (int n = 0; n < 2; ++n) _Pragma("unroll") for (int k = 0; k < 2; ++k) \
;       acc[ai][bj][m][n] = __builtin_amdgcn_mfma_f32_16x16x32_bf16(Bx_[n][k], At_[m][k], acc[ai][bj][m][n], 0, 0, 0); \
;     __builtin_amdgcn_s_setprio(0); } while (0)
; #define WAITV8(n) asm volatile("s_waitcnt vmcnt(" #n ")" ::: "memory")
; #define WAITL8(n) asm volatile("s_waitcnt lgkmcnt(" #n ")" ::: "memory")
; #define BAR8 __builtin_amdgcn_s_barrier()
; template <class Epi>
; DEV void gemm8_phase(const u16* __restrict__ A, int lda, const u16* __restrict__ Bt, int K, int nM, int nN, char* shmc, const Epi& epi) {
;     ...
;       BAR8; WAITL8(0); MMA8(1, 0, At, B0); BAR8; SBAR();
;       STAGE8(SB8(1, 1), Bt, K, bcol + HALF, kt + 3);
;       WAITV8(6); BAR8; MMA8(1, 1, At, B1); BAR8;
;     }
;     { LDB8(B0, 0, 0); LDA8(At, 0, 0); STAGE8(SA8(1, 1), A, lda, brow + HALF, nt - 1);
;       BAR8; WAITL8(0); MMA8(0, 0, At, B0); BAR8;
;       LDB8(B1, 0, 1); BAR8; WAITL8(0); MMA8(0, 1, At, B1); BAR8;
	s_waitcnt lgkmcnt(7)
	s_setprio 1
	v_mfma_f32_16x16x32_bf16 v[60:63], v[144:147], v[182:185], v[60:63]
	v_mfma_f32_16x16x32_bf16 v[56:59], v[152:155], v[182:185], v[56:59]
	s_waitcnt lgkmcnt(5)
	v_mfma_f32_16x16x32_bf16 v[52:55], v[144:147], v[190:193], v[52:55]
	v_mfma_f32_16x16x32_bf16 v[48:51], v[152:155], v[190:193], v[48:51]
	s_waitcnt lgkmcnt(3)
	v_mfma_f32_16x16x32_bf16 v[44:47], v[144:147], v[198:201], v[44:47]
	v_mfma_f32_16x16x32_bf16 v[40:43], v[152:155], v[198:201], v[40:43]
	s_waitcnt lgkmcnt(1)
	v_mfma_f32_16x16x32_bf16 v[36:39], v[144:147], v[206:209], v[36:39]
	v_mfma_f32_16x16x32_bf16 v[32:35], v[152:155], v[206:209], v[32:35]
	v_mfma_f32_16x16x32_bf16 v[60:63], v[148:151], v[186:189], v[60:63]
	v_mfma_f32_16x16x32_bf16 v[56:59], v[156:159], v[186:189], v[56:59]
	v_mfma_f32_16x16x32_bf16 v[52:55], v[148:151], v[194:197], v[52:55]
	v_mfma_f32_16x16x32_bf16 v[48:51], v[156:159], v[194:197], v[48:51]
	v_mfma_f32_16x16x32_bf16 v[44:47], v[148:151], v[202:205], v[44:47]
	v_mfma_f32_16x16x32_bf16 v[40:43], v[156:159], v[202:205], v[40:43]
	s_waitcnt lgkmcnt(0)
	v_mfma_f32_16x16x32_bf16 v[36:39], v[148:151], v[210:213], v[36:39]
	v_mfma_f32_16x16x32_bf16 v[32:35], v[156:159], v[210:213], v[32:35]
	s_setprio 0
	s_barrier
	s_mov_b32 m0, s63
	s_nop 0
	global_load_lds_dwordx4 v143, s[26:27]
	s_mov_b32 m0, s70
	s_nop 0
	global_load_lds_dwordx4 v230, s[26:27]
	s_waitcnt vmcnt(6)
	s_barrier
	s_setprio 1
	v_mfma_f32_16x16x32_bf16 v[28:31], v[214:217], v[182:185], v[28:31]
	v_mfma_f32_16x16x32_bf16 v[24:27], v[222:225], v[182:185], v[24:27]
	v_mfma_f32_16x16x32_bf16 v[20:23], v[214:217], v[190:193], v[20:23]
	v_mfma_f32_16x16x32_bf16 v[16:19], v[222:225], v[190:193], v[16:19]
	v_mfma_f32_16x16x32_bf16 v[12:15], v[214:217], v[198:201], v[12:15]
	v_mfma_f32_16x16x32_bf16 v[8:11], v[222:225], v[198:201], v[8:11]
	v_mfma_f32_16x16x32_bf16 v[4:7], v[214:217], v[206:209], v[4:7]
	v_mfma_f32_16x16x32_bf16 v[0:3], v[222:225], v[206:209], v[0:3]
	v_mfma_f32_16x16x32_bf16 v[28:31], v[218:221], v[186:189], v[28:31]
	v_mfma_f32_16x16x32_bf16 v[24:27], v[226:229], v[186:189], v[24:27]
	v_mfma_f32_16x16x32_bf16 v[20:23], v[218:221], v[194:197], v[20:23]
	v_mfma_f32_16x16x32_bf16 v[16:19], v[226:229], v[194:197], v[16:19]
	v_mfma_f32_16x16x32_bf16 v[12:15], v[218:221], v[202:205], v[12:15]
	v_mfma_f32_16x16x32_bf16 v[8:11], v[226:229], v[202:205], v[8:11]
	v_mfma_f32_16x16x32_bf16 v[4:7], v[218:221], v[210:213], v[4:7]
	v_mfma_f32_16x16x32_bf16 v[0:3], v[226:229], v[210:213], v[0:3]
	s_setprio 0
	s_add_i32 s0, s0, 2
	v_add_u32_e32 v142, 0x100, v142
	s_cmp_lt_u32 s0, 28
	v_add_u32_e32 v132, 0x100, v132
	s_barrier
	s_cbranch_scc1 .LBB0_408
	s_mov_b32 m0, s71
	v_lshl_add_u64 v[158:159], s[24:25], 0, v[138:139]
	ds_read_b128 v[142:145], v166
	ds_read_b128 v[146:149], v167
	ds_read_b128 v[150:153], v168
	ds_read_b128 v[154:157], v169
	ds_read_b128 v[182:185], v161
	ds_read_b128 v[186:189], v161 offset:1024
	ds_read_b128 v[190:193], v161 offset:2048
	ds_read_b128 v[194:197], v161 offset:3072
	ds_read_b128 v[198:201], v161 offset:4096
	ds_read_b128 v[202:205], v161 offset:5120
	ds_read_b128 v[206:209], v161 offset:6144
	ds_read_b128 v[210:213], v161 offset:7168
	global_load_lds_dwordx4 v[158:159], off
	v_lshl_add_u64 v[158:159], s[24:25], 0, v[140:141]
	s_mov_b32 m0, s72
	s_nop 0
	global_load_lds_dwordx4 v[158:159], off
	s_barrier
	s_waitcnt lgkmcnt(0)
	s_setprio 1
	s_waitcnt lgkmcnt(0)
	v_mfma_f32_16x16x32_bf16 v[124:127], v[142:145], v[182:185], v[124:127]
	v_mfma_f32_16x16x32_bf16 v[116:119], v[142:145], v[190:193], v[116:119]
	v_mfma_f32_16x16x32_bf16 v[108:111], v[142:145], v[198:201], v[108:111]
	v_mfma_f32_16x16x32_bf16 v[100:103], v[142:145], v[206:209], v[100:103]
	v_mfma_f32_16x16x32_bf16 v[124:127], v[146:149], v[186:189], v[124:127]
	v_mfma_f32_16x16x32_bf16 v[120:123], v[150:153], v[182:185], v[120:123]
	v_mfma_f32_16x16x32_bf16 v[116:119], v[146:149], v[194:197], v[116:119]
	v_mfma_f32_16x16x32_bf16 v[112:115], v[150:153], v[190:193], v[112:115]
	v_mfma_f32_16x16x32_bf16 v[108:111], v[146:149], v[202:205], v[108:111]
	v_mfma_f32_16x16x32_bf16 v[104:107], v[150:153], v[198:201], v[104:107]
	v_mfma_f32_16x16x32_bf16 v[100:103], v[146:149], v[210:213], v[100:103]
	v_mfma_f32_16x16x32_bf16 v[96:99], v[150:153], v[206:209], v[96:99]
	v_mfma_f32_16x16x32_bf16 v[214:217], v[154:157], v[186:189], v[120:123]
	v_mfma_f32_16x16x32_bf16 v[218:221], v[154:157], v[194:197], v[112:115]
	v_mfma_f32_16x16x32_bf16 v[222:225], v[154:157], v[202:205], v[104:107]
	v_mfma_f32_16x16x32_bf16 v[226:229], v[154:157], v[210:213], v[96:99]
	s_setprio 0
	s_barrier
	s_nop 1
	ds_read_b128 v[96:99], v170
	ds_read_b128 v[104:107], v171
	ds_read_b128 v[112:115], v172
	ds_read_b128 v[120:123], v173
	s_barrier
	s_waitcnt lgkmcnt(0)
	s_setprio 1
	s_waitcnt lgkmcnt(0)
	v_mfma_f32_16x16x32_bf16 v[92:95], v[96:99], v[182:185], v[92:95]
	v_mfma_f32_16x16x32_bf16 v[84:87], v[96:99], v[190:193], v[84:87]
	v_mfma_f32_16x16x32_bf16 v[76:79], v[96:99], v[198:201], v[76:79]
	v_mfma_f32_16x16x32_bf16 v[68:71], v[96:99], v[206:209], v[68:71]
	v_mfma_f32_16x16x32_bf16 v[92:95], v[104:107], v[186:189], v[92:95]
	v_mfma_f32_16x16x32_bf16 v[88:91], v[112:115], v[182:185], v[88:91]
	v_mfma_f32_16x16x32_bf16 v[84:87], v[104:107], v[194:197], v[84:87]
	v_mfma_f32_16x16x32_bf16 v[80:83], v[112:115], v[190:193], v[80:83]
	v_mfma_f32_16x16x32_bf16 v[76:79], v[104:107], v[202:205], v[76:79]
	v_mfma_f32_16x16x32_bf16 v[72:75], v[112:115], v[198:201], v[72:75]
	v_mfma_f32_16x16x32_bf16 v[68:71], v[104:107], v[210:213], v[68:71]
	v_mfma_f32_16x16x32_bf16 v[64:67], v[112:115], v[206:209], v[64:67]
	v_mfma_f32_16x16x32_bf16 v[182:185], v[120:123], v[186:189], v[88:91]
	v_mfma_f32_16x16x32_bf16 v[186:189], v[120:123], v[194:197], v[80:83]
	v_mfma_f32_16x16x32_bf16 v[190:193], v[120:123], v[202:205], v[72:75]
	v_mfma_f32_16x16x32_bf16 v[194:197], v[120:123], v[210:213], v[64:67]
	s_setprio 0
	s_barrier
; #define LDA8(dst, b, h) _Pragma("unroll") for (int m = 0; m < 4; ++m) _Pragma("unroll") for (int k = 0; k < 2; ++k) \
;     dst[m][k] = *reinterpret_cast<const bf16x8*>((const char*)SA8(b, h) + la + m * 2048 + k * 1024)
; #define LDB8(dst, b, h) _Pragma("unroll") for (int n = 0; n < 2; ++n) _Pragma("unroll") for (int k = 0; k < 2; ++k) \
;     dst[n][k] = *reinterpret_cast<const bf16x8*>((const char*)SB8(b, h) + lb + n * 2048 + k * 1024)
; #define MMA8(ai, bj, At_, Bx_) do { __builtin_amdgcn_s_setprio(1); \
;     _Pragma("unroll") for (int m = 0; m < 4; ++m) _Pragma("unroll") for (int n = 0; n < 2; ++n) _Pragma("unroll") for (int k = 0; k < 2; ++k) \
;       acc[ai][bj][m][n] = __builtin_amdgcn_mfma_f32_16x16x32_bf16(Bx_[n][k], At_[m][k], acc[ai][bj][m][n], 0, 0, 0); \
;     __builtin_amdgcn_s_setprio(0); } while (0)
; #define WAITV8(n) asm volatile("s_waitcnt vmcnt(" #n ")" ::: "memory")
; #define WAITL8(n) asm volatile("s_waitcnt lgkmcnt(" #n ")" ::: "memory")
; #define BAR8 __builtin_amdgcn_s_barrier()
; template <class Epi>
; DEV void gemm8_phase(const u16* __restrict__ A, int lda, const u16* __restrict__ Bt, int K, int nM, int nN, char* shmc, const Epi& epi) {
;     ...
;       LDA8(At, 0, 1); WAITV8(4); BAR8; WAITL8(0); MMA8(1, 0, At, B0); MMA8(1, 1, At, B1); BAR8; }
;     { LDB8(B0, 1, 0); LDA8(At, 1, 0); WAITV8(2); BAR8; WAITL8(0); MMA8(0, 0, At, B0); BAR8;
	s_nop 1
	ds_read_b128 v[64:67], v161 offset:16384
	ds_read_b128 v[72:75], v161 offset:17408
	ds_read_b128 v[80:83], v161 offset:18432
	ds_read_b128 v[88:91], v161 offset:19456
	ds_read_b128 v[198:201], v161 offset:20480
	ds_read_b128 v[202:205], v161 offset:21504
	ds_read_b128 v[206:209], v161 offset:22528
	ds_read_b128 v[210:213], v161 offset:23552
	s_waitcnt vmcnt(4)
	s_barrier
	s_waitcnt lgkmcnt(0)
	s_setprio 1
	s_waitcnt lgkmcnt(0)
	v_mfma_f32_16x16x32_bf16 v[60:63], v[142:145], v[64:67], v[60:63]
	v_mfma_f32_16x16x32_bf16 v[52:55], v[142:145], v[80:83], v[52:55]
	v_mfma_f32_16x16x32_bf16 v[44:47], v[142:145], v[198:201], v[44:47]
	v_mfma_f32_16x16x32_bf16 v[36:39], v[142:145], v[206:209], v[36:39]
	v_mfma_f32_16x16x32_bf16 v[60:63], v[146:149], v[72:75], v[60:63]
	v_mfma_f32_16x16x32_bf16 v[56:59], v[150:153], v[64:67], v[56:59]
	v_mfma_f32_16x16x32_bf16 v[52:55], v[146:149], v[88:91], v[52:55]
	v_mfma_f32_16x16x32_bf16 v[48:51], v[150:153], v[80:83], v[48:51]
	v_mfma_f32_16x16x32_bf16 v[44:47], v[146:149], v[202:205], v[44:47]
	v_mfma_f32_16x16x32_bf16 v[40:43], v[150:153], v[198:201], v[40:43]
	v_mfma_f32_16x16x32_bf16 v[36:39], v[146:149], v[210:213], v[36:39]
	v_mfma_f32_16x16x32_bf16 v[32:35], v[150:153], v[206:209], v[32:35]
	v_mfma_f32_16x16x32_bf16 v[230:233], v[154:157], v[72:75], v[56:59]
	v_mfma_f32_16x16x32_bf16 v[234:237], v[154:157], v[88:91], v[48:51]
	v_mfma_f32_16x16x32_bf16 v[238:241], v[154:157], v[202:205], v[40:43]
	v_mfma_f32_16x16x32_bf16 v[142:145], v[154:157], v[210:213], v[32:35]
	s_setprio 0
	s_setprio 1
	v_mfma_f32_16x16x32_bf16 v[28:31], v[96:99], v[64:67], v[28:31]
	v_mfma_f32_16x16x32_bf16 v[20:23], v[96:99], v[80:83], v[20:23]
	v_mfma_f32_16x16x32_bf16 v[12:15], v[96:99], v[198:201], v[12:15]
	v_mfma_f32_16x16x32_bf16 v[4:7], v[96:99], v[206:209], v[4:7]
	v_mfma_f32_16x16x32_bf16 v[28:31], v[104:107], v[72:75], v[28:31]
	v_mfma_f32_16x16x32_bf16 v[24:27], v[112:115], v[64:67], v[24:27]
	v_mfma_f32_16x16x32_bf16 v[20:23], v[104:107], v[88:91], v[20:23]
	v_mfma_f32_16x16x32_bf16 v[16:19], v[112:115], v[80:83], v[16:19]
	v_mfma_f32_16x16x32_bf16 v[12:15], v[104:107], v[202:205], v[12:15]
	v_mfma_f32_16x16x32_bf16 v[8:11], v[112:115], v[198:201], v[8:11]
	v_mfma_f32_16x16x32_bf16 v[4:7], v[104:107], v[210:213], v[4:7]
	v_mfma_f32_16x16x32_bf16 v[0:3], v[112:115], v[206:209], v[0:3]
	v_mfma_f32_16x16x32_bf16 v[146:149], v[120:123], v[72:75], v[24:27]
	v_mfma_f32_16x16x32_bf16 v[150:153], v[120:123], v[88:91], v[16:19]
	v_mfma_f32_16x16x32_bf16 v[154:157], v[120:123], v[202:205], v[8:11]
	v_mfma_f32_16x16x32_bf16 v[198:201], v[120:123], v[210:213], v[0:3]
	s_setprio 0
	s_barrier
	s_nop 1
	ds_read_b128 v[0:3], v174
	ds_read_b128 v[8:11], v175
	ds_read_b128 v[16:19], v176
	ds_read_b128 v[24:27], v177
	ds_read_b128 v[32:35], v161 offset:32768
	ds_read_b128 v[40:43], v161 offset:33792
	ds_read_b128 v[48:51], v161 offset:34816
	ds_read_b128 v[56:59], v161 offset:35840
	ds_read_b128 v[64:67], v161 offset:36864
	ds_read_b128 v[202:205], v161 offset:37888
	ds_read_b128 v[206:209], v161 offset:38912
	ds_read_b128 v[210:213], v161 offset:39936
	s_waitcnt vmcnt(2)
	s_barrier
	s_waitcnt lgkmcnt(0)
	s_setprio 1
	s_waitcnt lgkmcnt(0)
	v_mfma_f32_16x16x32_bf16 v[72:75], v[0:3], v[32:35], v[124:127]
	v_mfma_f32_16x16x32_bf16 v[120:123], v[8:11], v[40:43], v[72:75]
	v_mfma_f32_16x16x32_bf16 v[72:75], v[16:19], v[32:35], v[214:217]
	v_mfma_f32_16x16x32_bf16 v[124:127], v[24:27], v[40:43], v[72:75]
	v_mfma_f32_16x16x32_bf16 v[72:75], v[0:3], v[48:51], v[116:119]
	v_mfma_f32_16x16x32_bf16 v[112:115], v[8:11], v[56:59], v[72:75]
	v_mfma_f32_16x16x32_bf16 v[72:75], v[16:19], v[48:51], v[218:221]
	v_mfma_f32_16x16x32_bf16 v[116:119], v[24:27], v[56:59], v[72:75]
	v_mfma_f32_16x16x32_bf16 v[72:75], v[0:3], v[64:67], v[108:111]
	v_mfma_f32_16x16x32_bf16 v[104:107], v[8:11], v[202:205], v[72:75]
	v_mfma_f32_16x16x32_bf16 v[72:75], v[16:19], v[64:67], v[222:225]
	v_mfma_f32_16x16x32_bf16 v[108:111], v[24:27], v[202:205], v[72:75]
	v_mfma_f32_16x16x32_bf16 v[72:75], v[0:3], v[206:209], v[100:103]
	v_mfma_f32_16x16x32_bf16 v[96:99], v[8:11], v[210:213], v[72:75]
	v_mfma_f32_16x16x32_bf16 v[72:75], v[16:19], v[206:209], v[226:229]
	v_mfma_f32_16x16x32_bf16 v[100:103], v[24:27], v[210:213], v[72:75]
	s_setprio 0
	s_barrier
; #define LDA8(dst, b, h) _Pragma("unroll") for (int m = 0; m < 4; ++m) _Pragma("unroll") for (int k = 0; k < 2; ++k) \
;     dst[m][k] = *reinterpret_cast<const bf16x8*>((const char*)SA8(b, h) + la + m * 2048 + k * 1024)
; #define LDB8(dst, b, h) _Pragma("unroll") for (int n = 0; n < 2; ++n) _Pragma("unroll") for (int k = 0; k < 2; ++k) \
;     dst[n][k] = *reinterpret_cast<const bf16x8*>((const char*)SB8(b, h) + lb + n * 2048 + k * 1024)
; #define MMA8(ai, bj, At_, Bx_) do { __builtin_amdgcn_s_setprio(1); \
;     _Pragma("unroll") for (int m = 0; m < 4; ++m) _Pragma("unroll") for (int n = 0; n < 2; ++n) _Pragma("unroll") for (int k = 0; k < 2; ++k) \
;       acc[ai][bj][m][n] = __builtin_amdgcn_mfma_f32_16x16x32_bf16(Bx_[n][k], At_[m][k], acc[ai][bj][m][n], 0, 0, 0); \
;     __builtin_amdgcn_s_setprio(0); } while (0)
; #define WAITV8(n) asm volatile("s_waitcnt vmcnt(" #n ")" ::: "memory")
; #define WAITL8(n) asm volatile("s_waitcnt lgkmcnt(" #n ")" ::: "memory")
; #define BAR8 __builtin_amdgcn_s_barrier()
; template <class Epi>
; DEV void gemm8_phase(const u16* __restrict__ A, int lda, const u16* __restrict__ Bt, int K, int nM, int nN, char* shmc, const Epi& epi) {
;     ...
;       LDB8(B1, 1, 1); WAITV8(0); BAR8; WAITL8(0); MMA8(0, 1, At, B1); BAR8;
;       LDA8(At, 1, 1); BAR8; WAITL8(0); MMA8(1, 0, At, B0); MMA8(1, 1, At, B1); BAR8; }
;     if (wr == 0) BAR8;
	ds_read_b128 v[214:217], v178
	ds_read_b128 v[218:221], v179
	ds_read_b128 v[222:225], v180
	ds_read_b128 v[226:229], v181
	s_waitcnt vmcnt(0)
	s_barrier
	s_waitcnt lgkmcnt(0)
	s_setprio 1
	s_waitcnt lgkmcnt(0)
	v_mfma_f32_16x16x32_bf16 v[72:75], v[214:217], v[32:35], v[92:95]
	v_mfma_f32_16x16x32_bf16 v[32:35], v[222:225], v[32:35], v[182:185]
	v_mfma_f32_16x16x32_bf16 v[92:95], v[226:229], v[40:43], v[32:35]
	v_mfma_f32_16x16x32_bf16 v[32:35], v[214:217], v[48:51], v[84:87]
	v_mfma_f32_16x16x32_bf16 v[80:83], v[218:221], v[56:59], v[32:35]
	v_mfma_f32_16x16x32_bf16 v[32:35], v[222:225], v[48:51], v[186:189]
	v_mfma_f32_16x16x32_bf16 v[84:87], v[226:229], v[56:59], v[32:35]
	v_mfma_f32_16x16x32_bf16 v[32:35], v[214:217], v[64:67], v[76:79]
	v_mfma_f32_16x16x32_bf16 v[88:91], v[218:221], v[40:43], v[72:75]
	v_mfma_f32_16x16x32_bf16 v[72:75], v[218:221], v[202:205], v[32:35]
	v_mfma_f32_16x16x32_bf16 v[32:35], v[222:225], v[64:67], v[190:193]
	v_mfma_f32_16x16x32_bf16 v[76:79], v[226:229], v[202:205], v[32:35]
	v_mfma_f32_16x16x32_bf16 v[32:35], v[214:217], v[206:209], v[68:71]
	v_mfma_f32_16x16x32_bf16 v[64:67], v[218:221], v[210:213], v[32:35]
	v_mfma_f32_16x16x32_bf16 v[32:35], v[222:225], v[206:209], v[194:197]
	v_mfma_f32_16x16x32_bf16 v[68:71], v[226:229], v[210:213], v[32:35]
	s_setprio 0
	s_barrier
	ds_read_b128 v[182:185], v161 offset:49152
	ds_read_b128 v[186:189], v161 offset:50176
	ds_read_b128 v[190:193], v161 offset:51200
	ds_read_b128 v[194:197], v161 offset:52224
	ds_read_b128 v[202:205], v161 offset:53248
	ds_read_b128 v[206:209], v161 offset:54272
	ds_read_b128 v[210:213], v161 offset:55296
	ds_read_b128 v[242:245], v161 offset:56320
	s_barrier
	s_waitcnt lgkmcnt(0)
	s_setprio 1
	s_waitcnt lgkmcnt(0)
	v_mfma_f32_16x16x32_bf16 v[32:35], v[0:3], v[182:185], v[60:63]
	v_mfma_f32_16x16x32_bf16 v[56:59], v[8:11], v[186:189], v[32:35]
	v_mfma_f32_16x16x32_bf16 v[32:35], v[16:19], v[182:185], v[230:233]
	v_mfma_f32_16x16x32_bf16 v[60:63], v[24:27], v[186:189], v[32:35]
	v_mfma_f32_16x16x32_bf16 v[32:35], v[0:3], v[190:193], v[52:55]
	v_mfma_f32_16x16x32_bf16 v[48:51], v[8:11], v[194:197], v[32:35]
	v_mfma_f32_16x16x32_bf16 v[32:35], v[16:19], v[190:193], v[234:237]
	v_mfma_f32_16x16x32_bf16 v[52:55], v[24:27], v[194:197], v[32:35]
	v_mfma_f32_16x16x32_bf16 v[32:35], v[0:3], v[202:205], v[44:47]
	v_mfma_f32_16x16x32_bf16 v[40:43], v[8:11], v[206:209], v[32:35]
	v_mfma_f32_16x16x32_bf16 v[32:35], v[16:19], v[202:205], v[238:241]
	v_mfma_f32_16x16x32_bf16 v[0:3], v[0:3], v[210:213], v[36:39]
	v_mfma_f32_16x16x32_bf16 v[44:47], v[24:27], v[206:209], v[32:35]
	v_mfma_f32_16x16x32_bf16 v[32:35], v[8:11], v[242:245], v[0:3]
	v_mfma_f32_16x16x32_bf16 v[0:3], v[16:19], v[210:213], v[142:145]
	v_mfma_f32_16x16x32_bf16 v[36:39], v[24:27], v[242:245], v[0:3]
	s_setprio 0
	s_setprio 1
	v_mfma_f32_16x16x32_bf16 v[0:3], v[214:217], v[182:185], v[28:31]
	v_mfma_f32_16x16x32_bf16 v[24:27], v[218:221], v[186:189], v[0:3]
	v_mfma_f32_16x16x32_bf16 v[0:3], v[222:225], v[182:185], v[146:149]
	v_mfma_f32_16x16x32_bf16 v[28:31], v[226:229], v[186:189], v[0:3]
	v_mfma_f32_16x16x32_bf16 v[0:3], v[214:217], v[190:193], v[20:23]
	v_mfma_f32_16x16x32_bf16 v[16:19], v[218:221], v[194:197], v[0:3]
	v_mfma_f32_16x16x32_bf16 v[0:3], v[222:225], v[190:193], v[150:153]
	v_mfma_f32_16x16x32_bf16 v[20:23], v[226:229], v[194:197], v[0:3]
	v_mfma_f32_16x16x32_bf16 v[0:3], v[214:217], v[202:205], v[12:15]
	v_mfma_f32_16x16x32_bf16 v[8:11], v[218:221], v[206:209], v[0:3]
	v_mfma_f32_16x16x32_bf16 v[0:3], v[222:225], v[202:205], v[154:157]
	v_mfma_f32_16x16x32_bf16 v[12:15], v[226:229], v[206:209], v[0:3]
	v_mfma_f32_16x16x32_bf16 v[0:3], v[214:217], v[210:213], v[4:7]
	v_mfma_f32_16x16x32_bf16 v[4:7], v[222:225], v[210:213], v[198:201]
	v_mfma_f32_16x16x32_bf16 v[0:3], v[218:221], v[242:245], v[0:3]
	v_mfma_f32_16x16x32_bf16 v[4:7], v[226:229], v[242:245], v[4:7]
	s_setprio 0
	s_andn2_b64 vcc, exec, s[12:13]
	s_barrier
	s_cbranch_vccnz .LBB0_411
	s_barrier

; #define SBAR() __builtin_amdgcn_sched_barrier(0)
; #define LDA8(dst, b, h) _Pragma("unroll") for (int m = 0; m < 4; ++m) _Pragma("unroll") for (int k = 0; k < 2; ++k) \
;     dst[m][k] = *reinterpret_cast<const bf16x8*>((const char*)SA8(b, h) + la + m * 2048 + k * 1024)
; #define LDB8(dst, b, h) _Pragma("unroll") for (int n = 0; n < 2; ++n) _Pragma("unroll") for (int k = 0; k < 2; ++k) \
;     dst[n][k] = *reinterpret_cast<const bf16x8*>((const char*)SB8(b, h) + lb + n * 2048 + k * 1024)
; #define MMA8(ai, bj, At_, Bx_) do { __builtin_amdgcn_s_setprio(1); \
;     _Pragma("unroll") for (int m = 0; m < 4; ++m) _Pragma("unroll") for (int n = 0; n < 2; ++n) _Pragma("unroll") for (int k = 0; k < 2; ++k) \
;       acc[ai][bj][m][n] = __builtin_amdgcn_mfma_f32_16x16x32_bf16(Bx_[n][k], At_[m][k], acc[ai][bj][m][n], 0, 0, 0); \
;     __builtin_amdgcn_s_setprio(0); } while (0)
; #define WAITV8(n) asm volatile("s_waitcnt vmcnt(" #n ")" ::: "memory")
; #define WAITL8(n) asm volatile("s_waitcnt lgkmcnt(" #n ")" ::: "memory")
; #define BAR8 __builtin_amdgcn_s_barrier()
; template <class Epi>
; DEV void gemm8_phase(const u16* __restrict__ A, int lda, const u16* __restrict__ Bt, int K, int nM, int nN, char* shmc, const Epi& epi) {
;     ...
;       LDB8(B0, 0, 0); SBAR(); LDA8(At, 0, 0); STAGE8(SA8(1, 1), A, lda, brow + HALF, kt + 1);
;       WAITL8(8); BAR8; WAITL8(0); MMA8(0, 0, At, B0); BAR8; SBAR();
;       LDB8(B1, 0, 1); STAGE8(SB8(0, 0), Bt, K, bcol, kt + 2);
;       BAR8; WAITL8(0); MMA8(0, 1, At, B1); BAR8;
;       LDA8(At, 0, 1); STAGE8(SA8(0, 0), A, lda, brow, kt + 2);
;       BAR8; WAITL8(0); MMA8(1, 0, At, B0); BAR8; SBAR();
;       STAGE8(SB8(0, 1), Bt, K, bcol + HALF, kt + 2);
;       WAITV8(6); BAR8; MMA8(1, 1, At, B1); BAR8;
.LBB0_431:
	ds_read_b128 v[144:147], v154
	ds_read_b128 v[174:177], v155
	ds_read_b128 v[178:181], v156
	ds_read_b128 v[182:185], v157
	v_add_u32_e32 v143, v151, v132
	s_mov_b32 m0, s37
	v_add_u32_e32 v148, 0x80, v143
	ds_read_b128 v[186:189], v150
	ds_read_b128 v[190:193], v150 offset:1024
	ds_read_b128 v[194:197], v150 offset:2048
	ds_read_b128 v[198:201], v150 offset:3072
	ds_read_b128 v[202:205], v150 offset:4096
	ds_read_b128 v[206:209], v150 offset:5120
	ds_read_b128 v[210:213], v150 offset:6144
	ds_read_b128 v[214:217], v150 offset:7168
	global_load_lds_dwordx4 v148, s[16:17]
	v_add_u32_e32 v148, v151, v142
	v_add_u32_e32 v149, 0x80, v148
	s_mov_b32 m0, s38
	s_nop 0
	global_load_lds_dwordx4 v149, s[16:17]
	s_waitcnt lgkmcnt(8)
	s_barrier
	s_waitcnt lgkmcnt(7)
	s_setprio 1
	v_mfma_f32_16x16x32_bf16 v[124:127], v[144:147], v[186:189], v[124:127]
	v_mfma_f32_16x16x32_bf16 v[120:123], v[178:181], v[186:189], v[120:123]
	s_waitcnt lgkmcnt(5)
	v_mfma_f32_16x16x32_bf16 v[116:119], v[144:147], v[194:197], v[116:119]
	v_mfma_f32_16x16x32_bf16 v[112:115], v[178:181], v[194:197], v[112:115]
	s_waitcnt lgkmcnt(3)
	v_mfma_f32_16x16x32_bf16 v[108:111], v[144:147], v[202:205], v[108:111]
	v_mfma_f32_16x16x32_bf16 v[104:107], v[178:181], v[202:205], v[104:107]
	s_waitcnt lgkmcnt(1)
	v_mfma_f32_16x16x32_bf16 v[100:103], v[144:147], v[210:213], v[100:103]
	v_mfma_f32_16x16x32_bf16 v[96:99], v[178:181], v[210:213], v[96:99]
	v_mfma_f32_16x16x32_bf16 v[124:127], v[174:177], v[190:193], v[124:127]
	v_mfma_f32_16x16x32_bf16 v[120:123], v[182:185], v[190:193], v[120:123]
	v_mfma_f32_16x16x32_bf16 v[116:119], v[174:177], v[198:201], v[116:119]
	v_mfma_f32_16x16x32_bf16 v[112:115], v[182:185], v[198:201], v[112:115]
	v_mfma_f32_16x16x32_bf16 v[108:111], v[174:177], v[206:209], v[108:111]
	v_mfma_f32_16x16x32_bf16 v[104:107], v[182:185], v[206:209], v[104:107]
	s_waitcnt lgkmcnt(0)
	v_mfma_f32_16x16x32_bf16 v[100:103], v[174:177], v[214:217], v[100:103]
	v_mfma_f32_16x16x32_bf16 v[96:99], v[182:185], v[214:217], v[96:99]
	s_setprio 0
	s_barrier
	s_mov_b32 m0, s22
	v_add_u32_e32 v149, 0x100, v143
	ds_read_b128 v[218:221], v158
	ds_read_b128 v[222:225], v159
	ds_read_b128 v[226:229], v160
	ds_read_b128 v[230:233], v161
	global_load_lds_dwordx4 v149, s[6:7]
	v_add_u32_e32 v173, 0x100, v148
	s_mov_b32 m0, s23
	s_nop 0
	global_load_lds_dwordx4 v173, s[6:7]
	s_barrier
	s_waitcnt lgkmcnt(3)
	s_setprio 1
	v_mfma_f32_16x16x32_bf16 v[92:95], v[218:221], v[186:189], v[92:95]
	s_waitcnt lgkmcnt(1)
	v_mfma_f32_16x16x32_bf16 v[88:91], v[226:229], v[186:189], v[88:91]
	v_mfma_f32_16x16x32_bf16 v[84:87], v[218:221], v[194:197], v[84:87]
	v_mfma_f32_16x16x32_bf16 v[80:83], v[226:229], v[194:197], v[80:83]
	v_mfma_f32_16x16x32_bf16 v[76:79], v[218:221], v[202:205], v[76:79]
	v_mfma_f32_16x16x32_bf16 v[72:75], v[226:229], v[202:205], v[72:75]
	v_mfma_f32_16x16x32_bf16 v[68:71], v[218:221], v[210:213], v[68:71]
	v_mfma_f32_16x16x32_bf16 v[64:67], v[226:229], v[210:213], v[64:67]
	v_mfma_f32_16x16x32_bf16 v[92:95], v[222:225], v[190:193], v[92:95]
	s_waitcnt lgkmcnt(0)
	v_mfma_f32_16x16x32_bf16 v[88:91], v[230:233], v[190:193], v[88:91]
	v_mfma_f32_16x16x32_bf16 v[84:87], v[222:225], v[198:201], v[84:87]
	v_mfma_f32_16x16x32_bf16 v[80:83], v[230:233], v[198:201], v[80:83]
	v_mfma_f32_16x16x32_bf16 v[76:79], v[222:225], v[206:209], v[76:79]
	v_mfma_f32_16x16x32_bf16 v[72:75], v[230:233], v[206:209], v[72:75]
	v_mfma_f32_16x16x32_bf16 v[68:71], v[222:225], v[214:217], v[68:71]
	v_mfma_f32_16x16x32_bf16 v[64:67], v[230:233], v[214:217], v[64:67]
	s_setprio 0
	s_mov_b32 m0, s20
	s_barrier
	ds_read_b128 v[186:189], v150 offset:16384
	ds_read_b128 v[190:193], v150 offset:17408
	ds_read_b128 v[194:197], v150 offset:18432
	ds_read_b128 v[198:201], v150 offset:19456
	ds_read_b128 v[202:205], v150 offset:20480
	ds_read_b128 v[206:209], v150 offset:21504
	ds_read_b128 v[210:213], v150 offset:22528
	ds_read_b128 v[214:217], v150 offset:23552
	global_load_lds_dwordx4 v149, s[14:15]
	s_mov_b32 m0, s24
	s_nop 0
	global_load_lds_dwordx4 v173, s[14:15]
	s_barrier
	s_waitcnt lgkmcnt(7)
	s_setprio 1
	v_mfma_f32_16x16x32_bf16 v[60:63], v[144:147], v[186:189], v[60:63]
	v_mfma_f32_16x16x32_bf16 v[56:59], v[178:181], v[186:189], v[56:59]
	s_waitcnt lgkmcnt(5)
	v_mfma_f32_16x16x32_bf16 v[52:55], v[144:147], v[194:197], v[52:55]
	v_mfma_f32_16x16x32_bf16 v[48:51], v[178:181], v[194:197], v[48:51]
	s_waitcnt lgkmcnt(3)
	v_mfma_f32_16x16x32_bf16 v[44:47], v[144:147], v[202:205], v[44:47]
	v_mfma_f32_16x16x32_bf16 v[40:43], v[178:181], v[202:205], v[40:43]
	s_waitcnt lgkmcnt(1)
	v_mfma_f32_16x16x32_bf16 v[36:39], v[144:147], v[210:213], v[36:39]
	v_mfma_f32_16x16x32_bf16 v[32:35], v[178:181], v[210:213], v[32:35]
	v_mfma_f32_16x16x32_bf16 v[60:63], v[174:177], v[190:193], v[60:63]
	v_mfma_f32_16x16x32_bf16 v[56:59], v[182:185], v[190:193], v[56:59]
	v_mfma_f32_16x16x32_bf16 v[52:55], v[174:177], v[198:201], v[52:55]
	v_mfma_f32_16x16x32_bf16 v[48:51], v[182:185], v[198:201], v[48:51]
	v_mfma_f32_16x16x32_bf16 v[44:47], v[174:177], v[206:209], v[44:47]
	v_mfma_f32_16x16x32_bf16 v[40:43], v[182:185], v[206:209], v[40:43]
	s_waitcnt lgkmcnt(0)
	v_mfma_f32_16x16x32_bf16 v[36:39], v[174:177], v[214:217], v[36:39]
	v_mfma_f32_16x16x32_bf16 v[32:35], v[182:185], v[214:217], v[32:35]
	s_setprio 0
	s_barrier
	s_mov_b32 m0, s25
	s_nop 0
	global_load_lds_dwordx4 v149, s[18:19]
	s_mov_b32 m0, s26
	s_nop 0
	global_load_lds_dwordx4 v173, s[18:19]
	s_waitcnt vmcnt(6)
	s_barrier
; #define SBAR() __builtin_amdgcn_sched_barrier(0)
; #define LDA8(dst, b, h) _Pragma("unroll") for (int m = 0; m < 4; ++m) _Pragma("unroll") for (int k = 0; k < 2; ++k) \
;     dst[m][k] = *reinterpret_cast<const bf16x8*>((const char*)SA8(b, h) + la + m * 2048 + k * 1024)
; #define LDB8(dst, b, h) _Pragma("unroll") for (int n = 0; n < 2; ++n) _Pragma("unroll") for (int k = 0; k < 2; ++k) \
;     dst[n][k] = *reinterpret_cast<const bf16x8*>((const char*)SB8(b, h) + lb + n * 2048 + k * 1024)
; #define MMA8(ai, bj, At_, Bx_) do { __builtin_amdgcn_s_setprio(1); \
;     _Pragma("unroll") for (int m = 0; m < 4; ++m) _Pragma("unroll") for (int n = 0; n < 2; ++n) _Pragma("unroll") for (int k = 0; k < 2; ++k) \
;       acc[ai][bj][m][n] = __builtin_amdgcn_mfma_f32_16x16x32_bf16(Bx_[n][k], At_[m][k], acc[ai][bj][m][n], 0, 0, 0); \
;     __builtin_amdgcn_s_setprio(0); } while (0)
; #define WAITV8(n) asm volatile("s_waitcnt vmcnt(" #n ")" ::: "memory")
; #define WAITL8(n) asm volatile("s_waitcnt lgkmcnt(" #n ")" ::: "memory")
; #define BAR8 __builtin_amdgcn_s_barrier()
; template <class Epi>
; DEV void gemm8_phase(const u16* __restrict__ A, int lda, const u16* __restrict__ Bt, int K, int nM, int nN, char* shmc, const Epi& epi) {
;     ...
;       WAITV8(6); BAR8; MMA8(1, 1, At, B1); BAR8;
;       LDB8(B0, 1, 0); SBAR(); LDA8(At, 1, 0); STAGE8(SA8(0, 1), A, lda, brow + HALF, kt + 2);
;       WAITL8(8); BAR8; WAITL8(0); MMA8(0, 0, At, B0); BAR8; SBAR();
;       LDB8(B1, 1, 1); STAGE8(SB8(1, 0), Bt, K, bcol, kt + 3);
;       BAR8; WAITL8(0); MMA8(0, 1, At, B1); BAR8;
;       LDA8(At, 1, 1); STAGE8(SA8(1, 0), A, lda, brow, kt + 3);
	s_setprio 1
	v_mfma_f32_16x16x32_bf16 v[28:31], v[218:221], v[186:189], v[28:31]
	v_mfma_f32_16x16x32_bf16 v[24:27], v[226:229], v[186:189], v[24:27]
	v_mfma_f32_16x16x32_bf16 v[20:23], v[218:221], v[194:197], v[20:23]
	v_mfma_f32_16x16x32_bf16 v[16:19], v[226:229], v[194:197], v[16:19]
	v_mfma_f32_16x16x32_bf16 v[12:15], v[218:221], v[202:205], v[12:15]
	v_mfma_f32_16x16x32_bf16 v[8:11], v[226:229], v[202:205], v[8:11]
	v_mfma_f32_16x16x32_bf16 v[4:7], v[218:221], v[210:213], v[4:7]
	v_mfma_f32_16x16x32_bf16 v[0:3], v[226:229], v[210:213], v[0:3]
	v_mfma_f32_16x16x32_bf16 v[28:31], v[222:225], v[190:193], v[28:31]
	v_mfma_f32_16x16x32_bf16 v[24:27], v[230:233], v[190:193], v[24:27]
	v_mfma_f32_16x16x32_bf16 v[20:23], v[222:225], v[198:201], v[20:23]
	v_mfma_f32_16x16x32_bf16 v[16:19], v[230:233], v[198:201], v[16:19]
	v_mfma_f32_16x16x32_bf16 v[12:15], v[222:225], v[206:209], v[12:15]
	v_mfma_f32_16x16x32_bf16 v[8:11], v[230:233], v[206:209], v[8:11]
	v_mfma_f32_16x16x32_bf16 v[4:7], v[222:225], v[214:217], v[4:7]
	v_mfma_f32_16x16x32_bf16 v[0:3], v[230:233], v[214:217], v[0:3]
	s_setprio 0
	s_barrier
	ds_read_b128 v[144:147], v162
	ds_read_b128 v[174:177], v163
	ds_read_b128 v[178:181], v166
	ds_read_b128 v[182:185], v167
	s_mov_b32 m0, s27
	ds_read_b128 v[186:189], v150 offset:32768
	ds_read_b128 v[190:193], v150 offset:33792
	ds_read_b128 v[194:197], v150 offset:34816
	ds_read_b128 v[198:201], v150 offset:35840
	ds_read_b128 v[202:205], v150 offset:36864
	ds_read_b128 v[206:209], v150 offset:37888
	ds_read_b128 v[210:213], v150 offset:38912
	ds_read_b128 v[214:217], v150 offset:39936
	global_load_lds_dwordx4 v149, s[16:17]
	s_mov_b32 m0, s28
	s_nop 0
	global_load_lds_dwordx4 v173, s[16:17]
	s_waitcnt lgkmcnt(8)
	s_barrier
	s_waitcnt lgkmcnt(7)
	s_setprio 1
	v_mfma_f32_16x16x32_bf16 v[124:127], v[144:147], v[186:189], v[124:127]
	v_mfma_f32_16x16x32_bf16 v[120:123], v[178:181], v[186:189], v[120:123]
	s_waitcnt lgkmcnt(5)
	v_mfma_f32_16x16x32_bf16 v[116:119], v[144:147], v[194:197], v[116:119]
	v_mfma_f32_16x16x32_bf16 v[112:115], v[178:181], v[194:197], v[112:115]
	s_waitcnt lgkmcnt(3)
	v_mfma_f32_16x16x32_bf16 v[108:111], v[144:147], v[202:205], v[108:111]
	v_mfma_f32_16x16x32_bf16 v[104:107], v[178:181], v[202:205], v[104:107]
	s_waitcnt lgkmcnt(1)
	v_mfma_f32_16x16x32_bf16 v[100:103], v[144:147], v[210:213], v[100:103]
	v_mfma_f32_16x16x32_bf16 v[96:99], v[178:181], v[210:213], v[96:99]
	v_mfma_f32_16x16x32_bf16 v[124:127], v[174:177], v[190:193], v[124:127]
	v_mfma_f32_16x16x32_bf16 v[120:123], v[182:185], v[190:193], v[120:123]
	v_mfma_f32_16x16x32_bf16 v[116:119], v[174:177], v[198:201], v[116:119]
	v_mfma_f32_16x16x32_bf16 v[112:115], v[182:185], v[198:201], v[112:115]
	v_mfma_f32_16x16x32_bf16 v[108:111], v[174:177], v[206:209], v[108:111]
	v_mfma_f32_16x16x32_bf16 v[104:107], v[182:185], v[206:209], v[104:107]
	s_waitcnt lgkmcnt(0)
	v_mfma_f32_16x16x32_bf16 v[100:103], v[174:177], v[214:217], v[100:103]
	v_mfma_f32_16x16x32_bf16 v[96:99], v[182:185], v[214:217], v[96:99]
	s_setprio 0
	s_barrier
	s_mov_b32 m0, s29
	v_add_u32_e32 v143, 0x180, v143
	ds_read_b128 v[218:221], v168
	ds_read_b128 v[222:225], v169
	ds_read_b128 v[226:229], v170
	ds_read_b128 v[230:233], v171
	global_load_lds_dwordx4 v143, s[6:7]
	v_add_u32_e32 v148, 0x180, v148
	s_mov_b32 m0, s30
	s_nop 0
	global_load_lds_dwordx4 v148, s[6:7]
	s_barrier
	s_waitcnt lgkmcnt(3)
	s_setprio 1
	v_mfma_f32_16x16x32_bf16 v[92:95], v[218:221], v[186:189], v[92:95]
	s_waitcnt lgkmcnt(1)
	v_mfma_f32_16x16x32_bf16 v[88:91], v[226:229], v[186:189], v[88:91]
	v_mfma_f32_16x16x32_bf16 v[84:87], v[218:221], v[194:197], v[84:87]
	v_mfma_f32_16x16x32_bf16 v[80:83], v[226:229], v[194:197], v[80:83]
	v_mfma_f32_16x16x32_bf16 v[76:79], v[218:221], v[202:205], v[76:79]
	v_mfma_f32_16x16x32_bf16 v[72:75], v[226:229], v[202:205], v[72:75]
	v_mfma_f32_16x16x32_bf16 v[68:71], v[218:221], v[210:213], v[68:71]
	v_mfma_f32_16x16x32_bf16 v[64:67], v[226:229], v[210:213], v[64:67]
	v_mfma_f32_16x16x32_bf16 v[92:95], v[222:225], v[190:193], v[92:95]
	s_waitcnt lgkmcnt(0)
	v_mfma_f32_16x16x32_bf16 v[88:91], v[230:233], v[190:193], v[88:91]
	v_mfma_f32_16x16x32_bf16 v[84:87], v[222:225], v[198:201], v[84:87]
	v_mfma_f32_16x16x32_bf16 v[80:83], v[230:233], v[198:201], v[80:83]
	v_mfma_f32_16x16x32_bf16 v[76:79], v[222:225], v[206:209], v[76:79]
	v_mfma_f32_16x16x32_bf16 v[72:75], v[230:233], v[206:209], v[72:75]
	v_mfma_f32_16x16x32_bf16 v[68:71], v[222:225], v[214:217], v[68:71]
	v_mfma_f32_16x16x32_bf16 v[64:67], v[230:233], v[214:217], v[64:67]
	s_setprio 0
	s_mov_b32 m0, s31
	s_barrier
	ds_read_b128 v[186:189], v150 offset:49152
	ds_read_b128 v[190:193], v150 offset:50176
	ds_read_b128 v[194:197], v150 offset:51200
	ds_read_b128 v[198:201], v150 offset:52224
	ds_read_b128 v[202:205], v150 offset:53248
	ds_read_b128 v[206:209], v150 offset:54272
	ds_read_b128 v[210:213], v150 offset:55296
	ds_read_b128 v[214:217], v150 offset:56320
	global_load_lds_dwordx4 v143, s[14:15]
	s_mov_b32 m0, s34
	s_nop 0
	global_load_lds_dwordx4 v148, s[14:15]
	s_barrier
; #define SBAR() __builtin_amdgcn_sched_barrier(0)
; #define LDA8(dst, b, h) _Pragma("unroll") for (int m = 0; m < 4; ++m) _Pragma("unroll") for (int k = 0; k < 2; ++k) \
;     dst[m][k] = *reinterpret_cast<const bf16x8*>((const char*)SA8(b, h) + la + m * 2048 + k * 1024)
; #define LDB8(dst, b, h) _Pragma("unroll") for (int n = 0; n < 2; ++n) _Pragma("unroll") for (int k = 0; k < 2; ++k) \
;     dst[n][k] = *reinterpret_cast<const bf16x8*>((const char*)SB8(b, h) + lb + n * 2048 + k * 1024)
; #define MMA8(ai, bj, At_, Bx_) do { __builtin_amdgcn_s_setprio(1); \
;     _Pragma("unroll") for (int m = 0; m < 4; ++m) _Pragma("unroll") for (int n = 0; n < 2; ++n) _Pragma("unroll") for (int k = 0; k < 2; ++k) \
;       acc[ai][bj][m][n] = __builtin_amdgcn_mfma_f32_16x16x32_bf16(Bx_[n][k], At_[m][k], acc[ai][bj][m][n], 0, 0, 0); \
;     __builtin_amdgcn_s_setprio(0); } while (0)
; #define WAITV8(n) asm volatile("s_waitcnt vmcnt(" #n ")" ::: "memory")
; #define WAITL8(n) asm volatile("s_waitcnt lgkmcnt(" #n ")" ::: "memory")
; #define BAR8 __builtin_amdgcn_s_barrier()
; template <class Epi>
; DEV void gemm8_phase(const u16* __restrict__ A, int lda, const u16* __restrict__ Bt, int K, int nM, int nN, char* shmc, const Epi& epi) {
;     ...
;       BAR8; WAITL8(0); MMA8(1, 0, At, B0); BAR8; SBAR();
;       STAGE8(SB8(1, 1), Bt, K, bcol + HALF, kt + 3);
;       WAITV8(6); BAR8; MMA8(1, 1, At, B1); BAR8;
;     }
;     { LDB8(B0, 0, 0); LDA8(At, 0, 0); STAGE8(SA8(1, 1), A, lda, brow + HALF, nt - 1);
;       BAR8; WAITL8(0); MMA8(0, 0, At, B0); BAR8;
;       LDB8(B1, 0, 1); BAR8; WAITL8(0); MMA8(0, 1, At, B1); BAR8;
	s_waitcnt lgkmcnt(7)
	s_setprio 1
	v_mfma_f32_16x16x32_bf16 v[60:63], v[144:147], v[186:189], v[60:63]
	v_mfma_f32_16x16x32_bf16 v[56:59], v[178:181], v[186:189], v[56:59]
	s_waitcnt lgkmcnt(5)
	v_mfma_f32_16x16x32_bf16 v[52:55], v[144:147], v[194:197], v[52:55]
	v_mfma_f32_16x16x32_bf16 v[48:51], v[178:181], v[194:197], v[48:51]
	s_waitcnt lgkmcnt(3)
	v_mfma_f32_16x16x32_bf16 v[44:47], v[144:147], v[202:205], v[44:47]
	v_mfma_f32_16x16x32_bf16 v[40:43], v[178:181], v[202:205], v[40:43]
	s_waitcnt lgkmcnt(1)
	v_mfma_f32_16x16x32_bf16 v[36:39], v[144:147], v[210:213], v[36:39]
	v_mfma_f32_16x16x32_bf16 v[32:35], v[178:181], v[210:213], v[32:35]
	v_mfma_f32_16x16x32_bf16 v[60:63], v[174:177], v[190:193], v[60:63]
	v_mfma_f32_16x16x32_bf16 v[56:59], v[182:185], v[190:193], v[56:59]
	v_mfma_f32_16x16x32_bf16 v[52:55], v[174:177], v[198:201], v[52:55]
	v_mfma_f32_16x16x32_bf16 v[48:51], v[182:185], v[198:201], v[48:51]
	v_mfma_f32_16x16x32_bf16 v[44:47], v[174:177], v[206:209], v[44:47]
	v_mfma_f32_16x16x32_bf16 v[40:43], v[182:185], v[206:209], v[40:43]
	s_waitcnt lgkmcnt(0)
	v_mfma_f32_16x16x32_bf16 v[36:39], v[174:177], v[214:217], v[36:39]
	v_mfma_f32_16x16x32_bf16 v[32:35], v[182:185], v[214:217], v[32:35]
	s_setprio 0
	s_barrier
	s_mov_b32 m0, s35
	s_nop 0
	global_load_lds_dwordx4 v143, s[18:19]
	s_mov_b32 m0, s36
	s_nop 0
	global_load_lds_dwordx4 v148, s[18:19]
	s_waitcnt vmcnt(6)
	s_barrier
	s_setprio 1
	v_mfma_f32_16x16x32_bf16 v[28:31], v[218:221], v[186:189], v[28:31]
	v_mfma_f32_16x16x32_bf16 v[24:27], v[226:229], v[186:189], v[24:27]
	v_mfma_f32_16x16x32_bf16 v[20:23], v[218:221], v[194:197], v[20:23]
	v_mfma_f32_16x16x32_bf16 v[16:19], v[226:229], v[194:197], v[16:19]
	v_mfma_f32_16x16x32_bf16 v[12:15], v[218:221], v[202:205], v[12:15]
	v_mfma_f32_16x16x32_bf16 v[8:11], v[226:229], v[202:205], v[8:11]
	v_mfma_f32_16x16x32_bf16 v[4:7], v[218:221], v[210:213], v[4:7]
	v_mfma_f32_16x16x32_bf16 v[0:3], v[226:229], v[210:213], v[0:3]
	v_mfma_f32_16x16x32_bf16 v[28:31], v[222:225], v[190:193], v[28:31]
	v_mfma_f32_16x16x32_bf16 v[24:27], v[230:233], v[190:193], v[24:27]
	v_mfma_f32_16x16x32_bf16 v[20:23], v[222:225], v[198:201], v[20:23]
	v_mfma_f32_16x16x32_bf16 v[16:19], v[230:233], v[198:201], v[16:19]
	v_mfma_f32_16x16x32_bf16 v[12:15], v[222:225], v[206:209], v[12:15]
	v_mfma_f32_16x16x32_bf16 v[8:11], v[230:233], v[206:209], v[8:11]
	v_mfma_f32_16x16x32_bf16 v[4:7], v[222:225], v[214:217], v[4:7]
	v_mfma_f32_16x16x32_bf16 v[0:3], v[230:233], v[214:217], v[0:3]
	s_setprio 0
	s_add_i32 s54, s54, 2
	v_add_u32_e32 v142, 0x100, v142
	s_cmpk_gt_u32 s54, 0x53
	v_add_u32_e32 v132, 0x100, v132
	s_barrier
	s_cbranch_scc0 .LBB0_431
	s_mov_b32 m0, s37
	v_lshl_add_u64 v[214:215], s[16:17], 0, v[138:139]
	ds_read_b128 v[142:145], v154
	ds_read_b128 v[146:149], v155
	ds_read_b128 v[174:177], v156
	ds_read_b128 v[178:181], v157
	ds_read_b128 v[182:185], v150
	ds_read_b128 v[186:189], v150 offset:1024
	ds_read_b128 v[190:193], v150 offset:2048
	ds_read_b128 v[194:197], v150 offset:3072
	ds_read_b128 v[198:201], v150 offset:4096
	ds_read_b128 v[202:205], v150 offset:5120
	ds_read_b128 v[206:209], v150 offset:6144
	ds_read_b128 v[210:213], v150 offset:7168
	global_load_lds_dwordx4 v[214:215], off
	v_lshl_add_u64 v[214:215], s[16:17], 0, v[140:141]
	s_mov_b32 m0, s38
	s_nop 0
	global_load_lds_dwordx4 v[214:215], off
	s_barrier
	s_waitcnt lgkmcnt(0)
	s_setprio 1
	s_waitcnt lgkmcnt(0)
	v_mfma_f32_16x16x32_bf16 v[124:127], v[142:145], v[182:185], v[124:127]
	v_mfma_f32_16x16x32_bf16 v[120:123], v[174:177], v[182:185], v[120:123]
	v_mfma_f32_16x16x32_bf16 v[116:119], v[142:145], v[190:193], v[116:119]
	v_mfma_f32_16x16x32_bf16 v[112:115], v[174:177], v[190:193], v[112:115]
	v_mfma_f32_16x16x32_bf16 v[108:111], v[142:145], v[198:201], v[108:111]
	v_mfma_f32_16x16x32_bf16 v[104:107], v[174:177], v[198:201], v[104:107]
	v_mfma_f32_16x16x32_bf16 v[100:103], v[142:145], v[206:209], v[100:103]
	v_mfma_f32_16x16x32_bf16 v[96:99], v[174:177], v[206:209], v[96:99]
	v_mfma_f32_16x16x32_bf16 v[124:127], v[146:149], v[186:189], v[124:127]
	v_mfma_f32_16x16x32_bf16 v[120:123], v[178:181], v[186:189], v[120:123]
	v_mfma_f32_16x16x32_bf16 v[116:119], v[146:149], v[194:197], v[116:119]
	v_mfma_f32_16x16x32_bf16 v[112:115], v[178:181], v[194:197], v[112:115]
	v_mfma_f32_16x16x32_bf16 v[108:111], v[146:149], v[202:205], v[108:111]
	v_mfma_f32_16x16x32_bf16 v[104:107], v[178:181], v[202:205], v[104:107]
	v_mfma_f32_16x16x32_bf16 v[100:103], v[146:149], v[210:213], v[100:103]
	v_mfma_f32_16x16x32_bf16 v[96:99], v[178:181], v[210:213], v[96:99]
	s_setprio 0
	s_barrier
	ds_read_b128 v[214:217], v158
	ds_read_b128 v[218:221], v159
	ds_read_b128 v[222:225], v160
	ds_read_b128 v[226:229], v161
	s_barrier
	s_waitcnt lgkmcnt(0)
	s_setprio 1
	s_waitcnt lgkmcnt(0)
	v_mfma_f32_16x16x32_bf16 v[92:95], v[214:217], v[182:185], v[92:95]
	v_mfma_f32_16x16x32_bf16 v[88:91], v[222:225], v[182:185], v[88:91]
	v_mfma_f32_16x16x32_bf16 v[84:87], v[214:217], v[190:193], v[84:87]
	v_mfma_f32_16x16x32_bf16 v[80:83], v[222:225], v[190:193], v[80:83]
	v_mfma_f32_16x16x32_bf16 v[76:79], v[214:217], v[198:201], v[76:79]
	v_mfma_f32_16x16x32_bf16 v[72:75], v[222:225], v[198:201], v[72:75]
	v_mfma_f32_16x16x32_bf16 v[68:71], v[214:217], v[206:209], v[68:71]
	v_mfma_f32_16x16x32_bf16 v[64:67], v[222:225], v[206:209], v[64:67]
	v_mfma_f32_16x16x32_bf16 v[92:95], v[218:221], v[186:189], v[92:95]
	v_mfma_f32_16x16x32_bf16 v[88:91], v[226:229], v[186:189], v[88:91]
	v_mfma_f32_16x16x32_bf16 v[84:87], v[218:221], v[194:197], v[84:87]
	v_mfma_f32_16x16x32_bf16 v[80:83], v[226:229], v[194:197], v[80:83]
	v_mfma_f32_16x16x32_bf16 v[76:79], v[218:221], v[202:205], v[76:79]
	v_mfma_f32_16x16x32_bf16 v[72:75], v[226:229], v[202:205], v[72:75]
	v_mfma_f32_16x16x32_bf16 v[68:71], v[218:221], v[210:213], v[68:71]
	v_mfma_f32_16x16x32_bf16 v[64:67], v[226:229], v[210:213], v[64:67]
	s_setprio 0
	s_barrier
; #define LDA8(dst, b, h) _Pragma("unroll") for (int m = 0; m < 4; ++m) _Pragma("unroll") for (int k = 0; k < 2; ++k) \
;     dst[m][k] = *reinterpret_cast<const bf16x8*>((const char*)SA8(b, h) + la + m * 2048 + k * 1024)
; #define LDB8(dst, b, h) _Pragma("unroll") for (int n = 0; n < 2; ++n) _Pragma("unroll") for (int k = 0; k < 2; ++k) \
;     dst[n][k] = *reinterpret_cast<const bf16x8*>((const char*)SB8(b, h) + lb + n * 2048 + k * 1024)
; #define MMA8(ai, bj, At_, Bx_) do { __builtin_amdgcn_s_setprio(1); \
;     _Pragma("unroll") for (int m = 0; m < 4; ++m) _Pragma("unroll") for (int n = 0; n < 2; ++n) _Pragma("unroll") for (int k = 0; k < 2; ++k) \
;       acc[ai][bj][m][n] = __builtin_amdgcn_mfma_f32_16x16x32_bf16(Bx_[n][k], At_[m][k], acc[ai][bj][m][n], 0, 0, 0); \
;     __builtin_amdgcn_s_setprio(0); } while (0)
; #define WAITV8(n) asm volatile("s_waitcnt vmcnt(" #n ")" ::: "memory")
; #define WAITL8(n) asm volatile("s_waitcnt lgkmcnt(" #n ")" ::: "memory")
; #define BAR8 __builtin_amdgcn_s_barrier()
; template <class Epi>
; DEV void gemm8_phase(const u16* __restrict__ A, int lda, const u16* __restrict__ Bt, int K, int nM, int nN, char* shmc, const Epi& epi) {
;     ...
;       LDA8(At, 0, 1); WAITV8(4); BAR8; WAITL8(0); MMA8(1, 0, At, B0); MMA8(1, 1, At, B1); BAR8; }
;     { LDB8(B0, 1, 0); LDA8(At, 1, 0); WAITV8(2); BAR8; WAITL8(0); MMA8(0, 0, At, B0); BAR8;
	ds_read_b128 v[182:185], v150 offset:16384
	ds_read_b128 v[186:189], v150 offset:17408
	ds_read_b128 v[190:193], v150 offset:18432
	ds_read_b128 v[194:197], v150 offset:19456
	ds_read_b128 v[198:201], v150 offset:20480
	ds_read_b128 v[202:205], v150 offset:21504
	ds_read_b128 v[206:209], v150 offset:22528
	ds_read_b128 v[210:213], v150 offset:23552
	s_waitcnt vmcnt(4)
	s_barrier
	s_waitcnt lgkmcnt(0)
	s_setprio 1
	s_waitcnt lgkmcnt(0)
	v_mfma_f32_16x16x32_bf16 v[60:63], v[142:145], v[182:185], v[60:63]
	v_mfma_f32_16x16x32_bf16 v[56:59], v[174:177], v[182:185], v[56:59]
	v_mfma_f32_16x16x32_bf16 v[52:55], v[142:145], v[190:193], v[52:55]
	v_mfma_f32_16x16x32_bf16 v[48:51], v[174:177], v[190:193], v[48:51]
	v_mfma_f32_16x16x32_bf16 v[44:47], v[142:145], v[198:201], v[44:47]
	v_mfma_f32_16x16x32_bf16 v[40:43], v[174:177], v[198:201], v[40:43]
	v_mfma_f32_16x16x32_bf16 v[36:39], v[142:145], v[206:209], v[36:39]
	v_mfma_f32_16x16x32_bf16 v[32:35], v[174:177], v[206:209], v[32:35]
	v_mfma_f32_16x16x32_bf16 v[60:63], v[146:149], v[186:189], v[60:63]
	v_mfma_f32_16x16x32_bf16 v[56:59], v[178:181], v[186:189], v[56:59]
	v_mfma_f32_16x16x32_bf16 v[52:55], v[146:149], v[194:197], v[52:55]
	v_mfma_f32_16x16x32_bf16 v[48:51], v[178:181], v[194:197], v[48:51]
	v_mfma_f32_16x16x32_bf16 v[44:47], v[146:149], v[202:205], v[44:47]
	v_mfma_f32_16x16x32_bf16 v[40:43], v[178:181], v[202:205], v[40:43]
	v_mfma_f32_16x16x32_bf16 v[36:39], v[146:149], v[210:213], v[36:39]
	v_mfma_f32_16x16x32_bf16 v[32:35], v[178:181], v[210:213], v[32:35]
	s_setprio 0
	s_setprio 1
	v_mfma_f32_16x16x32_bf16 v[28:31], v[214:217], v[182:185], v[28:31]
	v_mfma_f32_16x16x32_bf16 v[24:27], v[222:225], v[182:185], v[24:27]
	v_mfma_f32_16x16x32_bf16 v[20:23], v[214:217], v[190:193], v[20:23]
	v_mfma_f32_16x16x32_bf16 v[16:19], v[222:225], v[190:193], v[16:19]
	v_mfma_f32_16x16x32_bf16 v[12:15], v[214:217], v[198:201], v[12:15]
	v_mfma_f32_16x16x32_bf16 v[8:11], v[222:225], v[198:201], v[8:11]
	v_mfma_f32_16x16x32_bf16 v[4:7], v[214:217], v[206:209], v[4:7]
	v_mfma_f32_16x16x32_bf16 v[0:3], v[222:225], v[206:209], v[0:3]
	v_mfma_f32_16x16x32_bf16 v[28:31], v[218:221], v[186:189], v[28:31]
	v_mfma_f32_16x16x32_bf16 v[24:27], v[226:229], v[186:189], v[24:27]
	v_mfma_f32_16x16x32_bf16 v[20:23], v[218:221], v[194:197], v[20:23]
	v_mfma_f32_16x16x32_bf16 v[16:19], v[226:229], v[194:197], v[16:19]
	v_mfma_f32_16x16x32_bf16 v[12:15], v[218:221], v[202:205], v[12:15]
	v_mfma_f32_16x16x32_bf16 v[8:11], v[226:229], v[202:205], v[8:11]
	v_mfma_f32_16x16x32_bf16 v[4:7], v[218:221], v[210:213], v[4:7]
	v_mfma_f32_16x16x32_bf16 v[0:3], v[226:229], v[210:213], v[0:3]
	s_setprio 0
	s_barrier
	ds_read_b128 v[142:145], v162
	ds_read_b128 v[146:149], v163
	ds_read_b128 v[174:177], v166
	ds_read_b128 v[178:181], v167
	ds_read_b128 v[182:185], v150 offset:32768
	ds_read_b128 v[186:189], v150 offset:33792
	ds_read_b128 v[190:193], v150 offset:34816
	ds_read_b128 v[194:197], v150 offset:35840
	ds_read_b128 v[198:201], v150 offset:36864
	ds_read_b128 v[202:205], v150 offset:37888
	ds_read_b128 v[206:209], v150 offset:38912
	ds_read_b128 v[210:213], v150 offset:39936
	s_waitcnt vmcnt(2)
	s_barrier
	s_waitcnt lgkmcnt(0)
	s_setprio 1
	s_waitcnt lgkmcnt(0)
	v_mfma_f32_16x16x32_bf16 v[124:127], v[142:145], v[182:185], v[124:127]
	v_mfma_f32_16x16x32_bf16 v[120:123], v[174:177], v[182:185], v[120:123]
	v_mfma_f32_16x16x32_bf16 v[116:119], v[142:145], v[190:193], v[116:119]
	v_mfma_f32_16x16x32_bf16 v[112:115], v[174:177], v[190:193], v[112:115]
	v_mfma_f32_16x16x32_bf16 v[108:111], v[142:145], v[198:201], v[108:111]
	v_mfma_f32_16x16x32_bf16 v[104:107], v[174:177], v[198:201], v[104:107]
	v_mfma_f32_16x16x32_bf16 v[100:103], v[142:145], v[206:209], v[100:103]
	v_mfma_f32_16x16x32_bf16 v[96:99], v[174:177], v[206:209], v[96:99]
	v_mfma_f32_16x16x32_bf16 v[124:127], v[146:149], v[186:189], v[124:127]
	v_mfma_f32_16x16x32_bf16 v[120:123], v[178:181], v[186:189], v[120:123]
	v_mfma_f32_16x16x32_bf16 v[116:119], v[146:149], v[194:197], v[116:119]
	v_mfma_f32_16x16x32_bf16 v[112:115], v[178:181], v[194:197], v[112:115]
	v_mfma_f32_16x16x32_bf16 v[108:111], v[146:149], v[202:205], v[108:111]
	v_mfma_f32_16x16x32_bf16 v[104:107], v[178:181], v[202:205], v[104:107]
	v_mfma_f32_16x16x32_bf16 v[100:103], v[146:149], v[210:213], v[100:103]
	v_mfma_f32_16x16x32_bf16 v[96:99], v[178:181], v[210:213], v[96:99]
	s_setprio 0
	s_barrier
; #define LDA8(dst, b, h) _Pragma("unroll") for (int m = 0; m < 4; ++m) _Pragma("unroll") for (int k = 0; k < 2; ++k) \
;     dst[m][k] = *reinterpret_cast<const bf16x8*>((const char*)SA8(b, h) + la + m * 2048 + k * 1024)
; #define LDB8(dst, b, h) _Pragma("unroll") for (int n = 0; n < 2; ++n) _Pragma("unroll") for (int k = 0; k < 2; ++k) \
;     dst[n][k] = *reinterpret_cast<const bf16x8*>((const char*)SB8(b, h) + lb + n * 2048 + k * 1024)
; #define MMA8(ai, bj, At_, Bx_) do { __builtin_amdgcn_s_setprio(1); \
;     _Pragma("unroll") for (int m = 0; m < 4; ++m) _Pragma("unroll") for (int n = 0; n < 2; ++n) _Pragma("unroll") for (int k = 0; k < 2; ++k) \
;       acc[ai][bj][m][n] = __builtin_amdgcn_mfma_f32_16x16x32_bf16(Bx_[n][k], At_[m][k], acc[ai][bj][m][n], 0, 0, 0); \
;     __builtin_amdgcn_s_setprio(0); } while (0)
; #define WAITV8(n) asm volatile("s_waitcnt vmcnt(" #n ")" ::: "memory")
; #define WAITL8(n) asm volatile("s_waitcnt lgkmcnt(" #n ")" ::: "memory")
; #define BAR8 __builtin_amdgcn_s_barrier()
; template <class Epi>
; DEV void gemm8_phase(const u16* __restrict__ A, int lda, const u16* __restrict__ Bt, int K, int nM, int nN, char* shmc, const Epi& epi) {
;     ...
;       LDB8(B1, 1, 1); WAITV8(0); BAR8; WAITL8(0); MMA8(0, 1, At, B1); BAR8;
;       LDA8(At, 1, 1); BAR8; WAITL8(0); MMA8(1, 0, At, B0); MMA8(1, 1, At, B1); BAR8; }
;     if (wr == 0) BAR8;
	ds_read_b128 v[214:217], v168
	ds_read_b128 v[218:221], v169
	ds_read_b128 v[222:225], v170
	ds_read_b128 v[226:229], v171
	s_waitcnt vmcnt(0)
	s_barrier
	s_waitcnt lgkmcnt(0)
	s_setprio 1
	s_waitcnt lgkmcnt(0)
	v_mfma_f32_16x16x32_bf16 v[92:95], v[214:217], v[182:185], v[92:95]
	v_mfma_f32_16x16x32_bf16 v[88:91], v[222:225], v[182:185], v[88:91]
	v_mfma_f32_16x16x32_bf16 v[84:87], v[214:217], v[190:193], v[84:87]
	v_mfma_f32_16x16x32_bf16 v[80:83], v[222:225], v[190:193], v[80:83]
	v_mfma_f32_16x16x32_bf16 v[76:79], v[214:217], v[198:201], v[76:79]
	v_mfma_f32_16x16x32_bf16 v[72:75], v[222:225], v[198:201], v[72:75]
	v_mfma_f32_16x16x32_bf16 v[68:71], v[214:217], v[206:209], v[68:71]
	v_mfma_f32_16x16x32_bf16 v[64:67], v[222:225], v[206:209], v[64:67]
	v_mfma_f32_16x16x32_bf16 v[92:95], v[218:221], v[186:189], v[92:95]
	v_mfma_f32_16x16x32_bf16 v[88:91], v[226:229], v[186:189], v[88:91]
	v_mfma_f32_16x16x32_bf16 v[84:87], v[218:221], v[194:197], v[84:87]
	v_mfma_f32_16x16x32_bf16 v[80:83], v[226:229], v[194:197], v[80:83]
	v_mfma_f32_16x16x32_bf16 v[76:79], v[218:221], v[202:205], v[76:79]
	v_mfma_f32_16x16x32_bf16 v[72:75], v[226:229], v[202:205], v[72:75]
	v_mfma_f32_16x16x32_bf16 v[68:71], v[218:221], v[210:213], v[68:71]
	v_mfma_f32_16x16x32_bf16 v[64:67], v[226:229], v[210:213], v[64:67]
	s_setprio 0
	s_barrier
	ds_read_b128 v[182:185], v150 offset:49152
	ds_read_b128 v[186:189], v150 offset:50176
	ds_read_b128 v[190:193], v150 offset:51200
	ds_read_b128 v[194:197], v150 offset:52224
	ds_read_b128 v[198:201], v150 offset:53248
	ds_read_b128 v[202:205], v150 offset:54272
	ds_read_b128 v[206:209], v150 offset:55296
	ds_read_b128 v[210:213], v150 offset:56320
	s_barrier
	s_waitcnt lgkmcnt(0)
	s_setprio 1
	s_waitcnt lgkmcnt(0)
	v_mfma_f32_16x16x32_bf16 v[60:63], v[142:145], v[182:185], v[60:63]
	v_mfma_f32_16x16x32_bf16 v[56:59], v[174:177], v[182:185], v[56:59]
	v_mfma_f32_16x16x32_bf16 v[52:55], v[142:145], v[190:193], v[52:55]
	v_mfma_f32_16x16x32_bf16 v[48:51], v[174:177], v[190:193], v[48:51]
	v_mfma_f32_16x16x32_bf16 v[44:47], v[142:145], v[198:201], v[44:47]
	v_mfma_f32_16x16x32_bf16 v[40:43], v[174:177], v[198:201], v[40:43]
	v_mfma_f32_16x16x32_bf16 v[36:39], v[142:145], v[206:209], v[36:39]
	v_mfma_f32_16x16x32_bf16 v[32:35], v[174:177], v[206:209], v[32:35]
	v_mfma_f32_16x16x32_bf16 v[60:63], v[146:149], v[186:189], v[60:63]
	v_mfma_f32_16x16x32_bf16 v[56:59], v[178:181], v[186:189], v[56:59]
	v_mfma_f32_16x16x32_bf16 v[52:55], v[146:149], v[194:197], v[52:55]
	v_mfma_f32_16x16x32_bf16 v[48:51], v[178:181], v[194:197], v[48:51]
	v_mfma_f32_16x16x32_bf16 v[44:47], v[146:149], v[202:205], v[44:47]
	v_mfma_f32_16x16x32_bf16 v[40:43], v[178:181], v[202:205], v[40:43]
	v_mfma_f32_16x16x32_bf16 v[36:39], v[146:149], v[210:213], v[36:39]
	v_mfma_f32_16x16x32_bf16 v[32:35], v[178:181], v[210:213], v[32:35]
	s_setprio 0
	s_setprio 1
	v_mfma_f32_16x16x32_bf16 v[28:31], v[214:217], v[182:185], v[28:31]
	v_mfma_f32_16x16x32_bf16 v[24:27], v[222:225], v[182:185], v[24:27]
	v_mfma_f32_16x16x32_bf16 v[20:23], v[214:217], v[190:193], v[20:23]
	v_mfma_f32_16x16x32_bf16 v[16:19], v[222:225], v[190:193], v[16:19]
	v_mfma_f32_16x16x32_bf16 v[12:15], v[214:217], v[198:201], v[12:15]
	v_mfma_f32_16x16x32_bf16 v[8:11], v[222:225], v[198:201], v[8:11]
	v_mfma_f32_16x16x32_bf16 v[4:7], v[214:217], v[206:209], v[4:7]
	v_mfma_f32_16x16x32_bf16 v[0:3], v[222:225], v[206:209], v[0:3]
	v_mfma_f32_16x16x32_bf16 v[28:31], v[218:221], v[186:189], v[28:31]
	v_mfma_f32_16x16x32_bf16 v[24:27], v[226:229], v[186:189], v[24:27]
	v_mfma_f32_16x16x32_bf16 v[20:23], v[218:221], v[194:197], v[20:23]
	v_mfma_f32_16x16x32_bf16 v[16:19], v[226:229], v[194:197], v[16:19]
	v_mfma_f32_16x16x32_bf16 v[12:15], v[218:221], v[202:205], v[12:15]
	v_mfma_f32_16x16x32_bf16 v[8:11], v[226:229], v[202:205], v[8:11]
	v_mfma_f32_16x16x32_bf16 v[4:7], v[218:221], v[210:213], v[4:7]
	v_mfma_f32_16x16x32_bf16 v[0:3], v[226:229], v[210:213], v[0:3]
	s_setprio 0
	s_and_b64 vcc, exec, s[8:9]
	s_barrier
	s_cbranch_vccz .LBB0_434
	s_barrier

; #define SBAR() __builtin_amdgcn_sched_barrier(0)
; #define LDA8(dst, b, h) _Pragma("unroll") for (int m = 0; m < 4; ++m) _Pragma("unroll") for (int k = 0; k < 2; ++k) \
;     dst[m][k] = *reinterpret_cast<const bf16x8*>((const char*)SA8(b, h) + la + m * 2048 + k * 1024)
; #define LDB8(dst, b, h) _Pragma("unroll") for (int n = 0; n < 2; ++n) _Pragma("unroll") for (int k = 0; k < 2; ++k) \
;     dst[n][k] = *reinterpret_cast<const bf16x8*>((const char*)SB8(b, h) + lb + n * 2048 + k * 1024)
; #define MMA8(ai, bj, At_, Bx_) do { __builtin_amdgcn_s_setprio(1); \
;     _Pragma("unroll") for (int m = 0; m < 4; ++m) _Pragma("unroll") for (int n = 0; n < 2; ++n) _Pragma("unroll") for (int k = 0; k < 2; ++k) \
;       acc[ai][bj][m][n] = __builtin_amdgcn_mfma_f32_16x16x32_bf16(Bx_[n][k], At_[m][k], acc[ai][bj][m][n], 0, 0, 0); \
;     __builtin_amdgcn_s_setprio(0); } while (0)
; #define WAITV8(n) asm volatile("s_waitcnt vmcnt(" #n ")" ::: "memory")
; #define WAITL8(n) asm volatile("s_waitcnt lgkmcnt(" #n ")" ::: "memory")
; #define BAR8 __builtin_amdgcn_s_barrier()
; template <class Epi>
; DEV void gemm8_phase(const u16* __restrict__ A, int lda, const u16* __restrict__ Bt, int K, int nM, int nN, char* shmc, const Epi& epi) {
;     ...
;       LDB8(B0, 0, 0); SBAR(); LDA8(At, 0, 0); STAGE8(SA8(1, 1), A, lda, brow + HALF, kt + 1);
;       WAITL8(8); BAR8; WAITL8(0); MMA8(0, 0, At, B0); BAR8; SBAR();
;       LDB8(B1, 0, 1); STAGE8(SB8(0, 0), Bt, K, bcol, kt + 2);
;       BAR8; WAITL8(0); MMA8(0, 1, At, B1); BAR8;
;       LDA8(At, 0, 1); STAGE8(SA8(0, 0), A, lda, brow, kt + 2);
;       BAR8; WAITL8(0); MMA8(1, 0, At, B0); BAR8; SBAR();
;       STAGE8(SB8(0, 1), Bt, K, bcol + HALF, kt + 2);
;       WAITV8(6); BAR8; MMA8(1, 1, At, B1); BAR8;
.LBB0_1555:
	ds_read_b128 v[142:145], v153
	ds_read_b128 v[146:149], v154
	ds_read_b128 v[172:175], v155
	ds_read_b128 v[176:179], v156
	v_add_u32_e32 v132, s1, v152
	s_mov_b32 m0, s42
	v_add_u32_e32 v212, 0x80, v132
	v_add_u32_e32 v228, s1, v151
	ds_read_b128 v[180:183], v150
	ds_read_b128 v[184:187], v150 offset:1024
	ds_read_b128 v[188:191], v150 offset:2048
	ds_read_b128 v[192:195], v150 offset:3072
	ds_read_b128 v[196:199], v150 offset:4096
	ds_read_b128 v[200:203], v150 offset:5120
	ds_read_b128 v[204:207], v150 offset:6144
	ds_read_b128 v[208:211], v150 offset:7168
	global_load_lds_dwordx4 v212, s[18:19]
	v_add_u32_e32 v212, 0x80, v228
	s_mov_b32 m0, s43
	s_nop 0
	global_load_lds_dwordx4 v212, s[18:19]
	s_waitcnt lgkmcnt(8)
	s_barrier
	s_waitcnt lgkmcnt(7)
	s_setprio 1
	v_mfma_f32_16x16x32_bf16 v[124:127], v[142:145], v[180:183], v[124:127]
	v_mfma_f32_16x16x32_bf16 v[120:123], v[172:175], v[180:183], v[120:123]
	s_waitcnt lgkmcnt(5)
	v_mfma_f32_16x16x32_bf16 v[116:119], v[142:145], v[188:191], v[116:119]
	v_mfma_f32_16x16x32_bf16 v[112:115], v[172:175], v[188:191], v[112:115]
	s_waitcnt lgkmcnt(3)
	v_mfma_f32_16x16x32_bf16 v[108:111], v[142:145], v[196:199], v[108:111]
	v_mfma_f32_16x16x32_bf16 v[104:107], v[172:175], v[196:199], v[104:107]
	s_waitcnt lgkmcnt(1)
	v_mfma_f32_16x16x32_bf16 v[100:103], v[142:145], v[204:207], v[100:103]
	v_mfma_f32_16x16x32_bf16 v[96:99], v[172:175], v[204:207], v[96:99]
	v_mfma_f32_16x16x32_bf16 v[124:127], v[146:149], v[184:187], v[124:127]
	v_mfma_f32_16x16x32_bf16 v[120:123], v[176:179], v[184:187], v[120:123]
	v_mfma_f32_16x16x32_bf16 v[116:119], v[146:149], v[192:195], v[116:119]
	v_mfma_f32_16x16x32_bf16 v[112:115], v[176:179], v[192:195], v[112:115]
	v_mfma_f32_16x16x32_bf16 v[108:111], v[146:149], v[200:203], v[108:111]
	v_mfma_f32_16x16x32_bf16 v[104:107], v[176:179], v[200:203], v[104:107]
	s_waitcnt lgkmcnt(0)
	v_mfma_f32_16x16x32_bf16 v[100:103], v[146:149], v[208:211], v[100:103]
	v_mfma_f32_16x16x32_bf16 v[96:99], v[176:179], v[208:211], v[96:99]
	s_setprio 0
	s_barrier
	s_mov_b32 m0, s23
	v_add_u32_e32 v229, 0x100, v132
	ds_read_b128 v[212:215], v157
	ds_read_b128 v[216:219], v158
	ds_read_b128 v[220:223], v159
	ds_read_b128 v[224:227], v160
	global_load_lds_dwordx4 v229, s[14:15]
	v_add_u32_e32 v230, 0x100, v228
	s_mov_b32 m0, s24
	s_nop 0
	global_load_lds_dwordx4 v230, s[14:15]
	s_barrier
	s_waitcnt lgkmcnt(3)
	s_setprio 1
	v_mfma_f32_16x16x32_bf16 v[92:95], v[212:215], v[180:183], v[92:95]
	s_waitcnt lgkmcnt(1)
	v_mfma_f32_16x16x32_bf16 v[88:91], v[220:223], v[180:183], v[88:91]
	v_mfma_f32_16x16x32_bf16 v[84:87], v[212:215], v[188:191], v[84:87]
	v_mfma_f32_16x16x32_bf16 v[80:83], v[220:223], v[188:191], v[80:83]
	v_mfma_f32_16x16x32_bf16 v[76:79], v[212:215], v[196:199], v[76:79]
	v_mfma_f32_16x16x32_bf16 v[72:75], v[220:223], v[196:199], v[72:75]
	v_mfma_f32_16x16x32_bf16 v[68:71], v[212:215], v[204:207], v[68:71]
	v_mfma_f32_16x16x32_bf16 v[64:67], v[220:223], v[204:207], v[64:67]
	v_mfma_f32_16x16x32_bf16 v[92:95], v[216:219], v[184:187], v[92:95]
	s_waitcnt lgkmcnt(0)
	v_mfma_f32_16x16x32_bf16 v[88:91], v[224:227], v[184:187], v[88:91]
	v_mfma_f32_16x16x32_bf16 v[84:87], v[216:219], v[192:195], v[84:87]
	v_mfma_f32_16x16x32_bf16 v[80:83], v[224:227], v[192:195], v[80:83]
	v_mfma_f32_16x16x32_bf16 v[76:79], v[216:219], v[200:203], v[76:79]
	v_mfma_f32_16x16x32_bf16 v[72:75], v[224:227], v[200:203], v[72:75]
	v_mfma_f32_16x16x32_bf16 v[68:71], v[216:219], v[208:211], v[68:71]
	v_mfma_f32_16x16x32_bf16 v[64:67], v[224:227], v[208:211], v[64:67]
	s_setprio 0
	s_mov_b32 m0, s3
	s_barrier
	ds_read_b128 v[180:183], v150 offset:16384
	ds_read_b128 v[184:187], v150 offset:17408
	ds_read_b128 v[188:191], v150 offset:18432
	ds_read_b128 v[192:195], v150 offset:19456
	ds_read_b128 v[196:199], v150 offset:20480
	ds_read_b128 v[200:203], v150 offset:21504
	ds_read_b128 v[204:207], v150 offset:22528
	ds_read_b128 v[208:211], v150 offset:23552
	global_load_lds_dwordx4 v229, s[16:17]
	s_mov_b32 m0, s25
	s_nop 0
	global_load_lds_dwordx4 v230, s[16:17]
	s_barrier
	s_waitcnt lgkmcnt(7)
	s_setprio 1
	v_mfma_f32_16x16x32_bf16 v[60:63], v[142:145], v[180:183], v[60:63]
	v_mfma_f32_16x16x32_bf16 v[56:59], v[172:175], v[180:183], v[56:59]
	s_waitcnt lgkmcnt(5)
	v_mfma_f32_16x16x32_bf16 v[52:55], v[142:145], v[188:191], v[52:55]
	v_mfma_f32_16x16x32_bf16 v[48:51], v[172:175], v[188:191], v[48:51]
	s_waitcnt lgkmcnt(3)
	v_mfma_f32_16x16x32_bf16 v[44:47], v[142:145], v[196:199], v[44:47]
	v_mfma_f32_16x16x32_bf16 v[40:43], v[172:175], v[196:199], v[40:43]
	s_waitcnt lgkmcnt(1)
	v_mfma_f32_16x16x32_bf16 v[36:39], v[142:145], v[204:207], v[36:39]
	v_mfma_f32_16x16x32_bf16 v[32:35], v[172:175], v[204:207], v[32:35]
	v_mfma_f32_16x16x32_bf16 v[60:63], v[146:149], v[184:187], v[60:63]
	v_mfma_f32_16x16x32_bf16 v[56:59], v[176:179], v[184:187], v[56:59]
	v_mfma_f32_16x16x32_bf16 v[52:55], v[146:149], v[192:195], v[52:55]
	v_mfma_f32_16x16x32_bf16 v[48:51], v[176:179], v[192:195], v[48:51]
	v_mfma_f32_16x16x32_bf16 v[44:47], v[146:149], v[200:203], v[44:47]
	v_mfma_f32_16x16x32_bf16 v[40:43], v[176:179], v[200:203], v[40:43]
	s_waitcnt lgkmcnt(0)
	v_mfma_f32_16x16x32_bf16 v[36:39], v[146:149], v[208:211], v[36:39]
	v_mfma_f32_16x16x32_bf16 v[32:35], v[176:179], v[208:211], v[32:35]
	s_setprio 0
	s_barrier
	s_mov_b32 m0, s26
	s_nop 0
	global_load_lds_dwordx4 v229, s[20:21]
	s_mov_b32 m0, s27
	s_nop 0
	global_load_lds_dwordx4 v230, s[20:21]
	s_waitcnt vmcnt(6)
	s_barrier
; #define SBAR() __builtin_amdgcn_sched_barrier(0)
; #define LDA8(dst, b, h) _Pragma("unroll") for (int m = 0; m < 4; ++m) _Pragma("unroll") for (int k = 0; k < 2; ++k) \
;     dst[m][k] = *reinterpret_cast<const bf16x8*>((const char*)SA8(b, h) + la + m * 2048 + k * 1024)
; #define LDB8(dst, b, h) _Pragma("unroll") for (int n = 0; n < 2; ++n) _Pragma("unroll") for (int k = 0; k < 2; ++k) \
;     dst[n][k] = *reinterpret_cast<const bf16x8*>((const char*)SB8(b, h) + lb + n * 2048 + k * 1024)
; #define MMA8(ai, bj, At_, Bx_) do { __builtin_amdgcn_s_setprio(1); \
;     _Pragma("unroll") for (int m = 0; m < 4; ++m) _Pragma("unroll") for (int n = 0; n < 2; ++n) _Pragma("unroll") for (int k = 0; k < 2; ++k) \
;       acc[ai][bj][m][n] = __builtin_amdgcn_mfma_f32_16x16x32_bf16(Bx_[n][k], At_[m][k], acc[ai][bj][m][n], 0, 0, 0); \
;     __builtin_amdgcn_s_setprio(0); } while (0)
; #define WAITV8(n) asm volatile("s_waitcnt vmcnt(" #n ")" ::: "memory")
; #define WAITL8(n) asm volatile("s_waitcnt lgkmcnt(" #n ")" ::: "memory")
; #define BAR8 __builtin_amdgcn_s_barrier()
; template <class Epi>
; DEV void gemm8_phase(const u16* __restrict__ A, int lda, const u16* __restrict__ Bt, int K, int nM, int nN, char* shmc, const Epi& epi) {
;     ...
;       WAITV8(6); BAR8; MMA8(1, 1, At, B1); BAR8;
;       LDB8(B0, 1, 0); SBAR(); LDA8(At, 1, 0); STAGE8(SA8(0, 1), A, lda, brow + HALF, kt + 2);
;       WAITL8(8); BAR8; WAITL8(0); MMA8(0, 0, At, B0); BAR8; SBAR();
;       LDB8(B1, 1, 1); STAGE8(SB8(1, 0), Bt, K, bcol, kt + 3);
;       BAR8; WAITL8(0); MMA8(0, 1, At, B1); BAR8;
;       LDA8(At, 1, 1); STAGE8(SA8(1, 0), A, lda, brow, kt + 3);
	s_setprio 1
	v_mfma_f32_16x16x32_bf16 v[28:31], v[212:215], v[180:183], v[28:31]
	v_mfma_f32_16x16x32_bf16 v[24:27], v[220:223], v[180:183], v[24:27]
	v_mfma_f32_16x16x32_bf16 v[20:23], v[212:215], v[188:191], v[20:23]
	v_mfma_f32_16x16x32_bf16 v[16:19], v[220:223], v[188:191], v[16:19]
	v_mfma_f32_16x16x32_bf16 v[12:15], v[212:215], v[196:199], v[12:15]
	v_mfma_f32_16x16x32_bf16 v[8:11], v[220:223], v[196:199], v[8:11]
	v_mfma_f32_16x16x32_bf16 v[4:7], v[212:215], v[204:207], v[4:7]
	v_mfma_f32_16x16x32_bf16 v[0:3], v[220:223], v[204:207], v[0:3]
	v_mfma_f32_16x16x32_bf16 v[28:31], v[216:219], v[184:187], v[28:31]
	v_mfma_f32_16x16x32_bf16 v[24:27], v[224:227], v[184:187], v[24:27]
	v_mfma_f32_16x16x32_bf16 v[20:23], v[216:219], v[192:195], v[20:23]
	v_mfma_f32_16x16x32_bf16 v[16:19], v[224:227], v[192:195], v[16:19]
	v_mfma_f32_16x16x32_bf16 v[12:15], v[216:219], v[200:203], v[12:15]
	v_mfma_f32_16x16x32_bf16 v[8:11], v[224:227], v[200:203], v[8:11]
	v_mfma_f32_16x16x32_bf16 v[4:7], v[216:219], v[208:211], v[4:7]
	v_mfma_f32_16x16x32_bf16 v[0:3], v[224:227], v[208:211], v[0:3]
	s_setprio 0
	s_barrier
	ds_read_b128 v[142:145], v161
	ds_read_b128 v[146:149], v162
	ds_read_b128 v[172:175], v163
	ds_read_b128 v[176:179], v166
	s_mov_b32 m0, s28
	ds_read_b128 v[180:183], v150 offset:32768
	ds_read_b128 v[184:187], v150 offset:33792
	ds_read_b128 v[188:191], v150 offset:34816
	ds_read_b128 v[192:195], v150 offset:35840
	ds_read_b128 v[196:199], v150 offset:36864
	ds_read_b128 v[200:203], v150 offset:37888
	ds_read_b128 v[204:207], v150 offset:38912
	ds_read_b128 v[208:211], v150 offset:39936
	global_load_lds_dwordx4 v229, s[18:19]
	s_mov_b32 m0, s29
	s_nop 0
	global_load_lds_dwordx4 v230, s[18:19]
	s_waitcnt lgkmcnt(8)
	s_barrier
	s_waitcnt lgkmcnt(7)
	s_setprio 1
	v_mfma_f32_16x16x32_bf16 v[124:127], v[142:145], v[180:183], v[124:127]
	v_mfma_f32_16x16x32_bf16 v[120:123], v[172:175], v[180:183], v[120:123]
	s_waitcnt lgkmcnt(5)
	v_mfma_f32_16x16x32_bf16 v[116:119], v[142:145], v[188:191], v[116:119]
	v_mfma_f32_16x16x32_bf16 v[112:115], v[172:175], v[188:191], v[112:115]
	s_waitcnt lgkmcnt(3)
	v_mfma_f32_16x16x32_bf16 v[108:111], v[142:145], v[196:199], v[108:111]
	v_mfma_f32_16x16x32_bf16 v[104:107], v[172:175], v[196:199], v[104:107]
	s_waitcnt lgkmcnt(1)
	v_mfma_f32_16x16x32_bf16 v[100:103], v[142:145], v[204:207], v[100:103]
	v_mfma_f32_16x16x32_bf16 v[96:99], v[172:175], v[204:207], v[96:99]
	v_mfma_f32_16x16x32_bf16 v[124:127], v[146:149], v[184:187], v[124:127]
	v_mfma_f32_16x16x32_bf16 v[120:123], v[176:179], v[184:187], v[120:123]
	v_mfma_f32_16x16x32_bf16 v[116:119], v[146:149], v[192:195], v[116:119]
	v_mfma_f32_16x16x32_bf16 v[112:115], v[176:179], v[192:195], v[112:115]
	v_mfma_f32_16x16x32_bf16 v[108:111], v[146:149], v[200:203], v[108:111]
	v_mfma_f32_16x16x32_bf16 v[104:107], v[176:179], v[200:203], v[104:107]
	s_waitcnt lgkmcnt(0)
	v_mfma_f32_16x16x32_bf16 v[100:103], v[146:149], v[208:211], v[100:103]
	v_mfma_f32_16x16x32_bf16 v[96:99], v[176:179], v[208:211], v[96:99]
	s_setprio 0
	s_barrier
	s_mov_b32 m0, s30
	v_add_u32_e32 v132, 0x180, v132
	ds_read_b128 v[212:215], v167
	ds_read_b128 v[216:219], v168
	ds_read_b128 v[220:223], v169
	ds_read_b128 v[224:227], v170
	global_load_lds_dwordx4 v132, s[14:15]
	v_add_u32_e32 v228, 0x180, v228
	s_mov_b32 m0, s31
	s_nop 0
	global_load_lds_dwordx4 v228, s[14:15]
	s_barrier
	s_waitcnt lgkmcnt(3)
	s_setprio 1
	v_mfma_f32_16x16x32_bf16 v[92:95], v[212:215], v[180:183], v[92:95]
	s_waitcnt lgkmcnt(1)
	v_mfma_f32_16x16x32_bf16 v[88:91], v[220:223], v[180:183], v[88:91]
	v_mfma_f32_16x16x32_bf16 v[84:87], v[212:215], v[188:191], v[84:87]
	v_mfma_f32_16x16x32_bf16 v[80:83], v[220:223], v[188:191], v[80:83]
	v_mfma_f32_16x16x32_bf16 v[76:79], v[212:215], v[196:199], v[76:79]
	v_mfma_f32_16x16x32_bf16 v[72:75], v[220:223], v[196:199], v[72:75]
	v_mfma_f32_16x16x32_bf16 v[68:71], v[212:215], v[204:207], v[68:71]
	v_mfma_f32_16x16x32_bf16 v[64:67], v[220:223], v[204:207], v[64:67]
	v_mfma_f32_16x16x32_bf16 v[92:95], v[216:219], v[184:187], v[92:95]
	s_waitcnt lgkmcnt(0)
	v_mfma_f32_16x16x32_bf16 v[88:91], v[224:227], v[184:187], v[88:91]
	v_mfma_f32_16x16x32_bf16 v[84:87], v[216:219], v[192:195], v[84:87]
	v_mfma_f32_16x16x32_bf16 v[80:83], v[224:227], v[192:195], v[80:83]
	v_mfma_f32_16x16x32_bf16 v[76:79], v[216:219], v[200:203], v[76:79]
	v_mfma_f32_16x16x32_bf16 v[72:75], v[224:227], v[200:203], v[72:75]
	v_mfma_f32_16x16x32_bf16 v[68:71], v[216:219], v[208:211], v[68:71]
	v_mfma_f32_16x16x32_bf16 v[64:67], v[224:227], v[208:211], v[64:67]
	s_setprio 0
	s_mov_b32 m0, s34
	s_barrier
	ds_read_b128 v[180:183], v150 offset:49152
	ds_read_b128 v[184:187], v150 offset:50176
	ds_read_b128 v[188:191], v150 offset:51200
	ds_read_b128 v[192:195], v150 offset:52224
	ds_read_b128 v[196:199], v150 offset:53248
	ds_read_b128 v[200:203], v150 offset:54272
	ds_read_b128 v[204:207], v150 offset:55296
	ds_read_b128 v[208:211], v150 offset:56320
	global_load_lds_dwordx4 v132, s[16:17]
	s_mov_b32 m0, s35
	s_nop 0
	global_load_lds_dwordx4 v228, s[16:17]
	s_barrier
; #define SBAR() __builtin_amdgcn_sched_barrier(0)
; #define LDA8(dst, b, h) _Pragma("unroll") for (int m = 0; m < 4; ++m) _Pragma("unroll") for (int k = 0; k < 2; ++k) \
;     dst[m][k] = *reinterpret_cast<const bf16x8*>((const char*)SA8(b, h) + la + m * 2048 + k * 1024)
; #define LDB8(dst, b, h) _Pragma("unroll") for (int n = 0; n < 2; ++n) _Pragma("unroll") for (int k = 0; k < 2; ++k) \
;     dst[n][k] = *reinterpret_cast<const bf16x8*>((const char*)SB8(b, h) + lb + n * 2048 + k * 1024)
; #define MMA8(ai, bj, At_, Bx_) do { __builtin_amdgcn_s_setprio(1); \
;     _Pragma("unroll") for (int m = 0; m < 4; ++m) _Pragma("unroll") for (int n = 0; n < 2; ++n) _Pragma("unroll") for (int k = 0; k < 2; ++k) \
;       acc[ai][bj][m][n] = __builtin_amdgcn_mfma_f32_16x16x32_bf16(Bx_[n][k], At_[m][k], acc[ai][bj][m][n], 0, 0, 0); \
;     __builtin_amdgcn_s_setprio(0); } while (0)
; #define WAITV8(n) asm volatile("s_waitcnt vmcnt(" #n ")" ::: "memory")
; #define WAITL8(n) asm volatile("s_waitcnt lgkmcnt(" #n ")" ::: "memory")
; #define BAR8 __builtin_amdgcn_s_barrier()
; template <class Epi>
; DEV void gemm8_phase(const u16* __restrict__ A, int lda, const u16* __restrict__ Bt, int K, int nM, int nN, char* shmc, const Epi& epi) {
;     ...
;       LDA8(At, 1, 1); STAGE8(SA8(1, 0), A, lda, brow, kt + 3);
;       BAR8; WAITL8(0); MMA8(1, 0, At, B0); BAR8; SBAR();
;       STAGE8(SB8(1, 1), Bt, K, bcol + HALF, kt + 3);
;       WAITV8(6); BAR8; MMA8(1, 1, At, B1); BAR8;
;     }
;     { LDB8(B0, 0, 0); LDA8(At, 0, 0); STAGE8(SA8(1, 1), A, lda, brow + HALF, nt - 1);
;       BAR8; WAITL8(0); MMA8(0, 0, At, B0); BAR8;
;       LDB8(B1, 0, 1); BAR8; WAITL8(0); MMA8(0, 1, At, B1); BAR8;
	s_waitcnt lgkmcnt(7)
	s_setprio 1
	v_mfma_f32_16x16x32_bf16 v[60:63], v[142:145], v[180:183], v[60:63]
	v_mfma_f32_16x16x32_bf16 v[56:59], v[172:175], v[180:183], v[56:59]
	s_waitcnt lgkmcnt(5)
	v_mfma_f32_16x16x32_bf16 v[52:55], v[142:145], v[188:191], v[52:55]
	v_mfma_f32_16x16x32_bf16 v[48:51], v[172:175], v[188:191], v[48:51]
	s_waitcnt lgkmcnt(3)
	v_mfma_f32_16x16x32_bf16 v[44:47], v[142:145], v[196:199], v[44:47]
	v_mfma_f32_16x16x32_bf16 v[40:43], v[172:175], v[196:199], v[40:43]
	s_waitcnt lgkmcnt(1)
	v_mfma_f32_16x16x32_bf16 v[36:39], v[142:145], v[204:207], v[36:39]
	v_mfma_f32_16x16x32_bf16 v[32:35], v[172:175], v[204:207], v[32:35]
	v_mfma_f32_16x16x32_bf16 v[60:63], v[146:149], v[184:187], v[60:63]
	v_mfma_f32_16x16x32_bf16 v[56:59], v[176:179], v[184:187], v[56:59]
	v_mfma_f32_16x16x32_bf16 v[52:55], v[146:149], v[192:195], v[52:55]
	v_mfma_f32_16x16x32_bf16 v[48:51], v[176:179], v[192:195], v[48:51]
	v_mfma_f32_16x16x32_bf16 v[44:47], v[146:149], v[200:203], v[44:47]
	v_mfma_f32_16x16x32_bf16 v[40:43], v[176:179], v[200:203], v[40:43]
	s_waitcnt lgkmcnt(0)
	v_mfma_f32_16x16x32_bf16 v[36:39], v[146:149], v[208:211], v[36:39]
	v_mfma_f32_16x16x32_bf16 v[32:35], v[176:179], v[208:211], v[32:35]
	s_setprio 0
	s_barrier
	s_mov_b32 m0, s36
	s_nop 0
	global_load_lds_dwordx4 v132, s[20:21]
	s_mov_b32 m0, s37
	s_nop 0
	global_load_lds_dwordx4 v228, s[20:21]
	s_waitcnt vmcnt(6)
	s_barrier
	s_setprio 1
	v_mfma_f32_16x16x32_bf16 v[28:31], v[212:215], v[180:183], v[28:31]
	v_mfma_f32_16x16x32_bf16 v[24:27], v[220:223], v[180:183], v[24:27]
	v_mfma_f32_16x16x32_bf16 v[20:23], v[212:215], v[188:191], v[20:23]
	v_mfma_f32_16x16x32_bf16 v[16:19], v[220:223], v[188:191], v[16:19]
	v_mfma_f32_16x16x32_bf16 v[12:15], v[212:215], v[196:199], v[12:15]
	v_mfma_f32_16x16x32_bf16 v[8:11], v[220:223], v[196:199], v[8:11]
	v_mfma_f32_16x16x32_bf16 v[4:7], v[212:215], v[204:207], v[4:7]
	v_mfma_f32_16x16x32_bf16 v[0:3], v[220:223], v[204:207], v[0:3]
	v_mfma_f32_16x16x32_bf16 v[28:31], v[216:219], v[184:187], v[28:31]
	v_mfma_f32_16x16x32_bf16 v[24:27], v[224:227], v[184:187], v[24:27]
	v_mfma_f32_16x16x32_bf16 v[20:23], v[216:219], v[192:195], v[20:23]
	v_mfma_f32_16x16x32_bf16 v[16:19], v[224:227], v[192:195], v[16:19]
	v_mfma_f32_16x16x32_bf16 v[12:15], v[216:219], v[200:203], v[12:15]
	v_mfma_f32_16x16x32_bf16 v[8:11], v[224:227], v[200:203], v[8:11]
	v_mfma_f32_16x16x32_bf16 v[4:7], v[216:219], v[208:211], v[4:7]
	v_mfma_f32_16x16x32_bf16 v[0:3], v[224:227], v[208:211], v[0:3]
	s_setprio 0
	s_add_i32 s0, s0, 2
	s_addk_i32 s1, 0x100
	s_cmp_gt_u32 s0, 27
	s_barrier
	s_cbranch_scc0 .LBB0_1555
	s_mov_b32 m0, s42
	v_lshl_add_u64 v[212:213], s[18:19], 0, v[138:139]
	ds_read_b128 v[142:145], v153
	ds_read_b128 v[146:149], v154
	ds_read_b128 v[172:175], v155
	ds_read_b128 v[176:179], v156
	ds_read_b128 v[180:183], v150
	ds_read_b128 v[184:187], v150 offset:1024
	ds_read_b128 v[188:191], v150 offset:2048
	ds_read_b128 v[192:195], v150 offset:3072
	ds_read_b128 v[196:199], v150 offset:4096
	ds_read_b128 v[200:203], v150 offset:5120
	ds_read_b128 v[204:207], v150 offset:6144
	ds_read_b128 v[208:211], v150 offset:7168
	global_load_lds_dwordx4 v[212:213], off
	v_lshl_add_u64 v[212:213], s[18:19], 0, v[140:141]
	s_mov_b32 m0, s43
	s_nop 0
	global_load_lds_dwordx4 v[212:213], off
	s_barrier
	s_waitcnt lgkmcnt(0)
	s_setprio 1
	s_waitcnt lgkmcnt(0)
	v_mfma_f32_16x16x32_bf16 v[124:127], v[142:145], v[180:183], v[124:127]
	v_mfma_f32_16x16x32_bf16 v[120:123], v[172:175], v[180:183], v[120:123]
	v_mfma_f32_16x16x32_bf16 v[116:119], v[142:145], v[188:191], v[116:119]
	v_mfma_f32_16x16x32_bf16 v[112:115], v[172:175], v[188:191], v[112:115]
	v_mfma_f32_16x16x32_bf16 v[108:111], v[142:145], v[196:199], v[108:111]
	v_mfma_f32_16x16x32_bf16 v[104:107], v[172:175], v[196:199], v[104:107]
	v_mfma_f32_16x16x32_bf16 v[100:103], v[142:145], v[204:207], v[100:103]
	v_mfma_f32_16x16x32_bf16 v[96:99], v[172:175], v[204:207], v[96:99]
	v_mfma_f32_16x16x32_bf16 v[124:127], v[146:149], v[184:187], v[124:127]
	v_mfma_f32_16x16x32_bf16 v[120:123], v[176:179], v[184:187], v[120:123]
	v_mfma_f32_16x16x32_bf16 v[116:119], v[146:149], v[192:195], v[116:119]
	v_mfma_f32_16x16x32_bf16 v[112:115], v[176:179], v[192:195], v[112:115]
	v_mfma_f32_16x16x32_bf16 v[108:111], v[146:149], v[200:203], v[108:111]
	v_mfma_f32_16x16x32_bf16 v[104:107], v[176:179], v[200:203], v[104:107]
	v_mfma_f32_16x16x32_bf16 v[100:103], v[146:149], v[208:211], v[100:103]
	v_mfma_f32_16x16x32_bf16 v[96:99], v[176:179], v[208:211], v[96:99]
	s_setprio 0
	s_barrier
	ds_read_b128 v[212:215], v157
	ds_read_b128 v[216:219], v158
	ds_read_b128 v[220:223], v159
	ds_read_b128 v[224:227], v160
	s_barrier
	s_waitcnt lgkmcnt(0)
	s_setprio 1
	s_waitcnt lgkmcnt(0)
	v_mfma_f32_16x16x32_bf16 v[92:95], v[212:215], v[180:183], v[92:95]
	v_mfma_f32_16x16x32_bf16 v[88:91], v[220:223], v[180:183], v[88:91]
	v_mfma_f32_16x16x32_bf16 v[84:87], v[212:215], v[188:191], v[84:87]
	v_mfma_f32_16x16x32_bf16 v[80:83], v[220:223], v[188:191], v[80:83]
	v_mfma_f32_16x16x32_bf16 v[76:79], v[212:215], v[196:199], v[76:79]
	v_mfma_f32_16x16x32_bf16 v[72:75], v[220:223], v[196:199], v[72:75]
	v_mfma_f32_16x16x32_bf16 v[68:71], v[212:215], v[204:207], v[68:71]
	v_mfma_f32_16x16x32_bf16 v[64:67], v[220:223], v[204:207], v[64:67]
	v_mfma_f32_16x16x32_bf16 v[92:95], v[216:219], v[184:187], v[92:95]
	v_mfma_f32_16x16x32_bf16 v[88:91], v[224:227], v[184:187], v[88:91]
	v_mfma_f32_16x16x32_bf16 v[84:87], v[216:219], v[192:195], v[84:87]
	v_mfma_f32_16x16x32_bf16 v[80:83], v[224:227], v[192:195], v[80:83]
	v_mfma_f32_16x16x32_bf16 v[76:79], v[216:219], v[200:203], v[76:79]
	v_mfma_f32_16x16x32_bf16 v[72:75], v[224:227], v[200:203], v[72:75]
	v_mfma_f32_16x16x32_bf16 v[68:71], v[216:219], v[208:211], v[68:71]
	v_mfma_f32_16x16x32_bf16 v[64:67], v[224:227], v[208:211], v[64:67]
	s_setprio 0
	s_barrier
; #define LDA8(dst, b, h) _Pragma("unroll") for (int m = 0; m < 4; ++m) _Pragma("unroll") for (int k = 0; k < 2; ++k) \
;     dst[m][k] = *reinterpret_cast<const bf16x8*>((const char*)SA8(b, h) + la + m * 2048 + k * 1024)
; #define LDB8(dst, b, h) _Pragma("unroll") for (int n = 0; n < 2; ++n) _Pragma("unroll") for (int k = 0; k < 2; ++k) \
;     dst[n][k] = *reinterpret_cast<const bf16x8*>((const char*)SB8(b, h) + lb + n * 2048 + k * 1024)
; #define MMA8(ai, bj, At_, Bx_) do { __builtin_amdgcn_s_setprio(1); \
;     _Pragma("unroll") for (int m = 0; m < 4; ++m) _Pragma("unroll") for (int n = 0; n < 2; ++n) _Pragma("unroll") for (int k = 0; k < 2; ++k) \
;       acc[ai][bj][m][n] = __builtin_amdgcn_mfma_f32_16x16x32_bf16(Bx_[n][k], At_[m][k], acc[ai][bj][m][n], 0, 0, 0); \
;     __builtin_amdgcn_s_setprio(0); } while (0)
; #define WAITV8(n) asm volatile("s_waitcnt vmcnt(" #n ")" ::: "memory")
; #define WAITL8(n) asm volatile("s_waitcnt lgkmcnt(" #n ")" ::: "memory")
; #define BAR8 __builtin_amdgcn_s_barrier()
; template <class Epi>
; DEV void gemm8_phase(const u16* __restrict__ A, int lda, const u16* __restrict__ Bt, int K, int nM, int nN, char* shmc, const Epi& epi) {
;     ...
;       LDA8(At, 0, 1); WAITV8(4); BAR8; WAITL8(0); MMA8(1, 0, At, B0); MMA8(1, 1, At, B1); BAR8; }
;     { LDB8(B0, 1, 0); LDA8(At, 1, 0); WAITV8(2); BAR8; WAITL8(0); MMA8(0, 0, At, B0); BAR8;
	ds_read_b128 v[180:183], v150 offset:16384
	ds_read_b128 v[184:187], v150 offset:17408
	ds_read_b128 v[188:191], v150 offset:18432
	ds_read_b128 v[192:195], v150 offset:19456
	ds_read_b128 v[196:199], v150 offset:20480
	ds_read_b128 v[200:203], v150 offset:21504
	ds_read_b128 v[204:207], v150 offset:22528
	ds_read_b128 v[208:211], v150 offset:23552
	s_waitcnt vmcnt(4)
	s_barrier
	s_waitcnt lgkmcnt(0)
	s_setprio 1
	s_waitcnt lgkmcnt(0)
	v_mfma_f32_16x16x32_bf16 v[60:63], v[142:145], v[180:183], v[60:63]
	v_mfma_f32_16x16x32_bf16 v[56:59], v[172:175], v[180:183], v[56:59]
	v_mfma_f32_16x16x32_bf16 v[52:55], v[142:145], v[188:191], v[52:55]
	v_mfma_f32_16x16x32_bf16 v[48:51], v[172:175], v[188:191], v[48:51]
	v_mfma_f32_16x16x32_bf16 v[44:47], v[142:145], v[196:199], v[44:47]
	v_mfma_f32_16x16x32_bf16 v[40:43], v[172:175], v[196:199], v[40:43]
	v_mfma_f32_16x16x32_bf16 v[36:39], v[142:145], v[204:207], v[36:39]
	v_mfma_f32_16x16x32_bf16 v[32:35], v[172:175], v[204:207], v[32:35]
	v_mfma_f32_16x16x32_bf16 v[60:63], v[146:149], v[184:187], v[60:63]
	v_mfma_f32_16x16x32_bf16 v[56:59], v[176:179], v[184:187], v[56:59]
	v_mfma_f32_16x16x32_bf16 v[52:55], v[146:149], v[192:195], v[52:55]
	v_mfma_f32_16x16x32_bf16 v[48:51], v[176:179], v[192:195], v[48:51]
	v_mfma_f32_16x16x32_bf16 v[44:47], v[146:149], v[200:203], v[44:47]
	v_mfma_f32_16x16x32_bf16 v[40:43], v[176:179], v[200:203], v[40:43]
	v_mfma_f32_16x16x32_bf16 v[36:39], v[146:149], v[208:211], v[36:39]
	v_mfma_f32_16x16x32_bf16 v[32:35], v[176:179], v[208:211], v[32:35]
	s_setprio 0
	s_setprio 1
	v_mfma_f32_16x16x32_bf16 v[28:31], v[212:215], v[180:183], v[28:31]
	v_mfma_f32_16x16x32_bf16 v[24:27], v[220:223], v[180:183], v[24:27]
	v_mfma_f32_16x16x32_bf16 v[20:23], v[212:215], v[188:191], v[20:23]
	v_mfma_f32_16x16x32_bf16 v[16:19], v[220:223], v[188:191], v[16:19]
	v_mfma_f32_16x16x32_bf16 v[12:15], v[212:215], v[196:199], v[12:15]
	v_mfma_f32_16x16x32_bf16 v[8:11], v[220:223], v[196:199], v[8:11]
	v_mfma_f32_16x16x32_bf16 v[4:7], v[212:215], v[204:207], v[4:7]
	v_mfma_f32_16x16x32_bf16 v[0:3], v[220:223], v[204:207], v[0:3]
	v_mfma_f32_16x16x32_bf16 v[28:31], v[216:219], v[184:187], v[28:31]
	v_mfma_f32_16x16x32_bf16 v[24:27], v[224:227], v[184:187], v[24:27]
	v_mfma_f32_16x16x32_bf16 v[20:23], v[216:219], v[192:195], v[20:23]
	v_mfma_f32_16x16x32_bf16 v[16:19], v[224:227], v[192:195], v[16:19]
	v_mfma_f32_16x16x32_bf16 v[12:15], v[216:219], v[200:203], v[12:15]
	v_mfma_f32_16x16x32_bf16 v[8:11], v[224:227], v[200:203], v[8:11]
	v_mfma_f32_16x16x32_bf16 v[4:7], v[216:219], v[208:211], v[4:7]
	v_mfma_f32_16x16x32_bf16 v[0:3], v[224:227], v[208:211], v[0:3]
	s_setprio 0
	s_barrier
	ds_read_b128 v[142:145], v161
	ds_read_b128 v[146:149], v162
	ds_read_b128 v[172:175], v163
	ds_read_b128 v[176:179], v166
	ds_read_b128 v[180:183], v150 offset:32768
	ds_read_b128 v[184:187], v150 offset:33792
	ds_read_b128 v[188:191], v150 offset:34816
	ds_read_b128 v[192:195], v150 offset:35840
	ds_read_b128 v[196:199], v150 offset:36864
	ds_read_b128 v[200:203], v150 offset:37888
	ds_read_b128 v[204:207], v150 offset:38912
	ds_read_b128 v[208:211], v150 offset:39936
	s_waitcnt vmcnt(2)
	s_barrier
	s_waitcnt lgkmcnt(0)
	s_setprio 1
	s_waitcnt lgkmcnt(0)
	v_mfma_f32_16x16x32_bf16 v[124:127], v[142:145], v[180:183], v[124:127]
	v_mfma_f32_16x16x32_bf16 v[120:123], v[172:175], v[180:183], v[120:123]
	v_mfma_f32_16x16x32_bf16 v[116:119], v[142:145], v[188:191], v[116:119]
	v_mfma_f32_16x16x32_bf16 v[112:115], v[172:175], v[188:191], v[112:115]
	v_mfma_f32_16x16x32_bf16 v[108:111], v[142:145], v[196:199], v[108:111]
	v_mfma_f32_16x16x32_bf16 v[104:107], v[172:175], v[196:199], v[104:107]
	v_mfma_f32_16x16x32_bf16 v[100:103], v[142:145], v[204:207], v[100:103]
	v_mfma_f32_16x16x32_bf16 v[96:99], v[172:175], v[204:207], v[96:99]
	v_mfma_f32_16x16x32_bf16 v[124:127], v[146:149], v[184:187], v[124:127]
	v_mfma_f32_16x16x32_bf16 v[120:123], v[176:179], v[184:187], v[120:123]
	v_mfma_f32_16x16x32_bf16 v[116:119], v[146:149], v[192:195], v[116:119]
	v_mfma_f32_16x16x32_bf16 v[112:115], v[176:179], v[192:195], v[112:115]
	v_mfma_f32_16x16x32_bf16 v[108:111], v[146:149], v[200:203], v[108:111]
	v_mfma_f32_16x16x32_bf16 v[104:107], v[176:179], v[200:203], v[104:107]
	v_mfma_f32_16x16x32_bf16 v[100:103], v[146:149], v[208:211], v[100:103]
	v_mfma_f32_16x16x32_bf16 v[96:99], v[176:179], v[208:211], v[96:99]
	s_setprio 0
	s_barrier
; #define LDA8(dst, b, h) _Pragma("unroll") for (int m = 0; m < 4; ++m) _Pragma("unroll") for (int k = 0; k < 2; ++k) \
;     dst[m][k] = *reinterpret_cast<const bf16x8*>((const char*)SA8(b, h) + la + m * 2048 + k * 1024)
; #define LDB8(dst, b, h) _Pragma("unroll") for (int n = 0; n < 2; ++n) _Pragma("unroll") for (int k = 0; k < 2; ++k) \
;     dst[n][k] = *reinterpret_cast<const bf16x8*>((const char*)SB8(b, h) + lb + n * 2048 + k * 1024)
; #define MMA8(ai, bj, At_, Bx_) do { __builtin_amdgcn_s_setprio(1); \
;     _Pragma("unroll") for (int m = 0; m < 4; ++m) _Pragma("unroll") for (int n = 0; n < 2; ++n) _Pragma("unroll") for (int k = 0; k < 2; ++k) \
;       acc[ai][bj][m][n] = __builtin_amdgcn_mfma_f32_16x16x32_bf16(Bx_[n][k], At_[m][k], acc[ai][bj][m][n], 0, 0, 0); \
;     __builtin_amdgcn_s_setprio(0); } while (0)
; #define WAITV8(n) asm volatile("s_waitcnt vmcnt(" #n ")" ::: "memory")
; #define WAITL8(n) asm volatile("s_waitcnt lgkmcnt(" #n ")" ::: "memory")
; #define BAR8 __builtin_amdgcn_s_barrier()
; template <class Epi>
; DEV void gemm8_phase(const u16* __restrict__ A, int lda, const u16* __restrict__ Bt, int K, int nM, int nN, char* shmc, const Epi& epi) {
;     ...
;       LDB8(B1, 1, 1); WAITV8(0); BAR8; WAITL8(0); MMA8(0, 1, At, B1); BAR8;
;       LDA8(At, 1, 1); BAR8; WAITL8(0); MMA8(1, 0, At, B0); MMA8(1, 1, At, B1); BAR8; }
;     if (wr == 0) BAR8;
	ds_read_b128 v[212:215], v167
	ds_read_b128 v[216:219], v168
	ds_read_b128 v[220:223], v169
	ds_read_b128 v[224:227], v170
	s_waitcnt vmcnt(0)
	s_barrier
	s_waitcnt lgkmcnt(0)
	s_setprio 1
	s_waitcnt lgkmcnt(0)
	v_mfma_f32_16x16x32_bf16 v[92:95], v[212:215], v[180:183], v[92:95]
	v_mfma_f32_16x16x32_bf16 v[88:91], v[220:223], v[180:183], v[88:91]
	v_mfma_f32_16x16x32_bf16 v[84:87], v[212:215], v[188:191], v[84:87]
	v_mfma_f32_16x16x32_bf16 v[80:83], v[220:223], v[188:191], v[80:83]
	v_mfma_f32_16x16x32_bf16 v[76:79], v[212:215], v[196:199], v[76:79]
	v_mfma_f32_16x16x32_bf16 v[72:75], v[220:223], v[196:199], v[72:75]
	v_mfma_f32_16x16x32_bf16 v[68:71], v[212:215], v[204:207], v[68:71]
	v_mfma_f32_16x16x32_bf16 v[64:67], v[220:223], v[204:207], v[64:67]
	v_mfma_f32_16x16x32_bf16 v[92:95], v[216:219], v[184:187], v[92:95]
	v_mfma_f32_16x16x32_bf16 v[88:91], v[224:227], v[184:187], v[88:91]
	v_mfma_f32_16x16x32_bf16 v[84:87], v[216:219], v[192:195], v[84:87]
	v_mfma_f32_16x16x32_bf16 v[80:83], v[224:227], v[192:195], v[80:83]
	v_mfma_f32_16x16x32_bf16 v[76:79], v[216:219], v[200:203], v[76:79]
	v_mfma_f32_16x16x32_bf16 v[72:75], v[224:227], v[200:203], v[72:75]
	v_mfma_f32_16x16x32_bf16 v[68:71], v[216:219], v[208:211], v[68:71]
	v_mfma_f32_16x16x32_bf16 v[64:67], v[224:227], v[208:211], v[64:67]
	s_setprio 0
	s_barrier
	ds_read_b128 v[180:183], v150 offset:49152
	ds_read_b128 v[184:187], v150 offset:50176
	ds_read_b128 v[188:191], v150 offset:51200
	ds_read_b128 v[192:195], v150 offset:52224
	ds_read_b128 v[196:199], v150 offset:53248
	ds_read_b128 v[200:203], v150 offset:54272
	ds_read_b128 v[204:207], v150 offset:55296
	ds_read_b128 v[208:211], v150 offset:56320
	s_barrier
	s_waitcnt lgkmcnt(0)
	s_setprio 1
	s_waitcnt lgkmcnt(0)
	v_mfma_f32_16x16x32_bf16 v[60:63], v[142:145], v[180:183], v[60:63]
	v_mfma_f32_16x16x32_bf16 v[56:59], v[172:175], v[180:183], v[56:59]
	v_mfma_f32_16x16x32_bf16 v[52:55], v[142:145], v[188:191], v[52:55]
	v_mfma_f32_16x16x32_bf16 v[48:51], v[172:175], v[188:191], v[48:51]
	v_mfma_f32_16x16x32_bf16 v[44:47], v[142:145], v[196:199], v[44:47]
	v_mfma_f32_16x16x32_bf16 v[40:43], v[172:175], v[196:199], v[40:43]
	v_mfma_f32_16x16x32_bf16 v[36:39], v[142:145], v[204:207], v[36:39]
	v_mfma_f32_16x16x32_bf16 v[32:35], v[172:175], v[204:207], v[32:35]
	v_mfma_f32_16x16x32_bf16 v[60:63], v[146:149], v[184:187], v[60:63]
	v_mfma_f32_16x16x32_bf16 v[56:59], v[176:179], v[184:187], v[56:59]
	v_mfma_f32_16x16x32_bf16 v[52:55], v[146:149], v[192:195], v[52:55]
	v_mfma_f32_16x16x32_bf16 v[48:51], v[176:179], v[192:195], v[48:51]
	v_mfma_f32_16x16x32_bf16 v[44:47], v[146:149], v[200:203], v[44:47]
	v_mfma_f32_16x16x32_bf16 v[40:43], v[176:179], v[200:203], v[40:43]
	v_mfma_f32_16x16x32_bf16 v[36:39], v[146:149], v[208:211], v[36:39]
	v_mfma_f32_16x16x32_bf16 v[32:35], v[176:179], v[208:211], v[32:35]
	s_setprio 0
	s_setprio 1
	v_mfma_f32_16x16x32_bf16 v[28:31], v[212:215], v[180:183], v[28:31]
	v_mfma_f32_16x16x32_bf16 v[24:27], v[220:223], v[180:183], v[24:27]
	v_mfma_f32_16x16x32_bf16 v[20:23], v[212:215], v[188:191], v[20:23]
	v_mfma_f32_16x16x32_bf16 v[16:19], v[220:223], v[188:191], v[16:19]
	v_mfma_f32_16x16x32_bf16 v[12:15], v[212:215], v[196:199], v[12:15]
	v_mfma_f32_16x16x32_bf16 v[8:11], v[220:223], v[196:199], v[8:11]
	v_mfma_f32_16x16x32_bf16 v[4:7], v[212:215], v[204:207], v[4:7]
	v_mfma_f32_16x16x32_bf16 v[0:3], v[220:223], v[204:207], v[0:3]
	v_mfma_f32_16x16x32_bf16 v[28:31], v[216:219], v[184:187], v[28:31]
	v_mfma_f32_16x16x32_bf16 v[24:27], v[224:227], v[184:187], v[24:27]
	v_mfma_f32_16x16x32_bf16 v[20:23], v[216:219], v[192:195], v[20:23]
	v_mfma_f32_16x16x32_bf16 v[16:19], v[224:227], v[192:195], v[16:19]
	v_mfma_f32_16x16x32_bf16 v[12:15], v[216:219], v[200:203], v[12:15]
	v_mfma_f32_16x16x32_bf16 v[8:11], v[224:227], v[200:203], v[8:11]
	v_mfma_f32_16x16x32_bf16 v[4:7], v[216:219], v[208:211], v[4:7]
	v_mfma_f32_16x16x32_bf16 v[0:3], v[224:227], v[208:211], v[0:3]
	s_setprio 0
	s_and_b64 vcc, exec, s[10:11]
	s_barrier
	s_cbranch_vccz .LBB0_1558
	s_barrier

; #define SBAR() __builtin_amdgcn_sched_barrier(0)
; #define LDA8(dst, b, h) _Pragma("unroll") for (int m = 0; m < 4; ++m) _Pragma("unroll") for (int k = 0; k < 2; ++k) \
;     dst[m][k] = *reinterpret_cast<const bf16x8*>((const char*)SA8(b, h) + la + m * 2048 + k * 1024)
; #define LDB8(dst, b, h) _Pragma("unroll") for (int n = 0; n < 2; ++n) _Pragma("unroll") for (int k = 0; k < 2; ++k) \
;     dst[n][k] = *reinterpret_cast<const bf16x8*>((const char*)SB8(b, h) + lb + n * 2048 + k * 1024)
; #define MMA8(ai, bj, At_, Bx_) do { __builtin_amdgcn_s_setprio(1); \
;     _Pragma("unroll") for (int m = 0; m < 4; ++m) _Pragma("unroll") for (int n = 0; n < 2; ++n) _Pragma("unroll") for (int k = 0; k < 2; ++k) \
;       acc[ai][bj][m][n] = __builtin_amdgcn_mfma_f32_16x16x32_bf16(Bx_[n][k], At_[m][k], acc[ai][bj][m][n], 0, 0, 0); \
;     __builtin_amdgcn_s_setprio(0); } while (0)
; #define WAITV8(n) asm volatile("s_waitcnt vmcnt(" #n ")" ::: "memory")
; #define WAITL8(n) asm volatile("s_waitcnt lgkmcnt(" #n ")" ::: "memory")
; #define BAR8 __builtin_amdgcn_s_barrier()
; template <class Epi>
; DEV void gemm8_phase(const u16* __restrict__ A, int lda, const u16* __restrict__ Bt, int K, int nM, int nN, char* shmc, const Epi& epi) {
;     ...
;       LDB8(B0, 0, 0); SBAR(); LDA8(At, 0, 0); STAGE8(SA8(1, 1), A, lda, brow + HALF, kt + 1);
;       WAITL8(8); BAR8; WAITL8(0); MMA8(0, 0, At, B0); BAR8; SBAR();
;       LDB8(B1, 0, 1); STAGE8(SB8(0, 0), Bt, K, bcol, kt + 2);
;       BAR8; WAITL8(0); MMA8(0, 1, At, B1); BAR8;
;       LDA8(At, 0, 1); STAGE8(SA8(0, 0), A, lda, brow, kt + 2);
;       BAR8; WAITL8(0); MMA8(1, 0, At, B0); BAR8; SBAR();
;       STAGE8(SB8(0, 1), Bt, K, bcol + HALF, kt + 2);
;       WAITV8(6); BAR8; MMA8(1, 1, At, B1); BAR8;
.LBB0_1625:
	ds_read_b128 v[144:147], v160
	ds_read_b128 v[148:151], v161
	ds_read_b128 v[152:155], v162
	ds_read_b128 v[178:181], v163
	v_add_u32_e32 v143, v156, v132
	s_mov_b32 m0, s44
	v_add_u32_e32 v214, 0x80, v143
	v_add_u32_e32 v230, v156, v142
	ds_read_b128 v[182:185], v157
	ds_read_b128 v[186:189], v157 offset:1024
	ds_read_b128 v[190:193], v157 offset:2048
	ds_read_b128 v[194:197], v157 offset:3072
	ds_read_b128 v[198:201], v157 offset:4096
	ds_read_b128 v[202:205], v157 offset:5120
	ds_read_b128 v[206:209], v157 offset:6144
	ds_read_b128 v[210:213], v157 offset:7168
	global_load_lds_dwordx4 v214, s[20:21]
	v_add_u32_e32 v214, 0x80, v230
	s_mov_b32 m0, s45
	s_nop 0
	global_load_lds_dwordx4 v214, s[20:21]
	s_waitcnt lgkmcnt(8)
	s_barrier
	s_waitcnt lgkmcnt(7)
	s_setprio 1
	v_mfma_f32_16x16x32_bf16 v[124:127], v[144:147], v[182:185], v[124:127]
	v_mfma_f32_16x16x32_bf16 v[120:123], v[152:155], v[182:185], v[120:123]
	s_waitcnt lgkmcnt(5)
	v_mfma_f32_16x16x32_bf16 v[116:119], v[144:147], v[190:193], v[116:119]
	v_mfma_f32_16x16x32_bf16 v[112:115], v[152:155], v[190:193], v[112:115]
	s_waitcnt lgkmcnt(3)
	v_mfma_f32_16x16x32_bf16 v[108:111], v[144:147], v[198:201], v[108:111]
	v_mfma_f32_16x16x32_bf16 v[104:107], v[152:155], v[198:201], v[104:107]
	s_waitcnt lgkmcnt(1)
	v_mfma_f32_16x16x32_bf16 v[100:103], v[144:147], v[206:209], v[100:103]
	v_mfma_f32_16x16x32_bf16 v[96:99], v[152:155], v[206:209], v[96:99]
	v_mfma_f32_16x16x32_bf16 v[124:127], v[148:151], v[186:189], v[124:127]
	v_mfma_f32_16x16x32_bf16 v[120:123], v[178:181], v[186:189], v[120:123]
	v_mfma_f32_16x16x32_bf16 v[116:119], v[148:151], v[194:197], v[116:119]
	v_mfma_f32_16x16x32_bf16 v[112:115], v[178:181], v[194:197], v[112:115]
	v_mfma_f32_16x16x32_bf16 v[108:111], v[148:151], v[202:205], v[108:111]
	v_mfma_f32_16x16x32_bf16 v[104:107], v[178:181], v[202:205], v[104:107]
	s_waitcnt lgkmcnt(0)
	v_mfma_f32_16x16x32_bf16 v[100:103], v[148:151], v[210:213], v[100:103]
	v_mfma_f32_16x16x32_bf16 v[96:99], v[178:181], v[210:213], v[96:99]
	s_setprio 0
	s_barrier
	s_mov_b32 m0, s25
	v_add_u32_e32 v231, 0x100, v143
	ds_read_b128 v[214:217], v166
	ds_read_b128 v[218:221], v167
	ds_read_b128 v[222:225], v168
	ds_read_b128 v[226:229], v169
	global_load_lds_dwordx4 v231, s[16:17]
	v_add_u32_e32 v232, 0x100, v230
	s_mov_b32 m0, s26
	s_nop 0
	global_load_lds_dwordx4 v232, s[16:17]
	s_barrier
	s_waitcnt lgkmcnt(3)
	s_setprio 1
	v_mfma_f32_16x16x32_bf16 v[92:95], v[214:217], v[182:185], v[92:95]
	s_waitcnt lgkmcnt(1)
	v_mfma_f32_16x16x32_bf16 v[88:91], v[222:225], v[182:185], v[88:91]
	v_mfma_f32_16x16x32_bf16 v[84:87], v[214:217], v[190:193], v[84:87]
	v_mfma_f32_16x16x32_bf16 v[80:83], v[222:225], v[190:193], v[80:83]
	v_mfma_f32_16x16x32_bf16 v[76:79], v[214:217], v[198:201], v[76:79]
	v_mfma_f32_16x16x32_bf16 v[72:75], v[222:225], v[198:201], v[72:75]
	v_mfma_f32_16x16x32_bf16 v[68:71], v[214:217], v[206:209], v[68:71]
	v_mfma_f32_16x16x32_bf16 v[64:67], v[222:225], v[206:209], v[64:67]
	v_mfma_f32_16x16x32_bf16 v[92:95], v[218:221], v[186:189], v[92:95]
	s_waitcnt lgkmcnt(0)
	v_mfma_f32_16x16x32_bf16 v[88:91], v[226:229], v[186:189], v[88:91]
	v_mfma_f32_16x16x32_bf16 v[84:87], v[218:221], v[194:197], v[84:87]
	v_mfma_f32_16x16x32_bf16 v[80:83], v[226:229], v[194:197], v[80:83]
	v_mfma_f32_16x16x32_bf16 v[76:79], v[218:221], v[202:205], v[76:79]
	v_mfma_f32_16x16x32_bf16 v[72:75], v[226:229], v[202:205], v[72:75]
	v_mfma_f32_16x16x32_bf16 v[68:71], v[218:221], v[210:213], v[68:71]
	v_mfma_f32_16x16x32_bf16 v[64:67], v[226:229], v[210:213], v[64:67]
	s_setprio 0
	s_mov_b32 m0, s3
	s_barrier
	ds_read_b128 v[182:185], v157 offset:16384
	ds_read_b128 v[186:189], v157 offset:17408
	ds_read_b128 v[190:193], v157 offset:18432
	ds_read_b128 v[194:197], v157 offset:19456
	ds_read_b128 v[198:201], v157 offset:20480
	ds_read_b128 v[202:205], v157 offset:21504
	ds_read_b128 v[206:209], v157 offset:22528
	ds_read_b128 v[210:213], v157 offset:23552
	global_load_lds_dwordx4 v231, s[18:19]
	s_mov_b32 m0, s27
	s_nop 0
	global_load_lds_dwordx4 v232, s[18:19]
	s_barrier
	s_waitcnt lgkmcnt(7)
	s_setprio 1
	v_mfma_f32_16x16x32_bf16 v[60:63], v[144:147], v[182:185], v[60:63]
	v_mfma_f32_16x16x32_bf16 v[56:59], v[152:155], v[182:185], v[56:59]
	s_waitcnt lgkmcnt(5)
	v_mfma_f32_16x16x32_bf16 v[52:55], v[144:147], v[190:193], v[52:55]
	v_mfma_f32_16x16x32_bf16 v[48:51], v[152:155], v[190:193], v[48:51]
	s_waitcnt lgkmcnt(3)
	v_mfma_f32_16x16x32_bf16 v[44:47], v[144:147], v[198:201], v[44:47]
	v_mfma_f32_16x16x32_bf16 v[40:43], v[152:155], v[198:201], v[40:43]
	s_waitcnt lgkmcnt(1)
	v_mfma_f32_16x16x32_bf16 v[36:39], v[144:147], v[206:209], v[36:39]
	v_mfma_f32_16x16x32_bf16 v[32:35], v[152:155], v[206:209], v[32:35]
	v_mfma_f32_16x16x32_bf16 v[60:63], v[148:151], v[186:189], v[60:63]
	v_mfma_f32_16x16x32_bf16 v[56:59], v[178:181], v[186:189], v[56:59]
	v_mfma_f32_16x16x32_bf16 v[52:55], v[148:151], v[194:197], v[52:55]
	v_mfma_f32_16x16x32_bf16 v[48:51], v[178:181], v[194:197], v[48:51]
	v_mfma_f32_16x16x32_bf16 v[44:47], v[148:151], v[202:205], v[44:47]
	v_mfma_f32_16x16x32_bf16 v[40:43], v[178:181], v[202:205], v[40:43]
	s_waitcnt lgkmcnt(0)
	v_mfma_f32_16x16x32_bf16 v[36:39], v[148:151], v[210:213], v[36:39]
	v_mfma_f32_16x16x32_bf16 v[32:35], v[178:181], v[210:213], v[32:35]
	s_setprio 0
	s_barrier
	s_mov_b32 m0, s28
	s_nop 0
	global_load_lds_dwordx4 v231, s[22:23]
	s_mov_b32 m0, s29
	s_nop 0
	global_load_lds_dwordx4 v232, s[22:23]
	s_waitcnt vmcnt(6)
	s_barrier
; #define SBAR() __builtin_amdgcn_sched_barrier(0)
; #define LDA8(dst, b, h) _Pragma("unroll") for (int m = 0; m < 4; ++m) _Pragma("unroll") for (int k = 0; k < 2; ++k) \
;     dst[m][k] = *reinterpret_cast<const bf16x8*>((const char*)SA8(b, h) + la + m * 2048 + k * 1024)
; #define LDB8(dst, b, h) _Pragma("unroll") for (int n = 0; n < 2; ++n) _Pragma("unroll") for (int k = 0; k < 2; ++k) \
;     dst[n][k] = *reinterpret_cast<const bf16x8*>((const char*)SB8(b, h) + lb + n * 2048 + k * 1024)
; #define MMA8(ai, bj, At_, Bx_) do { __builtin_amdgcn_s_setprio(1); \
;     _Pragma("unroll") for (int m = 0; m < 4; ++m) _Pragma("unroll") for (int n = 0; n < 2; ++n) _Pragma("unroll") for (int k = 0; k < 2; ++k) \
;       acc[ai][bj][m][n] = __builtin_amdgcn_mfma_f32_16x16x32_bf16(Bx_[n][k], At_[m][k], acc[ai][bj][m][n], 0, 0, 0); \
;     __builtin_amdgcn_s_setprio(0); } while (0)
; #define WAITV8(n) asm volatile("s_waitcnt vmcnt(" #n ")" ::: "memory")
; #define WAITL8(n) asm volatile("s_waitcnt lgkmcnt(" #n ")" ::: "memory")
; #define BAR8 __builtin_amdgcn_s_barrier()
; template <class Epi>
; DEV void gemm8_phase(const u16* __restrict__ A, int lda, const u16* __restrict__ Bt, int K, int nM, int nN, char* shmc, const Epi& epi) {
;     ...
;       WAITV8(6); BAR8; MMA8(1, 1, At, B1); BAR8;
;       LDB8(B0, 1, 0); SBAR(); LDA8(At, 1, 0); STAGE8(SA8(0, 1), A, lda, brow + HALF, kt + 2);
;       WAITL8(8); BAR8; WAITL8(0); MMA8(0, 0, At, B0); BAR8; SBAR();
;       LDB8(B1, 1, 1); STAGE8(SB8(1, 0), Bt, K, bcol, kt + 3);
;       BAR8; WAITL8(0); MMA8(0, 1, At, B1); BAR8;
;       LDA8(At, 1, 1); STAGE8(SA8(1, 0), A, lda, brow, kt + 3);
	s_setprio 1
	v_mfma_f32_16x16x32_bf16 v[28:31], v[214:217], v[182:185], v[28:31]
	v_mfma_f32_16x16x32_bf16 v[24:27], v[222:225], v[182:185], v[24:27]
	v_mfma_f32_16x16x32_bf16 v[20:23], v[214:217], v[190:193], v[20:23]
	v_mfma_f32_16x16x32_bf16 v[16:19], v[222:225], v[190:193], v[16:19]
	v_mfma_f32_16x16x32_bf16 v[12:15], v[214:217], v[198:201], v[12:15]
	v_mfma_f32_16x16x32_bf16 v[8:11], v[222:225], v[198:201], v[8:11]
	v_mfma_f32_16x16x32_bf16 v[4:7], v[214:217], v[206:209], v[4:7]
	v_mfma_f32_16x16x32_bf16 v[0:3], v[222:225], v[206:209], v[0:3]
	v_mfma_f32_16x16x32_bf16 v[28:31], v[218:221], v[186:189], v[28:31]
	v_mfma_f32_16x16x32_bf16 v[24:27], v[226:229], v[186:189], v[24:27]
	v_mfma_f32_16x16x32_bf16 v[20:23], v[218:221], v[194:197], v[20:23]
	v_mfma_f32_16x16x32_bf16 v[16:19], v[226:229], v[194:197], v[16:19]
	v_mfma_f32_16x16x32_bf16 v[12:15], v[218:221], v[202:205], v[12:15]
	v_mfma_f32_16x16x32_bf16 v[8:11], v[226:229], v[202:205], v[8:11]
	v_mfma_f32_16x16x32_bf16 v[4:7], v[218:221], v[210:213], v[4:7]
	v_mfma_f32_16x16x32_bf16 v[0:3], v[226:229], v[210:213], v[0:3]
	s_setprio 0
	s_barrier
	ds_read_b128 v[144:147], v170
	ds_read_b128 v[148:151], v171
	ds_read_b128 v[152:155], v172
	ds_read_b128 v[178:181], v173
	s_mov_b32 m0, s30
	ds_read_b128 v[182:185], v157 offset:32768
	ds_read_b128 v[186:189], v157 offset:33792
	ds_read_b128 v[190:193], v157 offset:34816
	ds_read_b128 v[194:197], v157 offset:35840
	ds_read_b128 v[198:201], v157 offset:36864
	ds_read_b128 v[202:205], v157 offset:37888
	ds_read_b128 v[206:209], v157 offset:38912
	ds_read_b128 v[210:213], v157 offset:39936
	global_load_lds_dwordx4 v231, s[20:21]
	s_mov_b32 m0, s31
	s_nop 0
	global_load_lds_dwordx4 v232, s[20:21]
	s_waitcnt lgkmcnt(8)
	s_barrier
	s_waitcnt lgkmcnt(7)
	s_setprio 1
	v_mfma_f32_16x16x32_bf16 v[124:127], v[144:147], v[182:185], v[124:127]
	v_mfma_f32_16x16x32_bf16 v[120:123], v[152:155], v[182:185], v[120:123]
	s_waitcnt lgkmcnt(5)
	v_mfma_f32_16x16x32_bf16 v[116:119], v[144:147], v[190:193], v[116:119]
	v_mfma_f32_16x16x32_bf16 v[112:115], v[152:155], v[190:193], v[112:115]
	s_waitcnt lgkmcnt(3)
	v_mfma_f32_16x16x32_bf16 v[108:111], v[144:147], v[198:201], v[108:111]
	v_mfma_f32_16x16x32_bf16 v[104:107], v[152:155], v[198:201], v[104:107]
	s_waitcnt lgkmcnt(1)
	v_mfma_f32_16x16x32_bf16 v[100:103], v[144:147], v[206:209], v[100:103]
	v_mfma_f32_16x16x32_bf16 v[96:99], v[152:155], v[206:209], v[96:99]
	v_mfma_f32_16x16x32_bf16 v[124:127], v[148:151], v[186:189], v[124:127]
	v_mfma_f32_16x16x32_bf16 v[120:123], v[178:181], v[186:189], v[120:123]
	v_mfma_f32_16x16x32_bf16 v[116:119], v[148:151], v[194:197], v[116:119]
	v_mfma_f32_16x16x32_bf16 v[112:115], v[178:181], v[194:197], v[112:115]
	v_mfma_f32_16x16x32_bf16 v[108:111], v[148:151], v[202:205], v[108:111]
	v_mfma_f32_16x16x32_bf16 v[104:107], v[178:181], v[202:205], v[104:107]
	s_waitcnt lgkmcnt(0)
	v_mfma_f32_16x16x32_bf16 v[100:103], v[148:151], v[210:213], v[100:103]
	v_mfma_f32_16x16x32_bf16 v[96:99], v[178:181], v[210:213], v[96:99]
	s_setprio 0
	s_barrier
	s_mov_b32 m0, s34
	v_add_u32_e32 v143, 0x180, v143
	ds_read_b128 v[214:217], v174
	ds_read_b128 v[218:221], v175
	ds_read_b128 v[222:225], v176
	ds_read_b128 v[226:229], v177
	global_load_lds_dwordx4 v143, s[16:17]
	v_add_u32_e32 v230, 0x180, v230
	s_mov_b32 m0, s35
	s_nop 0
	global_load_lds_dwordx4 v230, s[16:17]
	s_barrier
	s_waitcnt lgkmcnt(3)
	s_setprio 1
	v_mfma_f32_16x16x32_bf16 v[92:95], v[214:217], v[182:185], v[92:95]
	s_waitcnt lgkmcnt(1)
	v_mfma_f32_16x16x32_bf16 v[88:91], v[222:225], v[182:185], v[88:91]
	v_mfma_f32_16x16x32_bf16 v[84:87], v[214:217], v[190:193], v[84:87]
	v_mfma_f32_16x16x32_bf16 v[80:83], v[222:225], v[190:193], v[80:83]
	v_mfma_f32_16x16x32_bf16 v[76:79], v[214:217], v[198:201], v[76:79]
	v_mfma_f32_16x16x32_bf16 v[72:75], v[222:225], v[198:201], v[72:75]
	v_mfma_f32_16x16x32_bf16 v[68:71], v[214:217], v[206:209], v[68:71]
	v_mfma_f32_16x16x32_bf16 v[64:67], v[222:225], v[206:209], v[64:67]
	v_mfma_f32_16x16x32_bf16 v[92:95], v[218:221], v[186:189], v[92:95]
	s_waitcnt lgkmcnt(0)
	v_mfma_f32_16x16x32_bf16 v[88:91], v[226:229], v[186:189], v[88:91]
	v_mfma_f32_16x16x32_bf16 v[84:87], v[218:221], v[194:197], v[84:87]
	v_mfma_f32_16x16x32_bf16 v[80:83], v[226:229], v[194:197], v[80:83]
	v_mfma_f32_16x16x32_bf16 v[76:79], v[218:221], v[202:205], v[76:79]
	v_mfma_f32_16x16x32_bf16 v[72:75], v[226:229], v[202:205], v[72:75]
	v_mfma_f32_16x16x32_bf16 v[68:71], v[218:221], v[210:213], v[68:71]
	v_mfma_f32_16x16x32_bf16 v[64:67], v[226:229], v[210:213], v[64:67]
	s_setprio 0
	s_mov_b32 m0, s36
	s_barrier
	ds_read_b128 v[182:185], v157 offset:49152
	ds_read_b128 v[186:189], v157 offset:50176
	ds_read_b128 v[190:193], v157 offset:51200
	ds_read_b128 v[194:197], v157 offset:52224
	ds_read_b128 v[198:201], v157 offset:53248
	ds_read_b128 v[202:205], v157 offset:54272
	ds_read_b128 v[206:209], v157 offset:55296
	ds_read_b128 v[210:213], v157 offset:56320
	global_load_lds_dwordx4 v143, s[18:19]
	s_mov_b32 m0, s37
	s_nop 0
	global_load_lds_dwordx4 v230, s[18:19]
	s_barrier
; #define SBAR() __builtin_amdgcn_sched_barrier(0)
; #define LDA8(dst, b, h) _Pragma("unroll") for (int m = 0; m < 4; ++m) _Pragma("unroll") for (int k = 0; k < 2; ++k) \
;     dst[m][k] = *reinterpret_cast<const bf16x8*>((const char*)SA8(b, h) + la + m * 2048 + k * 1024)
; #define LDB8(dst, b, h) _Pragma("unroll") for (int n = 0; n < 2; ++n) _Pragma("unroll") for (int k = 0; k < 2; ++k) \
;     dst[n][k] = *reinterpret_cast<const bf16x8*>((const char*)SB8(b, h) + lb + n * 2048 + k * 1024)
; #define MMA8(ai, bj, At_, Bx_) do { __builtin_amdgcn_s_setprio(1); \
;     _Pragma("unroll") for (int m = 0; m < 4; ++m) _Pragma("unroll") for (int n = 0; n < 2; ++n) _Pragma("unroll") for (int k = 0; k < 2; ++k) \
;       acc[ai][bj][m][n] = __builtin_amdgcn_mfma_f32_16x16x32_bf16(Bx_[n][k], At_[m][k], acc[ai][bj][m][n], 0, 0, 0); \
;     __builtin_amdgcn_s_setprio(0); } while (0)
; #define WAITV8(n) asm volatile("s_waitcnt vmcnt(" #n ")" ::: "memory")
; #define WAITL8(n) asm volatile("s_waitcnt lgkmcnt(" #n ")" ::: "memory")
; #define BAR8 __builtin_amdgcn_s_barrier()
; template <class Epi>
; DEV void gemm8_phase(const u16* __restrict__ A, int lda, const u16* __restrict__ Bt, int K, int nM, int nN, char* shmc, const Epi& epi) {
;     ...
;       BAR8; WAITL8(0); MMA8(1, 0, At, B0); BAR8; SBAR();
;       STAGE8(SB8(1, 1), Bt, K, bcol + HALF, kt + 3);
;       WAITV8(6); BAR8; MMA8(1, 1, At, B1); BAR8;
;     }
;     { LDB8(B0, 0, 0); LDA8(At, 0, 0); STAGE8(SA8(1, 1), A, lda, brow + HALF, nt - 1);
;       BAR8; WAITL8(0); MMA8(0, 0, At, B0); BAR8;
;       LDB8(B1, 0, 1); BAR8; WAITL8(0); MMA8(0, 1, At, B1); BAR8;
	s_waitcnt lgkmcnt(7)
	s_setprio 1
	v_mfma_f32_16x16x32_bf16 v[60:63], v[144:147], v[182:185], v[60:63]
	v_mfma_f32_16x16x32_bf16 v[56:59], v[152:155], v[182:185], v[56:59]
	s_waitcnt lgkmcnt(5)
	v_mfma_f32_16x16x32_bf16 v[52:55], v[144:147], v[190:193], v[52:55]
	v_mfma_f32_16x16x32_bf16 v[48:51], v[152:155], v[190:193], v[48:51]
	s_waitcnt lgkmcnt(3)
	v_mfma_f32_16x16x32_bf16 v[44:47], v[144:147], v[198:201], v[44:47]
	v_mfma_f32_16x16x32_bf16 v[40:43], v[152:155], v[198:201], v[40:43]
	s_waitcnt lgkmcnt(1)
	v_mfma_f32_16x16x32_bf16 v[36:39], v[144:147], v[206:209], v[36:39]
	v_mfma_f32_16x16x32_bf16 v[32:35], v[152:155], v[206:209], v[32:35]
	v_mfma_f32_16x16x32_bf16 v[60:63], v[148:151], v[186:189], v[60:63]
	v_mfma_f32_16x16x32_bf16 v[56:59], v[178:181], v[186:189], v[56:59]
	v_mfma_f32_16x16x32_bf16 v[52:55], v[148:151], v[194:197], v[52:55]
	v_mfma_f32_16x16x32_bf16 v[48:51], v[178:181], v[194:197], v[48:51]
	v_mfma_f32_16x16x32_bf16 v[44:47], v[148:151], v[202:205], v[44:47]
	v_mfma_f32_16x16x32_bf16 v[40:43], v[178:181], v[202:205], v[40:43]
	s_waitcnt lgkmcnt(0)
	v_mfma_f32_16x16x32_bf16 v[36:39], v[148:151], v[210:213], v[36:39]
	v_mfma_f32_16x16x32_bf16 v[32:35], v[178:181], v[210:213], v[32:35]
	s_setprio 0
	s_barrier
	s_mov_b32 m0, s42
	s_nop 0
	global_load_lds_dwordx4 v143, s[22:23]
	s_mov_b32 m0, s43
	s_nop 0
	global_load_lds_dwordx4 v230, s[22:23]
	s_waitcnt vmcnt(6)
	s_barrier
	s_setprio 1
	v_mfma_f32_16x16x32_bf16 v[28:31], v[214:217], v[182:185], v[28:31]
	v_mfma_f32_16x16x32_bf16 v[24:27], v[222:225], v[182:185], v[24:27]
	v_mfma_f32_16x16x32_bf16 v[20:23], v[214:217], v[190:193], v[20:23]
	v_mfma_f32_16x16x32_bf16 v[16:19], v[222:225], v[190:193], v[16:19]
	v_mfma_f32_16x16x32_bf16 v[12:15], v[214:217], v[198:201], v[12:15]
	v_mfma_f32_16x16x32_bf16 v[8:11], v[222:225], v[198:201], v[8:11]
	v_mfma_f32_16x16x32_bf16 v[4:7], v[214:217], v[206:209], v[4:7]
	v_mfma_f32_16x16x32_bf16 v[0:3], v[222:225], v[206:209], v[0:3]
	v_mfma_f32_16x16x32_bf16 v[28:31], v[218:221], v[186:189], v[28:31]
	v_mfma_f32_16x16x32_bf16 v[24:27], v[226:229], v[186:189], v[24:27]
	v_mfma_f32_16x16x32_bf16 v[20:23], v[218:221], v[194:197], v[20:23]
	v_mfma_f32_16x16x32_bf16 v[16:19], v[226:229], v[194:197], v[16:19]
	v_mfma_f32_16x16x32_bf16 v[12:15], v[218:221], v[202:205], v[12:15]
	v_mfma_f32_16x16x32_bf16 v[8:11], v[226:229], v[202:205], v[8:11]
	v_mfma_f32_16x16x32_bf16 v[4:7], v[218:221], v[210:213], v[4:7]
	v_mfma_f32_16x16x32_bf16 v[0:3], v[226:229], v[210:213], v[0:3]
	s_setprio 0
	s_add_i32 s0, s0, 2
	v_add_u32_e32 v142, 0x100, v142
	s_cmp_lt_u32 s0, 28
	v_add_u32_e32 v132, 0x100, v132
	s_barrier
	s_cbranch_scc1 .LBB0_1625
	s_mov_b32 m0, s44
	v_lshl_add_u64 v[154:155], s[20:21], 0, v[138:139]
	ds_read_b128 v[142:145], v160
	ds_read_b128 v[146:149], v161
	ds_read_b128 v[150:153], v162
	ds_read_b128 v[178:181], v163
	ds_read_b128 v[182:185], v157
	ds_read_b128 v[186:189], v157 offset:1024
	ds_read_b128 v[190:193], v157 offset:2048
	ds_read_b128 v[194:197], v157 offset:3072
	ds_read_b128 v[198:201], v157 offset:4096
	ds_read_b128 v[202:205], v157 offset:5120
	ds_read_b128 v[206:209], v157 offset:6144
	ds_read_b128 v[210:213], v157 offset:7168
	global_load_lds_dwordx4 v[154:155], off
	v_lshl_add_u64 v[154:155], s[20:21], 0, v[140:141]
	s_mov_b32 m0, s45
	s_nop 0
	global_load_lds_dwordx4 v[154:155], off
	s_barrier
	s_waitcnt lgkmcnt(0)
	s_setprio 1
	s_waitcnt lgkmcnt(0)
	v_mfma_f32_16x16x32_bf16 v[124:127], v[142:145], v[182:185], v[124:127]
	v_mfma_f32_16x16x32_bf16 v[116:119], v[142:145], v[190:193], v[116:119]
	v_mfma_f32_16x16x32_bf16 v[108:111], v[142:145], v[198:201], v[108:111]
	v_mfma_f32_16x16x32_bf16 v[100:103], v[142:145], v[206:209], v[100:103]
	v_mfma_f32_16x16x32_bf16 v[124:127], v[146:149], v[186:189], v[124:127]
	v_mfma_f32_16x16x32_bf16 v[120:123], v[150:153], v[182:185], v[120:123]
	v_mfma_f32_16x16x32_bf16 v[116:119], v[146:149], v[194:197], v[116:119]
	v_mfma_f32_16x16x32_bf16 v[112:115], v[150:153], v[190:193], v[112:115]
	v_mfma_f32_16x16x32_bf16 v[108:111], v[146:149], v[202:205], v[108:111]
	v_mfma_f32_16x16x32_bf16 v[104:107], v[150:153], v[198:201], v[104:107]
	v_mfma_f32_16x16x32_bf16 v[100:103], v[146:149], v[210:213], v[100:103]
	v_mfma_f32_16x16x32_bf16 v[96:99], v[150:153], v[206:209], v[96:99]
	v_mfma_f32_16x16x32_bf16 v[214:217], v[178:181], v[186:189], v[120:123]
	v_mfma_f32_16x16x32_bf16 v[218:221], v[178:181], v[194:197], v[112:115]
	v_mfma_f32_16x16x32_bf16 v[222:225], v[178:181], v[202:205], v[104:107]
	v_mfma_f32_16x16x32_bf16 v[226:229], v[178:181], v[210:213], v[96:99]
	s_setprio 0
	s_barrier
	s_nop 1
	ds_read_b128 v[96:99], v166
	ds_read_b128 v[104:107], v167
	ds_read_b128 v[112:115], v168
	ds_read_b128 v[120:123], v169
	s_barrier
	s_waitcnt lgkmcnt(0)
	s_setprio 1
	s_waitcnt lgkmcnt(0)
	v_mfma_f32_16x16x32_bf16 v[92:95], v[96:99], v[182:185], v[92:95]
	v_mfma_f32_16x16x32_bf16 v[84:87], v[96:99], v[190:193], v[84:87]
	v_mfma_f32_16x16x32_bf16 v[76:79], v[96:99], v[198:201], v[76:79]
	v_mfma_f32_16x16x32_bf16 v[68:71], v[96:99], v[206:209], v[68:71]
	v_mfma_f32_16x16x32_bf16 v[92:95], v[104:107], v[186:189], v[92:95]
	v_mfma_f32_16x16x32_bf16 v[88:91], v[112:115], v[182:185], v[88:91]
	v_mfma_f32_16x16x32_bf16 v[84:87], v[104:107], v[194:197], v[84:87]
	v_mfma_f32_16x16x32_bf16 v[80:83], v[112:115], v[190:193], v[80:83]
	v_mfma_f32_16x16x32_bf16 v[76:79], v[104:107], v[202:205], v[76:79]
	v_mfma_f32_16x16x32_bf16 v[72:75], v[112:115], v[198:201], v[72:75]
	v_mfma_f32_16x16x32_bf16 v[68:71], v[104:107], v[210:213], v[68:71]
	v_mfma_f32_16x16x32_bf16 v[64:67], v[112:115], v[206:209], v[64:67]
	v_mfma_f32_16x16x32_bf16 v[182:185], v[120:123], v[186:189], v[88:91]
	v_mfma_f32_16x16x32_bf16 v[186:189], v[120:123], v[194:197], v[80:83]
	v_mfma_f32_16x16x32_bf16 v[190:193], v[120:123], v[202:205], v[72:75]
	v_mfma_f32_16x16x32_bf16 v[194:197], v[120:123], v[210:213], v[64:67]
	s_setprio 0
	s_barrier
; #define LDA8(dst, b, h) _Pragma("unroll") for (int m = 0; m < 4; ++m) _Pragma("unroll") for (int k = 0; k < 2; ++k) \
;     dst[m][k] = *reinterpret_cast<const bf16x8*>((const char*)SA8(b, h) + la + m * 2048 + k * 1024)
; #define LDB8(dst, b, h) _Pragma("unroll") for (int n = 0; n < 2; ++n) _Pragma("unroll") for (int k = 0; k < 2; ++k) \
;     dst[n][k] = *reinterpret_cast<const bf16x8*>((const char*)SB8(b, h) + lb + n * 2048 + k * 1024)
; #define MMA8(ai, bj, At_, Bx_) do { __builtin_amdgcn_s_setprio(1); \
;     _Pragma("unroll") for (int m = 0; m < 4; ++m) _Pragma("unroll") for (int n = 0; n < 2; ++n) _Pragma("unroll") for (int k = 0; k < 2; ++k) \
;       acc[ai][bj][m][n] = __builtin_amdgcn_mfma_f32_16x16x32_bf16(Bx_[n][k], At_[m][k], acc[ai][bj][m][n], 0, 0, 0); \
;     __builtin_amdgcn_s_setprio(0); } while (0)
; #define WAITV8(n) asm volatile("s_waitcnt vmcnt(" #n ")" ::: "memory")
; #define WAITL8(n) asm volatile("s_waitcnt lgkmcnt(" #n ")" ::: "memory")
; #define BAR8 __builtin_amdgcn_s_barrier()
; template <class Epi>
; DEV void gemm8_phase(const u16* __restrict__ A, int lda, const u16* __restrict__ Bt, int K, int nM, int nN, char* shmc, const Epi& epi) {
;     ...
;       LDA8(At, 0, 1); WAITV8(4); BAR8; WAITL8(0); MMA8(1, 0, At, B0); MMA8(1, 1, At, B1); BAR8; }
;     { LDB8(B0, 1, 0); LDA8(At, 1, 0); WAITV8(2); BAR8; WAITL8(0); MMA8(0, 0, At, B0); BAR8;
	s_nop 1
	ds_read_b128 v[64:67], v157 offset:16384
	ds_read_b128 v[72:75], v157 offset:17408
	ds_read_b128 v[80:83], v157 offset:18432
	ds_read_b128 v[88:91], v157 offset:19456
	ds_read_b128 v[198:201], v157 offset:20480
	ds_read_b128 v[202:205], v157 offset:21504
	ds_read_b128 v[206:209], v157 offset:22528
	ds_read_b128 v[210:213], v157 offset:23552
	s_waitcnt vmcnt(4)
	s_barrier
	s_waitcnt lgkmcnt(0)
	s_setprio 1
	s_waitcnt lgkmcnt(0)
	v_mfma_f32_16x16x32_bf16 v[60:63], v[142:145], v[64:67], v[60:63]
	v_mfma_f32_16x16x32_bf16 v[52:55], v[142:145], v[80:83], v[52:55]
	v_mfma_f32_16x16x32_bf16 v[44:47], v[142:145], v[198:201], v[44:47]
	v_mfma_f32_16x16x32_bf16 v[36:39], v[142:145], v[206:209], v[36:39]
	v_mfma_f32_16x16x32_bf16 v[60:63], v[146:149], v[72:75], v[60:63]
	v_mfma_f32_16x16x32_bf16 v[56:59], v[150:153], v[64:67], v[56:59]
	v_mfma_f32_16x16x32_bf16 v[52:55], v[146:149], v[88:91], v[52:55]
	v_mfma_f32_16x16x32_bf16 v[48:51], v[150:153], v[80:83], v[48:51]
	v_mfma_f32_16x16x32_bf16 v[44:47], v[146:149], v[202:205], v[44:47]
	v_mfma_f32_16x16x32_bf16 v[40:43], v[150:153], v[198:201], v[40:43]
	v_mfma_f32_16x16x32_bf16 v[36:39], v[146:149], v[210:213], v[36:39]
	v_mfma_f32_16x16x32_bf16 v[32:35], v[150:153], v[206:209], v[32:35]
	v_mfma_f32_16x16x32_bf16 v[230:233], v[178:181], v[72:75], v[56:59]
	v_mfma_f32_16x16x32_bf16 v[234:237], v[178:181], v[88:91], v[48:51]
	v_mfma_f32_16x16x32_bf16 v[238:241], v[178:181], v[202:205], v[40:43]
	v_mfma_f32_16x16x32_bf16 v[142:145], v[178:181], v[210:213], v[32:35]
	s_setprio 0
	s_setprio 1
	v_mfma_f32_16x16x32_bf16 v[28:31], v[96:99], v[64:67], v[28:31]
	v_mfma_f32_16x16x32_bf16 v[20:23], v[96:99], v[80:83], v[20:23]
	v_mfma_f32_16x16x32_bf16 v[12:15], v[96:99], v[198:201], v[12:15]
	v_mfma_f32_16x16x32_bf16 v[4:7], v[96:99], v[206:209], v[4:7]
	v_mfma_f32_16x16x32_bf16 v[28:31], v[104:107], v[72:75], v[28:31]
	v_mfma_f32_16x16x32_bf16 v[24:27], v[112:115], v[64:67], v[24:27]
	v_mfma_f32_16x16x32_bf16 v[20:23], v[104:107], v[88:91], v[20:23]
	v_mfma_f32_16x16x32_bf16 v[16:19], v[112:115], v[80:83], v[16:19]
	v_mfma_f32_16x16x32_bf16 v[12:15], v[104:107], v[202:205], v[12:15]
	v_mfma_f32_16x16x32_bf16 v[8:11], v[112:115], v[198:201], v[8:11]
	v_mfma_f32_16x16x32_bf16 v[4:7], v[104:107], v[210:213], v[4:7]
	v_mfma_f32_16x16x32_bf16 v[0:3], v[112:115], v[206:209], v[0:3]
	v_mfma_f32_16x16x32_bf16 v[146:149], v[120:123], v[72:75], v[24:27]
	v_mfma_f32_16x16x32_bf16 v[150:153], v[120:123], v[88:91], v[16:19]
	v_mfma_f32_16x16x32_bf16 v[178:181], v[120:123], v[202:205], v[8:11]
	v_mfma_f32_16x16x32_bf16 v[198:201], v[120:123], v[210:213], v[0:3]
	s_setprio 0
	s_barrier
	s_nop 1
	ds_read_b128 v[0:3], v170
	ds_read_b128 v[8:11], v171
	ds_read_b128 v[16:19], v172
	ds_read_b128 v[24:27], v173
	ds_read_b128 v[32:35], v157 offset:32768
	ds_read_b128 v[40:43], v157 offset:33792
	ds_read_b128 v[48:51], v157 offset:34816
	ds_read_b128 v[56:59], v157 offset:35840
	ds_read_b128 v[64:67], v157 offset:36864
	ds_read_b128 v[202:205], v157 offset:37888
	ds_read_b128 v[206:209], v157 offset:38912
	ds_read_b128 v[210:213], v157 offset:39936
	s_waitcnt vmcnt(2)
	s_barrier
	s_waitcnt lgkmcnt(0)
	s_setprio 1
	s_waitcnt lgkmcnt(0)
	v_mfma_f32_16x16x32_bf16 v[72:75], v[0:3], v[32:35], v[124:127]
	v_mfma_f32_16x16x32_bf16 v[120:123], v[8:11], v[40:43], v[72:75]
	v_mfma_f32_16x16x32_bf16 v[72:75], v[16:19], v[32:35], v[214:217]
	v_mfma_f32_16x16x32_bf16 v[124:127], v[24:27], v[40:43], v[72:75]
	v_mfma_f32_16x16x32_bf16 v[72:75], v[0:3], v[48:51], v[116:119]
	v_mfma_f32_16x16x32_bf16 v[112:115], v[8:11], v[56:59], v[72:75]
	v_mfma_f32_16x16x32_bf16 v[72:75], v[16:19], v[48:51], v[218:221]
	v_mfma_f32_16x16x32_bf16 v[116:119], v[24:27], v[56:59], v[72:75]
	v_mfma_f32_16x16x32_bf16 v[72:75], v[0:3], v[64:67], v[108:111]
	v_mfma_f32_16x16x32_bf16 v[104:107], v[8:11], v[202:205], v[72:75]
	v_mfma_f32_16x16x32_bf16 v[72:75], v[16:19], v[64:67], v[222:225]
	v_mfma_f32_16x16x32_bf16 v[108:111], v[24:27], v[202:205], v[72:75]
	v_mfma_f32_16x16x32_bf16 v[72:75], v[0:3], v[206:209], v[100:103]
	v_mfma_f32_16x16x32_bf16 v[96:99], v[8:11], v[210:213], v[72:75]
	v_mfma_f32_16x16x32_bf16 v[72:75], v[16:19], v[206:209], v[226:229]
	v_mfma_f32_16x16x32_bf16 v[100:103], v[24:27], v[210:213], v[72:75]
	s_setprio 0
	s_barrier
; #define LDA8(dst, b, h) _Pragma("unroll") for (int m = 0; m < 4; ++m) _Pragma("unroll") for (int k = 0; k < 2; ++k) \
;     dst[m][k] = *reinterpret_cast<const bf16x8*>((const char*)SA8(b, h) + la + m * 2048 + k * 1024)
; #define LDB8(dst, b, h) _Pragma("unroll") for (int n = 0; n < 2; ++n) _Pragma("unroll") for (int k = 0; k < 2; ++k) \
;     dst[n][k] = *reinterpret_cast<const bf16x8*>((const char*)SB8(b, h) + lb + n * 2048 + k * 1024)
; #define MMA8(ai, bj, At_, Bx_) do { __builtin_amdgcn_s_setprio(1); \
;     _Pragma("unroll") for (int m = 0; m < 4; ++m) _Pragma("unroll") for (int n = 0; n < 2; ++n) _Pragma("unroll") for (int k = 0; k < 2; ++k) \
;       acc[ai][bj][m][n] = __builtin_amdgcn_mfma_f32_16x16x32_bf16(Bx_[n][k], At_[m][k], acc[ai][bj][m][n], 0, 0, 0); \
;     __builtin_amdgcn_s_setprio(0); } while (0)
; #define WAITV8(n) asm volatile("s_waitcnt vmcnt(" #n ")" ::: "memory")
; #define WAITL8(n) asm volatile("s_waitcnt lgkmcnt(" #n ")" ::: "memory")
; #define BAR8 __builtin_amdgcn_s_barrier()
; template <class Epi>
; DEV void gemm8_phase(const u16* __restrict__ A, int lda, const u16* __restrict__ Bt, int K, int nM, int nN, char* shmc, const Epi& epi) {
;     ...
;       LDB8(B1, 1, 1); WAITV8(0); BAR8; WAITL8(0); MMA8(0, 1, At, B1); BAR8;
;       LDA8(At, 1, 1); BAR8; WAITL8(0); MMA8(1, 0, At, B0); MMA8(1, 1, At, B1); BAR8; }
;     if (wr == 0) BAR8;
	ds_read_b128 v[214:217], v174
	ds_read_b128 v[218:221], v175
	ds_read_b128 v[222:225], v176
	ds_read_b128 v[226:229], v177
	s_waitcnt vmcnt(0)
	s_barrier
	s_waitcnt lgkmcnt(0)
	s_setprio 1
	s_waitcnt lgkmcnt(0)
	v_mfma_f32_16x16x32_bf16 v[72:75], v[214:217], v[32:35], v[92:95]
	v_mfma_f32_16x16x32_bf16 v[32:35], v[222:225], v[32:35], v[182:185]
	v_mfma_f32_16x16x32_bf16 v[92:95], v[226:229], v[40:43], v[32:35]
	v_mfma_f32_16x16x32_bf16 v[32:35], v[214:217], v[48:51], v[84:87]
	v_mfma_f32_16x16x32_bf16 v[80:83], v[218:221], v[56:59], v[32:35]
	v_mfma_f32_16x16x32_bf16 v[32:35], v[222:225], v[48:51], v[186:189]
	v_mfma_f32_16x16x32_bf16 v[84:87], v[226:229], v[56:59], v[32:35]
	v_mfma_f32_16x16x32_bf16 v[32:35], v[214:217], v[64:67], v[76:79]
	v_mfma_f32_16x16x32_bf16 v[88:91], v[218:221], v[40:43], v[72:75]
	v_mfma_f32_16x16x32_bf16 v[72:75], v[218:221], v[202:205], v[32:35]
	v_mfma_f32_16x16x32_bf16 v[32:35], v[222:225], v[64:67], v[190:193]
	v_mfma_f32_16x16x32_bf16 v[76:79], v[226:229], v[202:205], v[32:35]
	v_mfma_f32_16x16x32_bf16 v[32:35], v[214:217], v[206:209], v[68:71]
	v_mfma_f32_16x16x32_bf16 v[64:67], v[218:221], v[210:213], v[32:35]
	v_mfma_f32_16x16x32_bf16 v[32:35], v[222:225], v[206:209], v[194:197]
	v_mfma_f32_16x16x32_bf16 v[68:71], v[226:229], v[210:213], v[32:35]
	s_setprio 0
	s_barrier
	ds_read_b128 v[182:185], v157 offset:49152
	ds_read_b128 v[186:189], v157 offset:50176
	ds_read_b128 v[190:193], v157 offset:51200
	ds_read_b128 v[194:197], v157 offset:52224
	ds_read_b128 v[202:205], v157 offset:53248
	ds_read_b128 v[206:209], v157 offset:54272
	ds_read_b128 v[210:213], v157 offset:55296
	ds_read_b128 v[242:245], v157 offset:56320
	s_barrier
	s_waitcnt lgkmcnt(0)
	s_setprio 1
	s_waitcnt lgkmcnt(0)
	v_mfma_f32_16x16x32_bf16 v[32:35], v[0:3], v[182:185], v[60:63]
	v_mfma_f32_16x16x32_bf16 v[56:59], v[8:11], v[186:189], v[32:35]
	v_mfma_f32_16x16x32_bf16 v[32:35], v[16:19], v[182:185], v[230:233]
	v_mfma_f32_16x16x32_bf16 v[60:63], v[24:27], v[186:189], v[32:35]
	v_mfma_f32_16x16x32_bf16 v[32:35], v[0:3], v[190:193], v[52:55]
	v_mfma_f32_16x16x32_bf16 v[48:51], v[8:11], v[194:197], v[32:35]
	v_mfma_f32_16x16x32_bf16 v[32:35], v[16:19], v[190:193], v[234:237]
	v_mfma_f32_16x16x32_bf16 v[52:55], v[24:27], v[194:197], v[32:35]
	v_mfma_f32_16x16x32_bf16 v[32:35], v[0:3], v[202:205], v[44:47]
	v_mfma_f32_16x16x32_bf16 v[40:43], v[8:11], v[206:209], v[32:35]
	v_mfma_f32_16x16x32_bf16 v[32:35], v[16:19], v[202:205], v[238:241]
	v_mfma_f32_16x16x32_bf16 v[0:3], v[0:3], v[210:213], v[36:39]
	v_mfma_f32_16x16x32_bf16 v[44:47], v[24:27], v[206:209], v[32:35]
	v_mfma_f32_16x16x32_bf16 v[32:35], v[8:11], v[242:245], v[0:3]
	v_mfma_f32_16x16x32_bf16 v[0:3], v[16:19], v[210:213], v[142:145]
	v_mfma_f32_16x16x32_bf16 v[36:39], v[24:27], v[242:245], v[0:3]
	s_setprio 0
	s_setprio 1
	v_mfma_f32_16x16x32_bf16 v[0:3], v[214:217], v[182:185], v[28:31]
	v_mfma_f32_16x16x32_bf16 v[24:27], v[218:221], v[186:189], v[0:3]
	v_mfma_f32_16x16x32_bf16 v[0:3], v[222:225], v[182:185], v[146:149]
	v_mfma_f32_16x16x32_bf16 v[28:31], v[226:229], v[186:189], v[0:3]
	v_mfma_f32_16x16x32_bf16 v[0:3], v[214:217], v[190:193], v[20:23]
	v_mfma_f32_16x16x32_bf16 v[16:19], v[218:221], v[194:197], v[0:3]
	v_mfma_f32_16x16x32_bf16 v[0:3], v[222:225], v[190:193], v[150:153]
	v_mfma_f32_16x16x32_bf16 v[20:23], v[226:229], v[194:197], v[0:3]
	v_mfma_f32_16x16x32_bf16 v[0:3], v[214:217], v[202:205], v[12:15]
	v_mfma_f32_16x16x32_bf16 v[8:11], v[218:221], v[206:209], v[0:3]
	v_mfma_f32_16x16x32_bf16 v[0:3], v[222:225], v[202:205], v[178:181]
	v_mfma_f32_16x16x32_bf16 v[12:15], v[226:229], v[206:209], v[0:3]
	v_mfma_f32_16x16x32_bf16 v[0:3], v[214:217], v[210:213], v[4:7]
	v_mfma_f32_16x16x32_bf16 v[4:7], v[222:225], v[210:213], v[198:201]
	v_mfma_f32_16x16x32_bf16 v[0:3], v[218:221], v[242:245], v[0:3]
	v_mfma_f32_16x16x32_bf16 v[4:7], v[226:229], v[242:245], v[4:7]
	s_setprio 0
	s_andn2_b64 vcc, exec, s[10:11]
	s_barrier
	s_cbranch_vccnz .LBB0_1628
	s_barrier

; #define SBAR() __builtin_amdgcn_sched_barrier(0)
; #define LDA8(dst, b, h) _Pragma("unroll") for (int m = 0; m < 4; ++m) _Pragma("unroll") for (int k = 0; k < 2; ++k) \
;     dst[m][k] = *reinterpret_cast<const bf16x8*>((const char*)SA8(b, h) + la + m * 2048 + k * 1024)
; #define LDB8(dst, b, h) _Pragma("unroll") for (int n = 0; n < 2; ++n) _Pragma("unroll") for (int k = 0; k < 2; ++k) \
;     dst[n][k] = *reinterpret_cast<const bf16x8*>((const char*)SB8(b, h) + lb + n * 2048 + k * 1024)
; #define MMA8(ai, bj, At_, Bx_) do { __builtin_amdgcn_s_setprio(1); \
;     _Pragma("unroll") for (int m = 0; m < 4; ++m) _Pragma("unroll") for (int n = 0; n < 2; ++n) _Pragma("unroll") for (int k = 0; k < 2; ++k) \
;       acc[ai][bj][m][n] = __builtin_amdgcn_mfma_f32_16x16x32_bf16(Bx_[n][k], At_[m][k], acc[ai][bj][m][n], 0, 0, 0); \
;     __builtin_amdgcn_s_setprio(0); } while (0)
; #define WAITV8(n) asm volatile("s_waitcnt vmcnt(" #n ")" ::: "memory")
; #define WAITL8(n) asm volatile("s_waitcnt lgkmcnt(" #n ")" ::: "memory")
; #define BAR8 __builtin_amdgcn_s_barrier()
; template <class Epi>
; DEV void gemm8_phase(const u16* __restrict__ A, int lda, const u16* __restrict__ Bt, int K, int nM, int nN, char* shmc, const Epi& epi) {
;     ...
;       LDB8(B0, 0, 0); SBAR(); LDA8(At, 0, 0); STAGE8(SA8(1, 1), A, lda, brow + HALF, kt + 1);
;       WAITL8(8); BAR8; WAITL8(0); MMA8(0, 0, At, B0); BAR8; SBAR();
;       LDB8(B1, 0, 1); STAGE8(SB8(0, 0), Bt, K, bcol, kt + 2);
;       BAR8; WAITL8(0); MMA8(0, 1, At, B1); BAR8;
;       LDA8(At, 0, 1); STAGE8(SA8(0, 0), A, lda, brow, kt + 2);
;       BAR8; WAITL8(0); MMA8(1, 0, At, B0); BAR8; SBAR();
;       STAGE8(SB8(0, 1), Bt, K, bcol + HALF, kt + 2);
;       WAITV8(6); BAR8; MMA8(1, 1, At, B1); BAR8;
.LBB0_1648:
	ds_read_b128 v[144:147], v154
	ds_read_b128 v[174:177], v155
	ds_read_b128 v[178:181], v156
	ds_read_b128 v[182:185], v157
	v_add_u32_e32 v143, v151, v132
	s_mov_b32 m0, s34
	v_add_u32_e32 v148, 0x80, v143
	ds_read_b128 v[186:189], v150
	ds_read_b128 v[190:193], v150 offset:1024
	ds_read_b128 v[194:197], v150 offset:2048
	ds_read_b128 v[198:201], v150 offset:3072
	ds_read_b128 v[202:205], v150 offset:4096
	ds_read_b128 v[206:209], v150 offset:5120
	ds_read_b128 v[210:213], v150 offset:6144
	ds_read_b128 v[214:217], v150 offset:7168
	global_load_lds_dwordx4 v148, s[14:15]
	v_add_u32_e32 v148, v151, v142
	v_add_u32_e32 v149, 0x80, v148
	s_mov_b32 m0, s35
	s_nop 0
	global_load_lds_dwordx4 v149, s[14:15]
	s_waitcnt lgkmcnt(8)
	s_barrier
	s_waitcnt lgkmcnt(7)
	s_setprio 1
	v_mfma_f32_16x16x32_bf16 v[124:127], v[144:147], v[186:189], v[124:127]
	v_mfma_f32_16x16x32_bf16 v[120:123], v[178:181], v[186:189], v[120:123]
	s_waitcnt lgkmcnt(5)
	v_mfma_f32_16x16x32_bf16 v[116:119], v[144:147], v[194:197], v[116:119]
	v_mfma_f32_16x16x32_bf16 v[112:115], v[178:181], v[194:197], v[112:115]
	s_waitcnt lgkmcnt(3)
	v_mfma_f32_16x16x32_bf16 v[108:111], v[144:147], v[202:205], v[108:111]
	v_mfma_f32_16x16x32_bf16 v[104:107], v[178:181], v[202:205], v[104:107]
	s_waitcnt lgkmcnt(1)
	v_mfma_f32_16x16x32_bf16 v[100:103], v[144:147], v[210:213], v[100:103]
	v_mfma_f32_16x16x32_bf16 v[96:99], v[178:181], v[210:213], v[96:99]
	v_mfma_f32_16x16x32_bf16 v[124:127], v[174:177], v[190:193], v[124:127]
	v_mfma_f32_16x16x32_bf16 v[120:123], v[182:185], v[190:193], v[120:123]
	v_mfma_f32_16x16x32_bf16 v[116:119], v[174:177], v[198:201], v[116:119]
	v_mfma_f32_16x16x32_bf16 v[112:115], v[182:185], v[198:201], v[112:115]
	v_mfma_f32_16x16x32_bf16 v[108:111], v[174:177], v[206:209], v[108:111]
	v_mfma_f32_16x16x32_bf16 v[104:107], v[182:185], v[206:209], v[104:107]
	s_waitcnt lgkmcnt(0)
	v_mfma_f32_16x16x32_bf16 v[100:103], v[174:177], v[214:217], v[100:103]
	v_mfma_f32_16x16x32_bf16 v[96:99], v[182:185], v[214:217], v[96:99]
	s_setprio 0
	s_barrier
	s_mov_b32 m0, s19
	v_add_u32_e32 v149, 0x100, v143
	ds_read_b128 v[218:221], v158
	ds_read_b128 v[222:225], v159
	ds_read_b128 v[226:229], v160
	ds_read_b128 v[230:233], v161
	global_load_lds_dwordx4 v149, s[6:7]
	v_add_u32_e32 v173, 0x100, v148
	s_mov_b32 m0, s20
	s_nop 0
	global_load_lds_dwordx4 v173, s[6:7]
	s_barrier
	s_waitcnt lgkmcnt(3)
	s_setprio 1
	v_mfma_f32_16x16x32_bf16 v[92:95], v[218:221], v[186:189], v[92:95]
	s_waitcnt lgkmcnt(1)
	v_mfma_f32_16x16x32_bf16 v[88:91], v[226:229], v[186:189], v[88:91]
	v_mfma_f32_16x16x32_bf16 v[84:87], v[218:221], v[194:197], v[84:87]
	v_mfma_f32_16x16x32_bf16 v[80:83], v[226:229], v[194:197], v[80:83]
	v_mfma_f32_16x16x32_bf16 v[76:79], v[218:221], v[202:205], v[76:79]
	v_mfma_f32_16x16x32_bf16 v[72:75], v[226:229], v[202:205], v[72:75]
	v_mfma_f32_16x16x32_bf16 v[68:71], v[218:221], v[210:213], v[68:71]
	v_mfma_f32_16x16x32_bf16 v[64:67], v[226:229], v[210:213], v[64:67]
	v_mfma_f32_16x16x32_bf16 v[92:95], v[222:225], v[190:193], v[92:95]
	s_waitcnt lgkmcnt(0)
	v_mfma_f32_16x16x32_bf16 v[88:91], v[230:233], v[190:193], v[88:91]
	v_mfma_f32_16x16x32_bf16 v[84:87], v[222:225], v[198:201], v[84:87]
	v_mfma_f32_16x16x32_bf16 v[80:83], v[230:233], v[198:201], v[80:83]
	v_mfma_f32_16x16x32_bf16 v[76:79], v[222:225], v[206:209], v[76:79]
	v_mfma_f32_16x16x32_bf16 v[72:75], v[230:233], v[206:209], v[72:75]
	v_mfma_f32_16x16x32_bf16 v[68:71], v[222:225], v[214:217], v[68:71]
	v_mfma_f32_16x16x32_bf16 v[64:67], v[230:233], v[214:217], v[64:67]
	s_setprio 0
	s_mov_b32 m0, s3
	s_barrier
	ds_read_b128 v[186:189], v150 offset:16384
	ds_read_b128 v[190:193], v150 offset:17408
	ds_read_b128 v[194:197], v150 offset:18432
	ds_read_b128 v[198:201], v150 offset:19456
	ds_read_b128 v[202:205], v150 offset:20480
	ds_read_b128 v[206:209], v150 offset:21504
	ds_read_b128 v[210:213], v150 offset:22528
	ds_read_b128 v[214:217], v150 offset:23552
	global_load_lds_dwordx4 v149, s[12:13]
	s_mov_b32 m0, s21
	s_nop 0
	global_load_lds_dwordx4 v173, s[12:13]
	s_barrier
	s_waitcnt lgkmcnt(7)
	s_setprio 1
	v_mfma_f32_16x16x32_bf16 v[60:63], v[144:147], v[186:189], v[60:63]
	v_mfma_f32_16x16x32_bf16 v[56:59], v[178:181], v[186:189], v[56:59]
	s_waitcnt lgkmcnt(5)
	v_mfma_f32_16x16x32_bf16 v[52:55], v[144:147], v[194:197], v[52:55]
	v_mfma_f32_16x16x32_bf16 v[48:51], v[178:181], v[194:197], v[48:51]
	s_waitcnt lgkmcnt(3)
	v_mfma_f32_16x16x32_bf16 v[44:47], v[144:147], v[202:205], v[44:47]
	v_mfma_f32_16x16x32_bf16 v[40:43], v[178:181], v[202:205], v[40:43]
	s_waitcnt lgkmcnt(1)
	v_mfma_f32_16x16x32_bf16 v[36:39], v[144:147], v[210:213], v[36:39]
	v_mfma_f32_16x16x32_bf16 v[32:35], v[178:181], v[210:213], v[32:35]
	v_mfma_f32_16x16x32_bf16 v[60:63], v[174:177], v[190:193], v[60:63]
	v_mfma_f32_16x16x32_bf16 v[56:59], v[182:185], v[190:193], v[56:59]
	v_mfma_f32_16x16x32_bf16 v[52:55], v[174:177], v[198:201], v[52:55]
	v_mfma_f32_16x16x32_bf16 v[48:51], v[182:185], v[198:201], v[48:51]
	v_mfma_f32_16x16x32_bf16 v[44:47], v[174:177], v[206:209], v[44:47]
	v_mfma_f32_16x16x32_bf16 v[40:43], v[182:185], v[206:209], v[40:43]
	s_waitcnt lgkmcnt(0)
	v_mfma_f32_16x16x32_bf16 v[36:39], v[174:177], v[214:217], v[36:39]
	v_mfma_f32_16x16x32_bf16 v[32:35], v[182:185], v[214:217], v[32:35]
	s_setprio 0
	s_barrier
	s_mov_b32 m0, s22
	s_nop 0
	global_load_lds_dwordx4 v149, s[16:17]
	s_mov_b32 m0, s23
	s_nop 0
	global_load_lds_dwordx4 v173, s[16:17]
	s_waitcnt vmcnt(6)
	s_barrier
; #define SBAR() __builtin_amdgcn_sched_barrier(0)
; #define LDA8(dst, b, h) _Pragma("unroll") for (int m = 0; m < 4; ++m) _Pragma("unroll") for (int k = 0; k < 2; ++k) \
;     dst[m][k] = *reinterpret_cast<const bf16x8*>((const char*)SA8(b, h) + la + m * 2048 + k * 1024)
; #define LDB8(dst, b, h) _Pragma("unroll") for (int n = 0; n < 2; ++n) _Pragma("unroll") for (int k = 0; k < 2; ++k) \
;     dst[n][k] = *reinterpret_cast<const bf16x8*>((const char*)SB8(b, h) + lb + n * 2048 + k * 1024)
; #define MMA8(ai, bj, At_, Bx_) do { __builtin_amdgcn_s_setprio(1); \
;     _Pragma("unroll") for (int m = 0; m < 4; ++m) _Pragma("unroll") for (int n = 0; n < 2; ++n) _Pragma("unroll") for (int k = 0; k < 2; ++k) \
;       acc[ai][bj][m][n] = __builtin_amdgcn_mfma_f32_16x16x32_bf16(Bx_[n][k], At_[m][k], acc[ai][bj][m][n], 0, 0, 0); \
;     __builtin_amdgcn_s_setprio(0); } while (0)
; #define WAITV8(n) asm volatile("s_waitcnt vmcnt(" #n ")" ::: "memory")
; #define WAITL8(n) asm volatile("s_waitcnt lgkmcnt(" #n ")" ::: "memory")
; #define BAR8 __builtin_amdgcn_s_barrier()
; template <class Epi>
; DEV void gemm8_phase(const u16* __restrict__ A, int lda, const u16* __restrict__ Bt, int K, int nM, int nN, char* shmc, const Epi& epi) {
;     ...
;       WAITV8(6); BAR8; MMA8(1, 1, At, B1); BAR8;
;       LDB8(B0, 1, 0); SBAR(); LDA8(At, 1, 0); STAGE8(SA8(0, 1), A, lda, brow + HALF, kt + 2);
;       WAITL8(8); BAR8; WAITL8(0); MMA8(0, 0, At, B0); BAR8; SBAR();
;       LDB8(B1, 1, 1); STAGE8(SB8(1, 0), Bt, K, bcol, kt + 3);
;       BAR8; WAITL8(0); MMA8(0, 1, At, B1); BAR8;
;       LDA8(At, 1, 1); STAGE8(SA8(1, 0), A, lda, brow, kt + 3);
	s_setprio 1
	v_mfma_f32_16x16x32_bf16 v[28:31], v[218:221], v[186:189], v[28:31]
	v_mfma_f32_16x16x32_bf16 v[24:27], v[226:229], v[186:189], v[24:27]
	v_mfma_f32_16x16x32_bf16 v[20:23], v[218:221], v[194:197], v[20:23]
	v_mfma_f32_16x16x32_bf16 v[16:19], v[226:229], v[194:197], v[16:19]
	v_mfma_f32_16x16x32_bf16 v[12:15], v[218:221], v[202:205], v[12:15]
	v_mfma_f32_16x16x32_bf16 v[8:11], v[226:229], v[202:205], v[8:11]
	v_mfma_f32_16x16x32_bf16 v[4:7], v[218:221], v[210:213], v[4:7]
	v_mfma_f32_16x16x32_bf16 v[0:3], v[226:229], v[210:213], v[0:3]
	v_mfma_f32_16x16x32_bf16 v[28:31], v[222:225], v[190:193], v[28:31]
	v_mfma_f32_16x16x32_bf16 v[24:27], v[230:233], v[190:193], v[24:27]
	v_mfma_f32_16x16x32_bf16 v[20:23], v[222:225], v[198:201], v[20:23]
	v_mfma_f32_16x16x32_bf16 v[16:19], v[230:233], v[198:201], v[16:19]
	v_mfma_f32_16x16x32_bf16 v[12:15], v[222:225], v[206:209], v[12:15]
	v_mfma_f32_16x16x32_bf16 v[8:11], v[230:233], v[206:209], v[8:11]
	v_mfma_f32_16x16x32_bf16 v[4:7], v[222:225], v[214:217], v[4:7]
	v_mfma_f32_16x16x32_bf16 v[0:3], v[230:233], v[214:217], v[0:3]
	s_setprio 0
	s_barrier
	ds_read_b128 v[144:147], v162
	ds_read_b128 v[174:177], v163
	ds_read_b128 v[178:181], v166
	ds_read_b128 v[182:185], v167
	s_mov_b32 m0, s24
	ds_read_b128 v[186:189], v150 offset:32768
	ds_read_b128 v[190:193], v150 offset:33792
	ds_read_b128 v[194:197], v150 offset:34816
	ds_read_b128 v[198:201], v150 offset:35840
	ds_read_b128 v[202:205], v150 offset:36864
	ds_read_b128 v[206:209], v150 offset:37888
	ds_read_b128 v[210:213], v150 offset:38912
	ds_read_b128 v[214:217], v150 offset:39936
	global_load_lds_dwordx4 v149, s[14:15]
	s_mov_b32 m0, s25
	s_nop 0
	global_load_lds_dwordx4 v173, s[14:15]
	s_waitcnt lgkmcnt(8)
	s_barrier
	s_waitcnt lgkmcnt(7)
	s_setprio 1
	v_mfma_f32_16x16x32_bf16 v[124:127], v[144:147], v[186:189], v[124:127]
	v_mfma_f32_16x16x32_bf16 v[120:123], v[178:181], v[186:189], v[120:123]
	s_waitcnt lgkmcnt(5)
	v_mfma_f32_16x16x32_bf16 v[116:119], v[144:147], v[194:197], v[116:119]
	v_mfma_f32_16x16x32_bf16 v[112:115], v[178:181], v[194:197], v[112:115]
	s_waitcnt lgkmcnt(3)
	v_mfma_f32_16x16x32_bf16 v[108:111], v[144:147], v[202:205], v[108:111]
	v_mfma_f32_16x16x32_bf16 v[104:107], v[178:181], v[202:205], v[104:107]
	s_waitcnt lgkmcnt(1)
	v_mfma_f32_16x16x32_bf16 v[100:103], v[144:147], v[210:213], v[100:103]
	v_mfma_f32_16x16x32_bf16 v[96:99], v[178:181], v[210:213], v[96:99]
	v_mfma_f32_16x16x32_bf16 v[124:127], v[174:177], v[190:193], v[124:127]
	v_mfma_f32_16x16x32_bf16 v[120:123], v[182:185], v[190:193], v[120:123]
	v_mfma_f32_16x16x32_bf16 v[116:119], v[174:177], v[198:201], v[116:119]
	v_mfma_f32_16x16x32_bf16 v[112:115], v[182:185], v[198:201], v[112:115]
	v_mfma_f32_16x16x32_bf16 v[108:111], v[174:177], v[206:209], v[108:111]
	v_mfma_f32_16x16x32_bf16 v[104:107], v[182:185], v[206:209], v[104:107]
	s_waitcnt lgkmcnt(0)
	v_mfma_f32_16x16x32_bf16 v[100:103], v[174:177], v[214:217], v[100:103]
	v_mfma_f32_16x16x32_bf16 v[96:99], v[182:185], v[214:217], v[96:99]
	s_setprio 0
	s_barrier
	s_mov_b32 m0, s26
	v_add_u32_e32 v143, 0x180, v143
	ds_read_b128 v[218:221], v168
	ds_read_b128 v[222:225], v169
	ds_read_b128 v[226:229], v170
	ds_read_b128 v[230:233], v171
	global_load_lds_dwordx4 v143, s[6:7]
	v_add_u32_e32 v148, 0x180, v148
	s_mov_b32 m0, s27
	s_nop 0
	global_load_lds_dwordx4 v148, s[6:7]
	s_barrier
	s_waitcnt lgkmcnt(3)
	s_setprio 1
	v_mfma_f32_16x16x32_bf16 v[92:95], v[218:221], v[186:189], v[92:95]
	s_waitcnt lgkmcnt(1)
	v_mfma_f32_16x16x32_bf16 v[88:91], v[226:229], v[186:189], v[88:91]
	v_mfma_f32_16x16x32_bf16 v[84:87], v[218:221], v[194:197], v[84:87]
	v_mfma_f32_16x16x32_bf16 v[80:83], v[226:229], v[194:197], v[80:83]
	v_mfma_f32_16x16x32_bf16 v[76:79], v[218:221], v[202:205], v[76:79]
	v_mfma_f32_16x16x32_bf16 v[72:75], v[226:229], v[202:205], v[72:75]
	v_mfma_f32_16x16x32_bf16 v[68:71], v[218:221], v[210:213], v[68:71]
	v_mfma_f32_16x16x32_bf16 v[64:67], v[226:229], v[210:213], v[64:67]
	v_mfma_f32_16x16x32_bf16 v[92:95], v[222:225], v[190:193], v[92:95]
	s_waitcnt lgkmcnt(0)
	v_mfma_f32_16x16x32_bf16 v[88:91], v[230:233], v[190:193], v[88:91]
	v_mfma_f32_16x16x32_bf16 v[84:87], v[222:225], v[198:201], v[84:87]
	v_mfma_f32_16x16x32_bf16 v[80:83], v[230:233], v[198:201], v[80:83]
	v_mfma_f32_16x16x32_bf16 v[76:79], v[222:225], v[206:209], v[76:79]
	v_mfma_f32_16x16x32_bf16 v[72:75], v[230:233], v[206:209], v[72:75]
	v_mfma_f32_16x16x32_bf16 v[68:71], v[222:225], v[214:217], v[68:71]
	v_mfma_f32_16x16x32_bf16 v[64:67], v[230:233], v[214:217], v[64:67]
	s_setprio 0
	s_mov_b32 m0, s28
	s_barrier
	ds_read_b128 v[186:189], v150 offset:49152
	ds_read_b128 v[190:193], v150 offset:50176
	ds_read_b128 v[194:197], v150 offset:51200
	ds_read_b128 v[198:201], v150 offset:52224
	ds_read_b128 v[202:205], v150 offset:53248
	ds_read_b128 v[206:209], v150 offset:54272
	ds_read_b128 v[210:213], v150 offset:55296
	ds_read_b128 v[214:217], v150 offset:56320
	global_load_lds_dwordx4 v143, s[12:13]
	s_mov_b32 m0, s29
	s_nop 0
	global_load_lds_dwordx4 v148, s[12:13]
	s_barrier
; #define SBAR() __builtin_amdgcn_sched_barrier(0)
; #define LDA8(dst, b, h) _Pragma("unroll") for (int m = 0; m < 4; ++m) _Pragma("unroll") for (int k = 0; k < 2; ++k) \
;     dst[m][k] = *reinterpret_cast<const bf16x8*>((const char*)SA8(b, h) + la + m * 2048 + k * 1024)
; #define LDB8(dst, b, h) _Pragma("unroll") for (int n = 0; n < 2; ++n) _Pragma("unroll") for (int k = 0; k < 2; ++k) \
;     dst[n][k] = *reinterpret_cast<const bf16x8*>((const char*)SB8(b, h) + lb + n * 2048 + k * 1024)
; #define MMA8(ai, bj, At_, Bx_) do { __builtin_amdgcn_s_setprio(1); \
;     _Pragma("unroll") for (int m = 0; m < 4; ++m) _Pragma("unroll") for (int n = 0; n < 2; ++n) _Pragma("unroll") for (int k = 0; k < 2; ++k) \
;       acc[ai][bj][m][n] = __builtin_amdgcn_mfma_f32_16x16x32_bf16(Bx_[n][k], At_[m][k], acc[ai][bj][m][n], 0, 0, 0); \
;     __builtin_amdgcn_s_setprio(0); } while (0)
; #define WAITV8(n) asm volatile("s_waitcnt vmcnt(" #n ")" ::: "memory")
; #define WAITL8(n) asm volatile("s_waitcnt lgkmcnt(" #n ")" ::: "memory")
; #define BAR8 __builtin_amdgcn_s_barrier()
; template <class Epi>
; DEV void gemm8_phase(const u16* __restrict__ A, int lda, const u16* __restrict__ Bt, int K, int nM, int nN, char* shmc, const Epi& epi) {
;     ...
;       BAR8; WAITL8(0); MMA8(1, 0, At, B0); BAR8; SBAR();
;       STAGE8(SB8(1, 1), Bt, K, bcol + HALF, kt + 3);
;       WAITV8(6); BAR8; MMA8(1, 1, At, B1); BAR8;
;     }
;     { LDB8(B0, 0, 0); LDA8(At, 0, 0); STAGE8(SA8(1, 1), A, lda, brow + HALF, nt - 1);
;       BAR8; WAITL8(0); MMA8(0, 0, At, B0); BAR8;
;       LDB8(B1, 0, 1); BAR8; WAITL8(0); MMA8(0, 1, At, B1); BAR8;
	s_waitcnt lgkmcnt(7)
	s_setprio 1
	v_mfma_f32_16x16x32_bf16 v[60:63], v[144:147], v[186:189], v[60:63]
	v_mfma_f32_16x16x32_bf16 v[56:59], v[178:181], v[186:189], v[56:59]
	s_waitcnt lgkmcnt(5)
	v_mfma_f32_16x16x32_bf16 v[52:55], v[144:147], v[194:197], v[52:55]
	v_mfma_f32_16x16x32_bf16 v[48:51], v[178:181], v[194:197], v[48:51]
	s_waitcnt lgkmcnt(3)
	v_mfma_f32_16x16x32_bf16 v[44:47], v[144:147], v[202:205], v[44:47]
	v_mfma_f32_16x16x32_bf16 v[40:43], v[178:181], v[202:205], v[40:43]
	s_waitcnt lgkmcnt(1)
	v_mfma_f32_16x16x32_bf16 v[36:39], v[144:147], v[210:213], v[36:39]
	v_mfma_f32_16x16x32_bf16 v[32:35], v[178:181], v[210:213], v[32:35]
	v_mfma_f32_16x16x32_bf16 v[60:63], v[174:177], v[190:193], v[60:63]
	v_mfma_f32_16x16x32_bf16 v[56:59], v[182:185], v[190:193], v[56:59]
	v_mfma_f32_16x16x32_bf16 v[52:55], v[174:177], v[198:201], v[52:55]
	v_mfma_f32_16x16x32_bf16 v[48:51], v[182:185], v[198:201], v[48:51]
	v_mfma_f32_16x16x32_bf16 v[44:47], v[174:177], v[206:209], v[44:47]
	v_mfma_f32_16x16x32_bf16 v[40:43], v[182:185], v[206:209], v[40:43]
	s_waitcnt lgkmcnt(0)
	v_mfma_f32_16x16x32_bf16 v[36:39], v[174:177], v[214:217], v[36:39]
	v_mfma_f32_16x16x32_bf16 v[32:35], v[182:185], v[214:217], v[32:35]
	s_setprio 0
	s_barrier
	s_mov_b32 m0, s30
	s_nop 0
	global_load_lds_dwordx4 v143, s[16:17]
	s_mov_b32 m0, s31
	s_nop 0
	global_load_lds_dwordx4 v148, s[16:17]
	s_waitcnt vmcnt(6)
	s_barrier
	s_setprio 1
	v_mfma_f32_16x16x32_bf16 v[28:31], v[218:221], v[186:189], v[28:31]
	v_mfma_f32_16x16x32_bf16 v[24:27], v[226:229], v[186:189], v[24:27]
	v_mfma_f32_16x16x32_bf16 v[20:23], v[218:221], v[194:197], v[20:23]
	v_mfma_f32_16x16x32_bf16 v[16:19], v[226:229], v[194:197], v[16:19]
	v_mfma_f32_16x16x32_bf16 v[12:15], v[218:221], v[202:205], v[12:15]
	v_mfma_f32_16x16x32_bf16 v[8:11], v[226:229], v[202:205], v[8:11]
	v_mfma_f32_16x16x32_bf16 v[4:7], v[218:221], v[210:213], v[4:7]
	v_mfma_f32_16x16x32_bf16 v[0:3], v[226:229], v[210:213], v[0:3]
	v_mfma_f32_16x16x32_bf16 v[28:31], v[222:225], v[190:193], v[28:31]
	v_mfma_f32_16x16x32_bf16 v[24:27], v[230:233], v[190:193], v[24:27]
	v_mfma_f32_16x16x32_bf16 v[20:23], v[222:225], v[198:201], v[20:23]
	v_mfma_f32_16x16x32_bf16 v[16:19], v[230:233], v[198:201], v[16:19]
	v_mfma_f32_16x16x32_bf16 v[12:15], v[222:225], v[206:209], v[12:15]
	v_mfma_f32_16x16x32_bf16 v[8:11], v[230:233], v[206:209], v[8:11]
	v_mfma_f32_16x16x32_bf16 v[4:7], v[222:225], v[214:217], v[4:7]
	v_mfma_f32_16x16x32_bf16 v[0:3], v[230:233], v[214:217], v[0:3]
	s_setprio 0
	s_add_i32 s36, s36, 2
	v_add_u32_e32 v142, 0x100, v142
	s_cmpk_gt_u32 s36, 0x53
	v_add_u32_e32 v132, 0x100, v132
	s_barrier
	s_cbranch_scc0 .LBB0_1648
	s_mov_b32 m0, s34
	v_lshl_add_u64 v[214:215], s[14:15], 0, v[138:139]
	ds_read_b128 v[142:145], v154
	ds_read_b128 v[146:149], v155
	ds_read_b128 v[174:177], v156
	ds_read_b128 v[178:181], v157
	ds_read_b128 v[182:185], v150
	ds_read_b128 v[186:189], v150 offset:1024
	ds_read_b128 v[190:193], v150 offset:2048
	ds_read_b128 v[194:197], v150 offset:3072
	ds_read_b128 v[198:201], v150 offset:4096
	ds_read_b128 v[202:205], v150 offset:5120
	ds_read_b128 v[206:209], v150 offset:6144
	ds_read_b128 v[210:213], v150 offset:7168
	global_load_lds_dwordx4 v[214:215], off
	v_lshl_add_u64 v[214:215], s[14:15], 0, v[140:141]
	s_mov_b32 m0, s35
	s_nop 0
	global_load_lds_dwordx4 v[214:215], off
	s_barrier
	s_waitcnt lgkmcnt(0)
	s_setprio 1
	s_waitcnt lgkmcnt(0)
	v_mfma_f32_16x16x32_bf16 v[124:127], v[142:145], v[182:185], v[124:127]
	v_mfma_f32_16x16x32_bf16 v[120:123], v[174:177], v[182:185], v[120:123]
	v_mfma_f32_16x16x32_bf16 v[116:119], v[142:145], v[190:193], v[116:119]
	v_mfma_f32_16x16x32_bf16 v[112:115], v[174:177], v[190:193], v[112:115]
	v_mfma_f32_16x16x32_bf16 v[108:111], v[142:145], v[198:201], v[108:111]
	v_mfma_f32_16x16x32_bf16 v[104:107], v[174:177], v[198:201], v[104:107]
	v_mfma_f32_16x16x32_bf16 v[100:103], v[142:145], v[206:209], v[100:103]
	v_mfma_f32_16x16x32_bf16 v[96:99], v[174:177], v[206:209], v[96:99]
	v_mfma_f32_16x16x32_bf16 v[124:127], v[146:149], v[186:189], v[124:127]
	v_mfma_f32_16x16x32_bf16 v[120:123], v[178:181], v[186:189], v[120:123]
	v_mfma_f32_16x16x32_bf16 v[116:119], v[146:149], v[194:197], v[116:119]
	v_mfma_f32_16x16x32_bf16 v[112:115], v[178:181], v[194:197], v[112:115]
	v_mfma_f32_16x16x32_bf16 v[108:111], v[146:149], v[202:205], v[108:111]
	v_mfma_f32_16x16x32_bf16 v[104:107], v[178:181], v[202:205], v[104:107]
	v_mfma_f32_16x16x32_bf16 v[100:103], v[146:149], v[210:213], v[100:103]
	v_mfma_f32_16x16x32_bf16 v[96:99], v[178:181], v[210:213], v[96:99]
	s_setprio 0
	s_barrier
	ds_read_b128 v[214:217], v158
	ds_read_b128 v[218:221], v159
	ds_read_b128 v[222:225], v160
	ds_read_b128 v[226:229], v161
	s_barrier
	s_waitcnt lgkmcnt(0)
	s_setprio 1
	s_waitcnt lgkmcnt(0)
	v_mfma_f32_16x16x32_bf16 v[92:95], v[214:217], v[182:185], v[92:95]
	v_mfma_f32_16x16x32_bf16 v[88:91], v[222:225], v[182:185], v[88:91]
	v_mfma_f32_16x16x32_bf16 v[84:87], v[214:217], v[190:193], v[84:87]
	v_mfma_f32_16x16x32_bf16 v[80:83], v[222:225], v[190:193], v[80:83]
	v_mfma_f32_16x16x32_bf16 v[76:79], v[214:217], v[198:201], v[76:79]
	v_mfma_f32_16x16x32_bf16 v[72:75], v[222:225], v[198:201], v[72:75]
	v_mfma_f32_16x16x32_bf16 v[68:71], v[214:217], v[206:209], v[68:71]
	v_mfma_f32_16x16x32_bf16 v[64:67], v[222:225], v[206:209], v[64:67]
	v_mfma_f32_16x16x32_bf16 v[92:95], v[218:221], v[186:189], v[92:95]
	v_mfma_f32_16x16x32_bf16 v[88:91], v[226:229], v[186:189], v[88:91]
	v_mfma_f32_16x16x32_bf16 v[84:87], v[218:221], v[194:197], v[84:87]
	v_mfma_f32_16x16x32_bf16 v[80:83], v[226:229], v[194:197], v[80:83]
	v_mfma_f32_16x16x32_bf16 v[76:79], v[218:221], v[202:205], v[76:79]
	v_mfma_f32_16x16x32_bf16 v[72:75], v[226:229], v[202:205], v[72:75]
	v_mfma_f32_16x16x32_bf16 v[68:71], v[218:221], v[210:213], v[68:71]
	v_mfma_f32_16x16x32_bf16 v[64:67], v[226:229], v[210:213], v[64:67]
	s_setprio 0
	s_barrier
; #define LDA8(dst, b, h) _Pragma("unroll") for (int m = 0; m < 4; ++m) _Pragma("unroll") for (int k = 0; k < 2; ++k) \
;     dst[m][k] = *reinterpret_cast<const bf16x8*>((const char*)SA8(b, h) + la + m * 2048 + k * 1024)
; #define LDB8(dst, b, h) _Pragma("unroll") for (int n = 0; n < 2; ++n) _Pragma("unroll") for (int k = 0; k < 2; ++k) \
;     dst[n][k] = *reinterpret_cast<const bf16x8*>((const char*)SB8(b, h) + lb + n * 2048 + k * 1024)
; #define MMA8(ai, bj, At_, Bx_) do { __builtin_amdgcn_s_setprio(1); \
;     _Pragma("unroll") for (int m = 0; m < 4; ++m) _Pragma("unroll") for (int n = 0; n < 2; ++n) _Pragma("unroll") for (int k = 0; k < 2; ++k) \
;       acc[ai][bj][m][n] = __builtin_amdgcn_mfma_f32_16x16x32_bf16(Bx_[n][k], At_[m][k], acc[ai][bj][m][n], 0, 0, 0); \
;     __builtin_amdgcn_s_setprio(0); } while (0)
; #define WAITV8(n) asm volatile("s_waitcnt vmcnt(" #n ")" ::: "memory")
; #define WAITL8(n) asm volatile("s_waitcnt lgkmcnt(" #n ")" ::: "memory")
; #define BAR8 __builtin_amdgcn_s_barrier()
; template <class Epi>
; DEV void gemm8_phase(const u16* __restrict__ A, int lda, const u16* __restrict__ Bt, int K, int nM, int nN, char* shmc, const Epi& epi) {
;     ...
;       LDA8(At, 0, 1); WAITV8(4); BAR8; WAITL8(0); MMA8(1, 0, At, B0); MMA8(1, 1, At, B1); BAR8; }
;     { LDB8(B0, 1, 0); LDA8(At, 1, 0); WAITV8(2); BAR8; WAITL8(0); MMA8(0, 0, At, B0); BAR8;
	ds_read_b128 v[182:185], v150 offset:16384
	ds_read_b128 v[186:189], v150 offset:17408
	ds_read_b128 v[190:193], v150 offset:18432
	ds_read_b128 v[194:197], v150 offset:19456
	ds_read_b128 v[198:201], v150 offset:20480
	ds_read_b128 v[202:205], v150 offset:21504
	ds_read_b128 v[206:209], v150 offset:22528
	ds_read_b128 v[210:213], v150 offset:23552
	s_waitcnt vmcnt(4)
	s_barrier
	s_waitcnt lgkmcnt(0)
	s_setprio 1
	s_waitcnt lgkmcnt(0)
	v_mfma_f32_16x16x32_bf16 v[60:63], v[142:145], v[182:185], v[60:63]
	v_mfma_f32_16x16x32_bf16 v[56:59], v[174:177], v[182:185], v[56:59]
	v_mfma_f32_16x16x32_bf16 v[52:55], v[142:145], v[190:193], v[52:55]
	v_mfma_f32_16x16x32_bf16 v[48:51], v[174:177], v[190:193], v[48:51]
	v_mfma_f32_16x16x32_bf16 v[44:47], v[142:145], v[198:201], v[44:47]
	v_mfma_f32_16x16x32_bf16 v[40:43], v[174:177], v[198:201], v[40:43]
	v_mfma_f32_16x16x32_bf16 v[36:39], v[142:145], v[206:209], v[36:39]
	v_mfma_f32_16x16x32_bf16 v[32:35], v[174:177], v[206:209], v[32:35]
	v_mfma_f32_16x16x32_bf16 v[60:63], v[146:149], v[186:189], v[60:63]
	v_mfma_f32_16x16x32_bf16 v[56:59], v[178:181], v[186:189], v[56:59]
	v_mfma_f32_16x16x32_bf16 v[52:55], v[146:149], v[194:197], v[52:55]
	v_mfma_f32_16x16x32_bf16 v[48:51], v[178:181], v[194:197], v[48:51]
	v_mfma_f32_16x16x32_bf16 v[44:47], v[146:149], v[202:205], v[44:47]
	v_mfma_f32_16x16x32_bf16 v[40:43], v[178:181], v[202:205], v[40:43]
	v_mfma_f32_16x16x32_bf16 v[36:39], v[146:149], v[210:213], v[36:39]
	v_mfma_f32_16x16x32_bf16 v[32:35], v[178:181], v[210:213], v[32:35]
	s_setprio 0
	s_setprio 1
	v_mfma_f32_16x16x32_bf16 v[28:31], v[214:217], v[182:185], v[28:31]
	v_mfma_f32_16x16x32_bf16 v[24:27], v[222:225], v[182:185], v[24:27]
	v_mfma_f32_16x16x32_bf16 v[20:23], v[214:217], v[190:193], v[20:23]
	v_mfma_f32_16x16x32_bf16 v[16:19], v[222:225], v[190:193], v[16:19]
	v_mfma_f32_16x16x32_bf16 v[12:15], v[214:217], v[198:201], v[12:15]
	v_mfma_f32_16x16x32_bf16 v[8:11], v[222:225], v[198:201], v[8:11]
	v_mfma_f32_16x16x32_bf16 v[4:7], v[214:217], v[206:209], v[4:7]
	v_mfma_f32_16x16x32_bf16 v[0:3], v[222:225], v[206:209], v[0:3]
	v_mfma_f32_16x16x32_bf16 v[28:31], v[218:221], v[186:189], v[28:31]
	v_mfma_f32_16x16x32_bf16 v[24:27], v[226:229], v[186:189], v[24:27]
	v_mfma_f32_16x16x32_bf16 v[20:23], v[218:221], v[194:197], v[20:23]
	v_mfma_f32_16x16x32_bf16 v[16:19], v[226:229], v[194:197], v[16:19]
	v_mfma_f32_16x16x32_bf16 v[12:15], v[218:221], v[202:205], v[12:15]
	v_mfma_f32_16x16x32_bf16 v[8:11], v[226:229], v[202:205], v[8:11]
	v_mfma_f32_16x16x32_bf16 v[4:7], v[218:221], v[210:213], v[4:7]
	v_mfma_f32_16x16x32_bf16 v[0:3], v[226:229], v[210:213], v[0:3]
	s_setprio 0
	s_barrier
	ds_read_b128 v[142:145], v162
	ds_read_b128 v[146:149], v163
	ds_read_b128 v[174:177], v166
	ds_read_b128 v[178:181], v167
	ds_read_b128 v[182:185], v150 offset:32768
	ds_read_b128 v[186:189], v150 offset:33792
	ds_read_b128 v[190:193], v150 offset:34816
	ds_read_b128 v[194:197], v150 offset:35840
	ds_read_b128 v[198:201], v150 offset:36864
	ds_read_b128 v[202:205], v150 offset:37888
	ds_read_b128 v[206:209], v150 offset:38912
	ds_read_b128 v[210:213], v150 offset:39936
	s_waitcnt vmcnt(2)
	s_barrier
	s_waitcnt lgkmcnt(0)
	s_setprio 1
	s_waitcnt lgkmcnt(0)
	v_mfma_f32_16x16x32_bf16 v[124:127], v[142:145], v[182:185], v[124:127]
	v_mfma_f32_16x16x32_bf16 v[120:123], v[174:177], v[182:185], v[120:123]
	v_mfma_f32_16x16x32_bf16 v[116:119], v[142:145], v[190:193], v[116:119]
	v_mfma_f32_16x16x32_bf16 v[112:115], v[174:177], v[190:193], v[112:115]
	v_mfma_f32_16x16x32_bf16 v[108:111], v[142:145], v[198:201], v[108:111]
	v_mfma_f32_16x16x32_bf16 v[104:107], v[174:177], v[198:201], v[104:107]
	v_mfma_f32_16x16x32_bf16 v[100:103], v[142:145], v[206:209], v[100:103]
	v_mfma_f32_16x16x32_bf16 v[96:99], v[174:177], v[206:209], v[96:99]
	v_mfma_f32_16x16x32_bf16 v[124:127], v[146:149], v[186:189], v[124:127]
	v_mfma_f32_16x16x32_bf16 v[120:123], v[178:181], v[186:189], v[120:123]
	v_mfma_f32_16x16x32_bf16 v[116:119], v[146:149], v[194:197], v[116:119]
	v_mfma_f32_16x16x32_bf16 v[112:115], v[178:181], v[194:197], v[112:115]
	v_mfma_f32_16x16x32_bf16 v[108:111], v[146:149], v[202:205], v[108:111]
	v_mfma_f32_16x16x32_bf16 v[104:107], v[178:181], v[202:205], v[104:107]
	v_mfma_f32_16x16x32_bf16 v[100:103], v[146:149], v[210:213], v[100:103]
	v_mfma_f32_16x16x32_bf16 v[96:99], v[178:181], v[210:213], v[96:99]
	s_setprio 0
	s_barrier
; #define LDA8(dst, b, h) _Pragma("unroll") for (int m = 0; m < 4; ++m) _Pragma("unroll") for (int k = 0; k < 2; ++k) \
;     dst[m][k] = *reinterpret_cast<const bf16x8*>((const char*)SA8(b, h) + la + m * 2048 + k * 1024)
; #define LDB8(dst, b, h) _Pragma("unroll") for (int n = 0; n < 2; ++n) _Pragma("unroll") for (int k = 0; k < 2; ++k) \
;     dst[n][k] = *reinterpret_cast<const bf16x8*>((const char*)SB8(b, h) + lb + n * 2048 + k * 1024)
; #define MMA8(ai, bj, At_, Bx_) do { __builtin_amdgcn_s_setprio(1); \
;     _Pragma("unroll") for (int m = 0; m < 4; ++m) _Pragma("unroll") for (int n = 0; n < 2; ++n) _Pragma("unroll") for (int k = 0; k < 2; ++k) \
;       acc[ai][bj][m][n] = __builtin_amdgcn_mfma_f32_16x16x32_bf16(Bx_[n][k], At_[m][k], acc[ai][bj][m][n], 0, 0, 0); \
;     __builtin_amdgcn_s_setprio(0); } while (0)
; #define WAITV8(n) asm volatile("s_waitcnt vmcnt(" #n ")" ::: "memory")
; #define WAITL8(n) asm volatile("s_waitcnt lgkmcnt(" #n ")" ::: "memory")
; #define BAR8 __builtin_amdgcn_s_barrier()
; template <class Epi>
; DEV void gemm8_phase(const u16* __restrict__ A, int lda, const u16* __restrict__ Bt, int K, int nM, int nN, char* shmc, const Epi& epi) {
;     ...
;       LDB8(B1, 1, 1); WAITV8(0); BAR8; WAITL8(0); MMA8(0, 1, At, B1); BAR8;
;       LDA8(At, 1, 1); BAR8; WAITL8(0); MMA8(1, 0, At, B0); MMA8(1, 1, At, B1); BAR8; }
;     if (wr == 0) BAR8;
	ds_read_b128 v[214:217], v168
	ds_read_b128 v[218:221], v169
	ds_read_b128 v[222:225], v170
	ds_read_b128 v[226:229], v171
	s_waitcnt vmcnt(0)
	s_barrier
	s_waitcnt lgkmcnt(0)
	s_setprio 1
	s_waitcnt lgkmcnt(0)
	v_mfma_f32_16x16x32_bf16 v[92:95], v[214:217], v[182:185], v[92:95]
	v_mfma_f32_16x16x32_bf16 v[88:91], v[222:225], v[182:185], v[88:91]
	v_mfma_f32_16x16x32_bf16 v[84:87], v[214:217], v[190:193], v[84:87]
	v_mfma_f32_16x16x32_bf16 v[80:83], v[222:225], v[190:193], v[80:83]
	v_mfma_f32_16x16x32_bf16 v[76:79], v[214:217], v[198:201], v[76:79]
	v_mfma_f32_16x16x32_bf16 v[72:75], v[222:225], v[198:201], v[72:75]
	v_mfma_f32_16x16x32_bf16 v[68:71], v[214:217], v[206:209], v[68:71]
	v_mfma_f32_16x16x32_bf16 v[64:67], v[222:225], v[206:209], v[64:67]
	v_mfma_f32_16x16x32_bf16 v[92:95], v[218:221], v[186:189], v[92:95]
	v_mfma_f32_16x16x32_bf16 v[88:91], v[226:229], v[186:189], v[88:91]
	v_mfma_f32_16x16x32_bf16 v[84:87], v[218:221], v[194:197], v[84:87]
	v_mfma_f32_16x16x32_bf16 v[80:83], v[226:229], v[194:197], v[80:83]
	v_mfma_f32_16x16x32_bf16 v[76:79], v[218:221], v[202:205], v[76:79]
	v_mfma_f32_16x16x32_bf16 v[72:75], v[226:229], v[202:205], v[72:75]
	v_mfma_f32_16x16x32_bf16 v[68:71], v[218:221], v[210:213], v[68:71]
	v_mfma_f32_16x16x32_bf16 v[64:67], v[226:229], v[210:213], v[64:67]
	s_setprio 0
	s_barrier
	ds_read_b128 v[182:185], v150 offset:49152
	ds_read_b128 v[186:189], v150 offset:50176
	ds_read_b128 v[190:193], v150 offset:51200
	ds_read_b128 v[194:197], v150 offset:52224
	ds_read_b128 v[198:201], v150 offset:53248
	ds_read_b128 v[202:205], v150 offset:54272
	ds_read_b128 v[206:209], v150 offset:55296
	ds_read_b128 v[210:213], v150 offset:56320
	s_barrier
	s_waitcnt lgkmcnt(0)
	s_setprio 1
	s_waitcnt lgkmcnt(0)
	v_mfma_f32_16x16x32_bf16 v[60:63], v[142:145], v[182:185], v[60:63]
	v_mfma_f32_16x16x32_bf16 v[56:59], v[174:177], v[182:185], v[56:59]
	v_mfma_f32_16x16x32_bf16 v[52:55], v[142:145], v[190:193], v[52:55]
	v_mfma_f32_16x16x32_bf16 v[48:51], v[174:177], v[190:193], v[48:51]
	v_mfma_f32_16x16x32_bf16 v[44:47], v[142:145], v[198:201], v[44:47]
	v_mfma_f32_16x16x32_bf16 v[40:43], v[174:177], v[198:201], v[40:43]
	v_mfma_f32_16x16x32_bf16 v[36:39], v[142:145], v[206:209], v[36:39]
	v_mfma_f32_16x16x32_bf16 v[32:35], v[174:177], v[206:209], v[32:35]
	v_mfma_f32_16x16x32_bf16 v[60:63], v[146:149], v[186:189], v[60:63]
	v_mfma_f32_16x16x32_bf16 v[56:59], v[178:181], v[186:189], v[56:59]
	v_mfma_f32_16x16x32_bf16 v[52:55], v[146:149], v[194:197], v[52:55]
	v_mfma_f32_16x16x32_bf16 v[48:51], v[178:181], v[194:197], v[48:51]
	v_mfma_f32_16x16x32_bf16 v[44:47], v[146:149], v[202:205], v[44:47]
	v_mfma_f32_16x16x32_bf16 v[40:43], v[178:181], v[202:205], v[40:43]
	v_mfma_f32_16x16x32_bf16 v[36:39], v[146:149], v[210:213], v[36:39]
	v_mfma_f32_16x16x32_bf16 v[32:35], v[178:181], v[210:213], v[32:35]
	s_setprio 0
	s_setprio 1
	v_mfma_f32_16x16x32_bf16 v[28:31], v[214:217], v[182:185], v[28:31]
	v_mfma_f32_16x16x32_bf16 v[24:27], v[222:225], v[182:185], v[24:27]
	v_mfma_f32_16x16x32_bf16 v[20:23], v[214:217], v[190:193], v[20:23]
	v_mfma_f32_16x16x32_bf16 v[16:19], v[222:225], v[190:193], v[16:19]
	v_mfma_f32_16x16x32_bf16 v[12:15], v[214:217], v[198:201], v[12:15]
	v_mfma_f32_16x16x32_bf16 v[8:11], v[222:225], v[198:201], v[8:11]
	v_mfma_f32_16x16x32_bf16 v[4:7], v[214:217], v[206:209], v[4:7]
	v_mfma_f32_16x16x32_bf16 v[0:3], v[222:225], v[206:209], v[0:3]
	v_mfma_f32_16x16x32_bf16 v[28:31], v[218:221], v[186:189], v[28:31]
	v_mfma_f32_16x16x32_bf16 v[24:27], v[226:229], v[186:189], v[24:27]
	v_mfma_f32_16x16x32_bf16 v[20:23], v[218:221], v[194:197], v[20:23]
	v_mfma_f32_16x16x32_bf16 v[16:19], v[226:229], v[194:197], v[16:19]
	v_mfma_f32_16x16x32_bf16 v[12:15], v[218:221], v[202:205], v[12:15]
	v_mfma_f32_16x16x32_bf16 v[8:11], v[226:229], v[202:205], v[8:11]
	v_mfma_f32_16x16x32_bf16 v[4:7], v[218:221], v[210:213], v[4:7]
	v_mfma_f32_16x16x32_bf16 v[0:3], v[226:229], v[210:213], v[0:3]
	s_setprio 0
	s_and_b64 vcc, exec, s[10:11]
	s_barrier
	s_cbranch_vccz .LBB0_1651
	s_barrier
